# priority windows: s_setprio 0/1 flip after every 4 MFMAs (3 per 16-MFMA block instead of 1) so the loading partner wave gets more issue windows
# speedup vs baseline: 1.0055x; 1.0055x over previous
.LBB0_197:
	s_ashr_i32 s47, s46, 31
	ds_read_b128 v[18:21], v190
	ds_read_b128 v[22:25], v190 offset:1024
	ds_read_b128 v[26:29], v190 offset:2048
	ds_read_b128 v[30:33], v190 offset:3072
	ds_read_b128 v[2:5], v190 offset:16384
	ds_read_b128 v[6:9], v190 offset:17408
	ds_read_b128 v[10:13], v190 offset:18432
	ds_read_b128 v[14:17], v190 offset:19456
	s_lshl_b64 s[8:9], s[46:47], 20
	s_add_u32 s48, s22, s8
	s_addc_u32 s49, s23, s9
	s_and_b64 s[8:9], s[2:3], exec
	s_cselect_b32 s47, s49, s73
	s_cselect_b32 s70, s48, s72
	s_ashr_i32 s45, s44, 31
	s_lshl_b64 s[8:9], s[44:45], 20
	s_add_u32 s50, s27, s8
	s_addc_u32 s51, s68, s9
	s_and_b64 s[8:9], s[2:3], exec
	s_cselect_b32 s45, s51, s55
	s_cselect_b32 s71, s50, s54
	s_add_u32 s8, s72, 0x80080
	s_addc_u32 s9, s73, 0
	s_mov_b32 m0, s92
	v_lshl_add_u64 v[216:217], s[8:9], 0, v[164:165]
	ds_read_b128 v[180:183], v191
	ds_read_b128 v[184:187], v191 offset:1024
	ds_read_b128 v[192:195], v191 offset:2048
	ds_read_b128 v[196:199], v191 offset:3072
	ds_read_b128 v[200:203], v191 offset:4096
	ds_read_b128 v[204:207], v191 offset:5120
	ds_read_b128 v[208:211], v191 offset:6144
	ds_read_b128 v[212:215], v191 offset:7168
	global_load_lds_dwordx4 v[216:217], off
	v_lshl_add_u64 v[216:217], s[8:9], 0, v[168:169]
	s_mov_b32 m0, s93
	s_nop 0
	global_load_lds_dwordx4 v[216:217], off
	s_waitcnt vmcnt(8)
	s_waitcnt lgkmcnt(0)
	s_setprio 1
	s_barrier
	v_mfma_f32_16x16x128_f8f6f4 v[158:161], v[18:25], v[180:187], 0
	v_mfma_f32_16x16x128_f8f6f4 v[154:157], v[26:33], v[180:187], 0
	v_mfma_f32_16x16x128_f8f6f4 v[122:125], v[10:17], v[180:187], 0
	v_mfma_f32_16x16x128_f8f6f4 v[126:129], v[2:9], v[180:187], 0
	s_setprio 0
	s_setprio 1
	v_mfma_f32_16x16x128_f8f6f4 v[118:121], v[2:9], v[192:199], 0
	v_mfma_f32_16x16x128_f8f6f4 v[114:117], v[10:17], v[192:199], 0
	v_mfma_f32_16x16x128_f8f6f4 v[146:149], v[26:33], v[192:199], 0
	v_mfma_f32_16x16x128_f8f6f4 v[150:153], v[18:25], v[192:199], 0
	s_setprio 0
	s_setprio 1
	v_mfma_f32_16x16x128_f8f6f4 v[142:145], v[18:25], v[200:207], 0
	v_mfma_f32_16x16x128_f8f6f4 v[138:141], v[26:33], v[200:207], 0
	v_mfma_f32_16x16x128_f8f6f4 v[106:109], v[10:17], v[200:207], 0
	v_mfma_f32_16x16x128_f8f6f4 v[110:113], v[2:9], v[200:207], 0
	s_setprio 0
	s_setprio 1
	v_mfma_f32_16x16x128_f8f6f4 v[102:105], v[2:9], v[208:215], 0
	v_mfma_f32_16x16x128_f8f6f4 v[98:101], v[10:17], v[208:215], 0
	v_mfma_f32_16x16x128_f8f6f4 v[130:133], v[26:33], v[208:215], 0
	v_mfma_f32_16x16x128_f8f6f4 v[134:137], v[18:25], v[208:215], 0
	s_barrier
	s_setprio 0
	v_lshl_add_u64 v[180:181], s[54:55], 0, v[166:167]
	s_mov_b32 m0, s77
	v_lshl_add_u64 v[182:183], v[180:181], 0, s[16:17]
	ds_read_b128 v[192:195], v191 offset:16384
	ds_read_b128 v[196:199], v191 offset:17408
	ds_read_b128 v[200:203], v191 offset:18432
	ds_read_b128 v[204:207], v191 offset:19456
	ds_read_b128 v[208:211], v191 offset:20480
	ds_read_b128 v[212:215], v191 offset:21504
	ds_read_b128 v[216:219], v191 offset:22528
	ds_read_b128 v[220:223], v191 offset:23552
	global_load_lds_dwordx4 v[182:183], off
	v_lshl_add_u64 v[182:183], s[54:55], 0, v[170:171]
	s_add_u32 s8, s54, 0x80100
	v_lshl_add_u64 v[184:185], v[182:183], 0, s[16:17]
	s_mov_b32 m0, s78
	s_addc_u32 s9, s55, 0
	global_load_lds_dwordx4 v[184:185], off
	v_lshl_add_u64 v[184:185], s[8:9], 0, v[166:167]
	s_mov_b32 m0, s79
	s_nop 0
	global_load_lds_dwordx4 v[184:185], off
	v_lshl_add_u64 v[184:185], s[8:9], 0, v[170:171]
	s_mov_b32 m0, s80
	s_nop 0
	global_load_lds_dwordx4 v[184:185], off
	v_lshl_add_u64 v[184:185], s[72:73], 0, v[164:165]
	v_lshl_add_u64 v[186:187], v[184:185], 0, s[16:17]
	s_mov_b32 m0, s53
	s_nop 0
	global_load_lds_dwordx4 v[186:187], off
	v_lshl_add_u64 v[186:187], s[72:73], 0, v[168:169]
	v_lshl_add_u64 v[224:225], v[186:187], 0, s[16:17]
	s_mov_b32 m0, s81
	s_nop 0
	global_load_lds_dwordx4 v[224:225], off
	s_waitcnt vmcnt(8)
	s_waitcnt lgkmcnt(0)
	s_setprio 1
	s_barrier
	v_mfma_f32_16x16x128_f8f6f4 v[94:97], v[18:25], v[192:199], 0
	v_mfma_f32_16x16x128_f8f6f4 v[90:93], v[26:33], v[192:199], 0
	v_mfma_f32_16x16x128_f8f6f4 v[58:61], v[10:17], v[192:199], 0
	v_mfma_f32_16x16x128_f8f6f4 v[62:65], v[2:9], v[192:199], 0
	s_setprio 0
	s_setprio 1
	v_mfma_f32_16x16x128_f8f6f4 v[54:57], v[2:9], v[200:207], 0
	v_mfma_f32_16x16x128_f8f6f4 v[50:53], v[10:17], v[200:207], 0
	v_mfma_f32_16x16x128_f8f6f4 v[82:85], v[26:33], v[200:207], 0
	v_mfma_f32_16x16x128_f8f6f4 v[86:89], v[18:25], v[200:207], 0
	s_setprio 0
	s_setprio 1
	v_mfma_f32_16x16x128_f8f6f4 v[78:81], v[18:25], v[208:215], 0
	v_mfma_f32_16x16x128_f8f6f4 v[74:77], v[26:33], v[208:215], 0
	v_mfma_f32_16x16x128_f8f6f4 v[42:45], v[10:17], v[208:215], 0
	v_mfma_f32_16x16x128_f8f6f4 v[46:49], v[2:9], v[208:215], 0
	s_setprio 0
	s_setprio 1
	v_mfma_f32_16x16x128_f8f6f4 v[38:41], v[2:9], v[216:223], 0
	v_mfma_f32_16x16x128_f8f6f4 v[34:37], v[10:17], v[216:223], 0
	v_mfma_f32_16x16x128_f8f6f4 v[66:69], v[26:33], v[216:223], 0
	v_mfma_f32_16x16x128_f8f6f4 v[70:73], v[18:25], v[216:223], 0
	s_barrier
	s_setprio 0
	ds_read_b128 v[18:21], v190 offset:32768
	ds_read_b128 v[22:25], v190 offset:33792
	ds_read_b128 v[26:29], v190 offset:34816
	ds_read_b128 v[30:33], v190 offset:35840
	ds_read_b128 v[2:5], v190 offset:49152
	ds_read_b128 v[6:9], v190 offset:50176
	ds_read_b128 v[10:13], v190 offset:51200
	ds_read_b128 v[14:17], v190 offset:52224
	s_add_u32 s8, s72, 0x80100
	s_addc_u32 s9, s73, 0
	s_mov_b32 m0, s82
	v_lshl_add_u64 v[224:225], s[8:9], 0, v[164:165]
	ds_read_b128 v[192:195], v191 offset:32768
	ds_read_b128 v[196:199], v191 offset:33792
	ds_read_b128 v[200:203], v191 offset:34816
	ds_read_b128 v[204:207], v191 offset:35840
	ds_read_b128 v[208:211], v191 offset:36864
	ds_read_b128 v[212:215], v191 offset:37888
	ds_read_b128 v[216:219], v191 offset:38912
	ds_read_b128 v[220:223], v191 offset:39936
	global_load_lds_dwordx4 v[224:225], off
	v_lshl_add_u64 v[224:225], s[8:9], 0, v[168:169]
	s_mov_b32 m0, s83
	s_nop 0
	global_load_lds_dwordx4 v[224:225], off
	s_waitcnt vmcnt(8)
	s_waitcnt lgkmcnt(0)
	s_setprio 1
	s_barrier
	v_mfma_f32_16x16x128_f8f6f4 v[158:161], v[18:25], v[192:199], v[158:161]
	v_mfma_f32_16x16x128_f8f6f4 v[154:157], v[26:33], v[192:199], v[154:157]
	v_mfma_f32_16x16x128_f8f6f4 v[122:125], v[10:17], v[192:199], v[122:125]
	v_mfma_f32_16x16x128_f8f6f4 v[126:129], v[2:9], v[192:199], v[126:129]
	s_setprio 0
	s_setprio 1
	v_mfma_f32_16x16x128_f8f6f4 v[118:121], v[2:9], v[200:207], v[118:121]
	v_mfma_f32_16x16x128_f8f6f4 v[114:117], v[10:17], v[200:207], v[114:117]
	v_mfma_f32_16x16x128_f8f6f4 v[146:149], v[26:33], v[200:207], v[146:149]
	v_mfma_f32_16x16x128_f8f6f4 v[150:153], v[18:25], v[200:207], v[150:153]
	s_setprio 0
	s_setprio 1
	v_mfma_f32_16x16x128_f8f6f4 v[142:145], v[18:25], v[208:215], v[142:145]
	v_mfma_f32_16x16x128_f8f6f4 v[138:141], v[26:33], v[208:215], v[138:141]
	v_mfma_f32_16x16x128_f8f6f4 v[106:109], v[10:17], v[208:215], v[106:109]
	v_mfma_f32_16x16x128_f8f6f4 v[110:113], v[2:9], v[208:215], v[110:113]
	s_setprio 0
	s_setprio 1
	v_mfma_f32_16x16x128_f8f6f4 v[102:105], v[2:9], v[216:223], v[102:105]
	v_mfma_f32_16x16x128_f8f6f4 v[98:101], v[10:17], v[216:223], v[98:101]
	v_mfma_f32_16x16x128_f8f6f4 v[130:133], v[26:33], v[216:223], v[130:133]
	v_mfma_f32_16x16x128_f8f6f4 v[134:137], v[18:25], v[216:223], v[134:137]
	s_barrier
	s_setprio 0
	s_mov_b32 m0, s86
	v_lshl_add_u64 v[180:181], v[180:181], 0, s[20:21]
	s_add_u32 s8, s54, 0x80180
	ds_read_b128 v[192:195], v191 offset:49152
	ds_read_b128 v[196:199], v191 offset:50176
	ds_read_b128 v[200:203], v191 offset:51200
	ds_read_b128 v[204:207], v191 offset:52224
	ds_read_b128 v[208:211], v191 offset:53248
	ds_read_b128 v[212:215], v191 offset:54272
	ds_read_b128 v[216:219], v191 offset:55296
	ds_read_b128 v[220:223], v191 offset:56320
	global_load_lds_dwordx4 v[180:181], off
	v_lshl_add_u64 v[180:181], v[182:183], 0, s[20:21]
	s_mov_b32 m0, s87
	s_addc_u32 s9, s55, 0
	global_load_lds_dwordx4 v[180:181], off
	v_lshl_add_u64 v[180:181], s[8:9], 0, v[166:167]
	s_mov_b32 m0, s90
	s_nop 0
	global_load_lds_dwordx4 v[180:181], off
	v_lshl_add_u64 v[180:181], s[8:9], 0, v[170:171]
	s_mov_b32 m0, s91
	s_nop 0
	global_load_lds_dwordx4 v[180:181], off
	v_lshl_add_u64 v[180:181], v[184:185], 0, s[20:21]
	s_mov_b32 m0, s88
	s_nop 0
	global_load_lds_dwordx4 v[180:181], off
	v_lshl_add_u64 v[180:181], v[186:187], 0, s[20:21]
	s_mov_b32 m0, s89
	s_nop 0
	global_load_lds_dwordx4 v[180:181], off
	s_waitcnt vmcnt(8)
	s_waitcnt lgkmcnt(0)
	s_setprio 1
	s_barrier
	v_mfma_f32_16x16x128_f8f6f4 v[94:97], v[18:25], v[192:199], v[94:97]
	v_mfma_f32_16x16x128_f8f6f4 v[90:93], v[26:33], v[192:199], v[90:93]
	v_mfma_f32_16x16x128_f8f6f4 v[58:61], v[10:17], v[192:199], v[58:61]
	v_mfma_f32_16x16x128_f8f6f4 v[62:65], v[2:9], v[192:199], v[62:65]
	s_setprio 0
	s_setprio 1
	v_mfma_f32_16x16x128_f8f6f4 v[54:57], v[2:9], v[200:207], v[54:57]
	v_mfma_f32_16x16x128_f8f6f4 v[50:53], v[10:17], v[200:207], v[50:53]
	v_mfma_f32_16x16x128_f8f6f4 v[82:85], v[26:33], v[200:207], v[82:85]
	v_mfma_f32_16x16x128_f8f6f4 v[86:89], v[18:25], v[200:207], v[86:89]
	s_setprio 0
	s_setprio 1
	v_mfma_f32_16x16x128_f8f6f4 v[78:81], v[18:25], v[208:215], v[78:81]
	v_mfma_f32_16x16x128_f8f6f4 v[74:77], v[26:33], v[208:215], v[74:77]
	v_mfma_f32_16x16x128_f8f6f4 v[42:45], v[10:17], v[208:215], v[42:45]
	v_mfma_f32_16x16x128_f8f6f4 v[46:49], v[2:9], v[208:215], v[46:49]
	s_setprio 0
	s_setprio 1
	v_mfma_f32_16x16x128_f8f6f4 v[38:41], v[2:9], v[216:223], v[38:41]
	v_mfma_f32_16x16x128_f8f6f4 v[34:37], v[10:17], v[216:223], v[34:37]
	v_mfma_f32_16x16x128_f8f6f4 v[66:69], v[26:33], v[216:223], v[66:69]
	v_mfma_f32_16x16x128_f8f6f4 v[70:73], v[18:25], v[216:223], v[70:73]
	s_barrier
	s_setprio 0
	s_add_u32 s72, s72, 0x80180
	s_addc_u32 s73, s73, 0
	s_add_u32 s8, s54, 0x200
	s_addc_u32 s9, s55, 0
	s_mov_b32 s62, 0
.LBB0_198:
	ds_read_b128 v[2:5], v190
	ds_read_b128 v[6:9], v190 offset:1024
	ds_read_b128 v[18:21], v190 offset:2048
	ds_read_b128 v[22:25], v190 offset:3072
	ds_read_b128 v[26:29], v190 offset:16384
	ds_read_b128 v[30:33], v190 offset:17408
	ds_read_b128 v[180:183], v190 offset:18432
	ds_read_b128 v[184:187], v190 offset:19456
	s_add_u32 s54, s72, 0xfff80080
	s_addc_u32 s55, s73, -1
	s_cmp_eq_u32 s62, 28
	s_cselect_b32 s75, s47, s55
	s_cselect_b32 s74, s70, s54
	s_cselect_b32 s55, s45, s9
	s_cselect_b32 s54, s71, s8
	s_mov_b32 m0, s92
	v_lshl_add_u64 v[216:217], s[72:73], 0, v[172:173]
	ds_read_b128 v[10:13], v191
	ds_read_b128 v[14:17], v191 offset:1024
	ds_read_b128 v[192:195], v191 offset:2048
	ds_read_b128 v[196:199], v191 offset:3072
	ds_read_b128 v[200:203], v191 offset:4096
	ds_read_b128 v[204:207], v191 offset:5120
	ds_read_b128 v[208:211], v191 offset:6144
	ds_read_b128 v[212:215], v191 offset:7168
	global_load_lds_dwordx4 v[216:217], off
	v_lshl_add_u64 v[216:217], s[72:73], 0, v[174:175]
	s_mov_b32 m0, s93
	s_nop 0
	global_load_lds_dwordx4 v[216:217], off
	s_waitcnt vmcnt(8)
	s_waitcnt lgkmcnt(0)
	s_setprio 1
	s_barrier
	v_mfma_f32_16x16x128_f8f6f4 v[158:161], v[2:9], v[10:17], v[158:161]
	v_mfma_f32_16x16x128_f8f6f4 v[154:157], v[18:25], v[10:17], v[154:157]
	v_mfma_f32_16x16x128_f8f6f4 v[122:125], v[180:187], v[10:17], v[122:125]
	v_mfma_f32_16x16x128_f8f6f4 v[126:129], v[26:33], v[10:17], v[126:129]
	s_setprio 0
	s_setprio 1
	v_mfma_f32_16x16x128_f8f6f4 v[118:121], v[26:33], v[192:199], v[118:121]
	v_mfma_f32_16x16x128_f8f6f4 v[114:117], v[180:187], v[192:199], v[114:117]
	v_mfma_f32_16x16x128_f8f6f4 v[146:149], v[18:25], v[192:199], v[146:149]
	v_mfma_f32_16x16x128_f8f6f4 v[150:153], v[2:9], v[192:199], v[150:153]
	s_setprio 0
	s_setprio 1
	v_mfma_f32_16x16x128_f8f6f4 v[142:145], v[2:9], v[200:207], v[142:145]
	v_mfma_f32_16x16x128_f8f6f4 v[138:141], v[18:25], v[200:207], v[138:141]
	v_mfma_f32_16x16x128_f8f6f4 v[106:109], v[180:187], v[200:207], v[106:109]
	v_mfma_f32_16x16x128_f8f6f4 v[110:113], v[26:33], v[200:207], v[110:113]
	s_setprio 0
	s_setprio 1
	v_mfma_f32_16x16x128_f8f6f4 v[102:105], v[26:33], v[208:215], v[102:105]
	v_mfma_f32_16x16x128_f8f6f4 v[98:101], v[180:187], v[208:215], v[98:101]
	v_mfma_f32_16x16x128_f8f6f4 v[130:133], v[18:25], v[208:215], v[130:133]
	v_mfma_f32_16x16x128_f8f6f4 v[134:137], v[2:9], v[208:215], v[134:137]
	s_barrier
	s_setprio 0
	s_mov_b32 m0, s77
	v_lshl_add_u64 v[10:11], s[54:55], 0, v[166:167]
	s_add_u32 vcc_lo, s54, 0x80000
	ds_read_b128 v[192:195], v191 offset:16384
	ds_read_b128 v[196:199], v191 offset:17408
	ds_read_b128 v[200:203], v191 offset:18432
	ds_read_b128 v[204:207], v191 offset:19456
	ds_read_b128 v[208:211], v191 offset:20480
	ds_read_b128 v[212:215], v191 offset:21504
	ds_read_b128 v[216:219], v191 offset:22528
	ds_read_b128 v[220:223], v191 offset:23552
	global_load_lds_dwordx4 v[10:11], off
	v_lshl_add_u64 v[12:13], s[54:55], 0, v[170:171]
	s_mov_b32 m0, s78
	s_addc_u32 vcc_hi, s55, 0
	global_load_lds_dwordx4 v[12:13], off
	v_lshl_add_u64 v[14:15], vcc, 0, v[166:167]
	s_mov_b32 m0, s79
	v_lshl_add_u64 v[16:17], s[74:75], 0, v[168:169]
	global_load_lds_dwordx4 v[14:15], off
	v_lshl_add_u64 v[14:15], vcc, 0, v[170:171]
	s_mov_b32 m0, s80
	s_nop 0
	global_load_lds_dwordx4 v[14:15], off
	v_lshl_add_u64 v[14:15], s[74:75], 0, v[164:165]
	s_mov_b32 m0, s53
	s_nop 0
	global_load_lds_dwordx4 v[14:15], off
	s_mov_b32 m0, s81
	s_nop 0
	global_load_lds_dwordx4 v[16:17], off
	s_waitcnt vmcnt(8)
	s_waitcnt lgkmcnt(0)
	s_setprio 1
	s_barrier
	v_mfma_f32_16x16x128_f8f6f4 v[94:97], v[2:9], v[192:199], v[94:97]
	v_mfma_f32_16x16x128_f8f6f4 v[90:93], v[18:25], v[192:199], v[90:93]
	v_mfma_f32_16x16x128_f8f6f4 v[58:61], v[180:187], v[192:199], v[58:61]
	v_mfma_f32_16x16x128_f8f6f4 v[62:65], v[26:33], v[192:199], v[62:65]
	s_setprio 0
	s_setprio 1
	v_mfma_f32_16x16x128_f8f6f4 v[54:57], v[26:33], v[200:207], v[54:57]
	v_mfma_f32_16x16x128_f8f6f4 v[50:53], v[180:187], v[200:207], v[50:53]
	v_mfma_f32_16x16x128_f8f6f4 v[82:85], v[18:25], v[200:207], v[82:85]
	v_mfma_f32_16x16x128_f8f6f4 v[86:89], v[2:9], v[200:207], v[86:89]
	s_setprio 0
	s_setprio 1
	v_mfma_f32_16x16x128_f8f6f4 v[78:81], v[2:9], v[208:215], v[78:81]
	v_mfma_f32_16x16x128_f8f6f4 v[74:77], v[18:25], v[208:215], v[74:77]
	v_mfma_f32_16x16x128_f8f6f4 v[42:45], v[180:187], v[208:215], v[42:45]
	v_mfma_f32_16x16x128_f8f6f4 v[46:49], v[26:33], v[208:215], v[46:49]
	s_setprio 0
	s_setprio 1
	v_mfma_f32_16x16x128_f8f6f4 v[38:41], v[26:33], v[216:223], v[38:41]
	v_mfma_f32_16x16x128_f8f6f4 v[34:37], v[180:187], v[216:223], v[34:37]
	v_mfma_f32_16x16x128_f8f6f4 v[66:69], v[18:25], v[216:223], v[66:69]
	v_mfma_f32_16x16x128_f8f6f4 v[70:73], v[2:9], v[216:223], v[70:73]
	s_barrier
	s_setprio 0
	ds_read_b128 v[18:21], v190 offset:32768
	ds_read_b128 v[22:25], v190 offset:33792
	ds_read_b128 v[26:29], v190 offset:34816
	ds_read_b128 v[30:33], v190 offset:35840
	ds_read_b128 v[2:5], v190 offset:49152
	ds_read_b128 v[6:9], v190 offset:50176
	ds_read_b128 v[180:183], v190 offset:51200
	ds_read_b128 v[184:187], v190 offset:52224
	s_add_u32 s74, s74, 0x80000
	s_addc_u32 s75, s75, 0
	s_mov_b32 m0, s82
	v_lshl_add_u64 v[224:225], s[74:75], 0, v[164:165]
	ds_read_b128 v[192:195], v191 offset:32768
	ds_read_b128 v[196:199], v191 offset:33792
	ds_read_b128 v[200:203], v191 offset:34816
	ds_read_b128 v[204:207], v191 offset:35840
	ds_read_b128 v[208:211], v191 offset:36864
	ds_read_b128 v[212:215], v191 offset:37888
	ds_read_b128 v[216:219], v191 offset:38912
	ds_read_b128 v[220:223], v191 offset:39936
	global_load_lds_dwordx4 v[224:225], off
	v_lshl_add_u64 v[224:225], s[74:75], 0, v[168:169]
	s_mov_b32 m0, s83
	s_nop 0
	global_load_lds_dwordx4 v[224:225], off
	s_waitcnt vmcnt(8)
	s_waitcnt lgkmcnt(0)
	s_setprio 1
	s_barrier
	v_mfma_f32_16x16x128_f8f6f4 v[158:161], v[18:25], v[192:199], v[158:161]
	v_mfma_f32_16x16x128_f8f6f4 v[154:157], v[26:33], v[192:199], v[154:157]
	v_mfma_f32_16x16x128_f8f6f4 v[122:125], v[180:187], v[192:199], v[122:125]
	v_mfma_f32_16x16x128_f8f6f4 v[126:129], v[2:9], v[192:199], v[126:129]
	s_setprio 0
	s_setprio 1
	v_mfma_f32_16x16x128_f8f6f4 v[118:121], v[2:9], v[200:207], v[118:121]
	v_mfma_f32_16x16x128_f8f6f4 v[114:117], v[180:187], v[200:207], v[114:117]
	v_mfma_f32_16x16x128_f8f6f4 v[146:149], v[26:33], v[200:207], v[146:149]
	v_mfma_f32_16x16x128_f8f6f4 v[150:153], v[18:25], v[200:207], v[150:153]
	s_setprio 0
	s_setprio 1
	v_mfma_f32_16x16x128_f8f6f4 v[142:145], v[18:25], v[208:215], v[142:145]
	v_mfma_f32_16x16x128_f8f6f4 v[138:141], v[26:33], v[208:215], v[138:141]
	v_mfma_f32_16x16x128_f8f6f4 v[106:109], v[180:187], v[208:215], v[106:109]
	v_mfma_f32_16x16x128_f8f6f4 v[110:113], v[2:9], v[208:215], v[110:113]
	s_setprio 0
	s_setprio 1
	v_mfma_f32_16x16x128_f8f6f4 v[102:105], v[2:9], v[216:223], v[102:105]
	v_mfma_f32_16x16x128_f8f6f4 v[98:101], v[180:187], v[216:223], v[98:101]
	v_mfma_f32_16x16x128_f8f6f4 v[130:133], v[26:33], v[216:223], v[130:133]
	v_mfma_f32_16x16x128_f8f6f4 v[134:137], v[18:25], v[216:223], v[134:137]
	s_barrier
	s_setprio 0
	s_mov_b32 m0, s86
	v_lshl_add_u64 v[10:11], v[10:11], 0, s[4:5]
	s_add_u32 s54, s54, 0x80080
	ds_read_b128 v[192:195], v191 offset:49152
	ds_read_b128 v[196:199], v191 offset:50176
	ds_read_b128 v[200:203], v191 offset:51200
	ds_read_b128 v[204:207], v191 offset:52224
	ds_read_b128 v[208:211], v191 offset:53248
	ds_read_b128 v[212:215], v191 offset:54272
	ds_read_b128 v[216:219], v191 offset:55296
	ds_read_b128 v[220:223], v191 offset:56320
	global_load_lds_dwordx4 v[10:11], off
	v_lshl_add_u64 v[10:11], v[12:13], 0, s[4:5]
	s_mov_b32 m0, s87
	s_addc_u32 s55, s55, 0
	global_load_lds_dwordx4 v[10:11], off
	v_lshl_add_u64 v[10:11], s[54:55], 0, v[166:167]
	s_mov_b32 m0, s90
	s_nop 0
	global_load_lds_dwordx4 v[10:11], off
	v_lshl_add_u64 v[10:11], s[54:55], 0, v[170:171]
	s_mov_b32 m0, s91
	s_nop 0
	global_load_lds_dwordx4 v[10:11], off
	v_lshl_add_u64 v[10:11], v[14:15], 0, s[4:5]
	s_mov_b32 m0, s88
	s_nop 0
	global_load_lds_dwordx4 v[10:11], off
	v_lshl_add_u64 v[10:11], v[16:17], 0, s[4:5]
	s_mov_b32 m0, s89
	s_nop 0
	global_load_lds_dwordx4 v[10:11], off
	s_waitcnt vmcnt(8)
	s_waitcnt lgkmcnt(0)
	s_setprio 1
	s_barrier
	v_mfma_f32_16x16x128_f8f6f4 v[94:97], v[18:25], v[192:199], v[94:97]
	v_mfma_f32_16x16x128_f8f6f4 v[90:93], v[26:33], v[192:199], v[90:93]
	v_mfma_f32_16x16x128_f8f6f4 v[58:61], v[180:187], v[192:199], v[58:61]
	v_mfma_f32_16x16x128_f8f6f4 v[62:65], v[2:9], v[192:199], v[62:65]
	s_setprio 0
	s_setprio 1
	v_mfma_f32_16x16x128_f8f6f4 v[54:57], v[2:9], v[200:207], v[54:57]
	v_mfma_f32_16x16x128_f8f6f4 v[50:53], v[180:187], v[200:207], v[50:53]
	v_mfma_f32_16x16x128_f8f6f4 v[82:85], v[26:33], v[200:207], v[82:85]
	v_mfma_f32_16x16x128_f8f6f4 v[86:89], v[18:25], v[200:207], v[86:89]
	s_setprio 0
	s_setprio 1
	v_mfma_f32_16x16x128_f8f6f4 v[78:81], v[18:25], v[208:215], v[78:81]
	v_mfma_f32_16x16x128_f8f6f4 v[74:77], v[26:33], v[208:215], v[74:77]
	v_mfma_f32_16x16x128_f8f6f4 v[42:45], v[180:187], v[208:215], v[42:45]
	v_mfma_f32_16x16x128_f8f6f4 v[46:49], v[2:9], v[208:215], v[46:49]
	s_setprio 0
	s_setprio 1
	v_mfma_f32_16x16x128_f8f6f4 v[38:41], v[2:9], v[216:223], v[38:41]
	v_mfma_f32_16x16x128_f8f6f4 v[34:37], v[180:187], v[216:223], v[34:37]
	v_mfma_f32_16x16x128_f8f6f4 v[66:69], v[26:33], v[216:223], v[66:69]
	v_mfma_f32_16x16x128_f8f6f4 v[70:73], v[18:25], v[216:223], v[70:73]
	s_barrier
	s_setprio 0
	s_add_i32 s62, s62, 2
	s_add_u32 s72, s72, 0x100
	s_addc_u32 s73, s73, 0
	s_add_u32 s8, s8, 0x100
	s_addc_u32 s9, s9, 0
	s_cmp_gt_u32 s62, 29
	s_cbranch_scc0 .LBB0_198
	s_and_b64 vcc, exec, s[6:7]
	s_cbranch_vccz .LBB0_201
	s_barrier

.LBB0_282:
	ds_read_b128 v[2:5], v187
	ds_read_b128 v[6:9], v187 offset:1024
	ds_read_b128 v[174:177], v187 offset:2048
	ds_read_b128 v[178:181], v187 offset:3072
	ds_read_b128 v[190:193], v187 offset:16384
	ds_read_b128 v[194:197], v187 offset:17408
	ds_read_b128 v[198:201], v187 offset:18432
	ds_read_b128 v[202:205], v187 offset:19456
	s_add_u32 s49, s52, 0x100
	s_addc_u32 s71, s53, 0
	s_and_b64 s[62:63], s[54:55], exec
	s_cselect_b32 s73, s1, s71
	s_cselect_b32 s72, s0, s49
	s_add_u32 s49, s50, 0x100
	s_addc_u32 s62, s51, 0
	s_and_b64 s[54:55], s[54:55], exec
	s_cselect_b32 s55, s5, s62
	s_cselect_b32 s54, s4, s49
	s_add_u32 s62, s52, 0x158080
	s_addc_u32 s63, s53, 0
	s_add_i32 s49, s33, 0xc000
	v_lshl_add_u64 v[182:183], s[62:63], 0, v[154:155]
	s_mov_b32 m0, s49
	s_add_i32 s71, s33, 0xe000
	ds_read_b128 v[206:209], v188
	ds_read_b128 v[210:213], v188 offset:1024
	ds_read_b128 v[214:217], v188 offset:2048
	ds_read_b128 v[218:221], v188 offset:3072
	ds_read_b128 v[222:225], v188 offset:4096
	ds_read_b128 v[226:229], v188 offset:5120
	ds_read_b128 v[230:233], v188 offset:6144
	ds_read_b128 v[234:237], v188 offset:7168
	global_load_lds_dwordx4 v[182:183], off
	v_lshl_add_u64 v[182:183], s[62:63], 0, v[158:159]
	s_mov_b32 m0, s71
	s_nop 0
	global_load_lds_dwordx4 v[182:183], off
	s_waitcnt vmcnt(8)
	s_waitcnt lgkmcnt(0)
	s_setprio 1
	s_barrier
	v_mfma_f32_16x16x128_f8f6f4 v[134:137], v[2:9], v[206:213], 0
	v_mfma_f32_16x16x128_f8f6f4 v[130:133], v[174:181], v[206:213], 0
	v_mfma_f32_16x16x128_f8f6f4 v[98:101], v[198:205], v[206:213], 0
	v_mfma_f32_16x16x128_f8f6f4 v[102:105], v[190:197], v[206:213], 0
	s_setprio 0
	s_setprio 1
	v_mfma_f32_16x16x128_f8f6f4 v[94:97], v[190:197], v[214:221], 0
	v_mfma_f32_16x16x128_f8f6f4 v[90:93], v[198:205], v[214:221], 0
	v_mfma_f32_16x16x128_f8f6f4 v[122:125], v[174:181], v[214:221], 0
	v_mfma_f32_16x16x128_f8f6f4 v[126:129], v[2:9], v[214:221], 0
	s_setprio 0
	s_setprio 1
	v_mfma_f32_16x16x128_f8f6f4 v[118:121], v[2:9], v[222:229], 0
	v_mfma_f32_16x16x128_f8f6f4 v[114:117], v[174:181], v[222:229], 0
	v_mfma_f32_16x16x128_f8f6f4 v[82:85], v[198:205], v[222:229], 0
	v_mfma_f32_16x16x128_f8f6f4 v[86:89], v[190:197], v[222:229], 0
	s_setprio 0
	s_setprio 1
	v_mfma_f32_16x16x128_f8f6f4 v[78:81], v[190:197], v[230:237], 0
	v_mfma_f32_16x16x128_f8f6f4 v[74:77], v[198:205], v[230:237], 0
	v_mfma_f32_16x16x128_f8f6f4 v[106:109], v[174:181], v[230:237], 0
	v_mfma_f32_16x16x128_f8f6f4 v[110:113], v[2:9], v[230:237], 0
	s_barrier
	s_setprio 0
	s_mov_b32 m0, s47
	v_lshl_add_u64 v[182:183], s[54:55], 0, v[156:157]
	s_add_u32 s62, s54, 0x158000
	ds_read_b128 v[206:209], v188 offset:16384
	ds_read_b128 v[210:213], v188 offset:17408
	ds_read_b128 v[214:217], v188 offset:18432
	ds_read_b128 v[218:221], v188 offset:19456
	ds_read_b128 v[222:225], v188 offset:20480
	ds_read_b128 v[226:229], v188 offset:21504
	ds_read_b128 v[230:233], v188 offset:22528
	ds_read_b128 v[234:237], v188 offset:23552
	global_load_lds_dwordx4 v[182:183], off
	v_lshl_add_u64 v[238:239], s[54:55], 0, v[160:161]
	s_mov_b32 m0, s68
	s_addc_u32 s63, s55, 0
	global_load_lds_dwordx4 v[238:239], off
	v_lshl_add_u64 v[242:243], s[62:63], 0, v[156:157]
	s_mov_b32 m0, s69
	v_lshl_add_u64 v[244:245], s[72:73], 0, v[158:159]
	global_load_lds_dwordx4 v[242:243], off
	v_lshl_add_u64 v[242:243], s[62:63], 0, v[160:161]
	s_mov_b32 m0, s74
	s_nop 0
	global_load_lds_dwordx4 v[242:243], off
	v_lshl_add_u64 v[242:243], s[72:73], 0, v[154:155]
	s_mov_b32 m0, s33
	s_nop 0
	global_load_lds_dwordx4 v[242:243], off
	s_mov_b32 m0, s75
	s_nop 0
	global_load_lds_dwordx4 v[244:245], off
	s_waitcnt vmcnt(8)
	s_waitcnt lgkmcnt(0)
	s_setprio 1
	s_barrier
	v_mfma_f32_16x16x128_f8f6f4 v[70:73], v[2:9], v[206:213], 0
	v_mfma_f32_16x16x128_f8f6f4 v[66:69], v[174:181], v[206:213], 0
	v_mfma_f32_16x16x128_f8f6f4 v[34:37], v[198:205], v[206:213], 0
	v_mfma_f32_16x16x128_f8f6f4 v[38:41], v[190:197], v[206:213], 0
	s_setprio 0
	s_setprio 1
	v_mfma_f32_16x16x128_f8f6f4 v[30:33], v[190:197], v[214:221], 0
	v_mfma_f32_16x16x128_f8f6f4 v[26:29], v[198:205], v[214:221], 0
	v_mfma_f32_16x16x128_f8f6f4 v[58:61], v[174:181], v[214:221], 0
	v_mfma_f32_16x16x128_f8f6f4 v[62:65], v[2:9], v[214:221], 0
	s_setprio 0
	s_setprio 1
	v_mfma_f32_16x16x128_f8f6f4 v[54:57], v[2:9], v[222:229], 0
	v_mfma_f32_16x16x128_f8f6f4 v[50:53], v[174:181], v[222:229], 0
	v_mfma_f32_16x16x128_f8f6f4 v[18:21], v[198:205], v[222:229], 0
	v_mfma_f32_16x16x128_f8f6f4 v[22:25], v[190:197], v[222:229], 0
	s_setprio 0
	s_setprio 1
	v_mfma_f32_16x16x128_f8f6f4 v[14:17], v[190:197], v[230:237], 0
	v_mfma_f32_16x16x128_f8f6f4 v[10:13], v[198:205], v[230:237], 0
	v_mfma_f32_16x16x128_f8f6f4 v[42:45], v[174:181], v[230:237], 0
	v_mfma_f32_16x16x128_f8f6f4 v[46:49], v[2:9], v[230:237], 0
	s_barrier
	s_setprio 0
	ds_read_b128 v[2:5], v187 offset:32768
	ds_read_b128 v[6:9], v187 offset:33792
	ds_read_b128 v[174:177], v187 offset:34816
	ds_read_b128 v[178:181], v187 offset:35840
	ds_read_b128 v[190:193], v187 offset:49152
	ds_read_b128 v[194:197], v187 offset:50176
	ds_read_b128 v[198:201], v187 offset:51200
	ds_read_b128 v[202:205], v187 offset:52224
	s_add_u32 s62, s72, 0x158000
	s_addc_u32 s63, s73, 0
	s_mov_b32 m0, s76
	v_lshl_add_u64 v[246:247], s[62:63], 0, v[154:155]
	ds_read_b128 v[206:209], v188 offset:32768
	ds_read_b128 v[210:213], v188 offset:33792
	ds_read_b128 v[214:217], v188 offset:34816
	ds_read_b128 v[218:221], v188 offset:35840
	ds_read_b128 v[222:225], v188 offset:36864
	ds_read_b128 v[226:229], v188 offset:37888
	ds_read_b128 v[230:233], v188 offset:38912
	ds_read_b128 v[234:237], v188 offset:39936
	global_load_lds_dwordx4 v[246:247], off
	v_lshl_add_u64 v[246:247], s[62:63], 0, v[158:159]
	s_mov_b32 m0, s77
	s_nop 0
	global_load_lds_dwordx4 v[246:247], off
	s_waitcnt vmcnt(8)
	s_waitcnt lgkmcnt(0)
	s_setprio 1
	s_barrier
	v_mfma_f32_16x16x128_f8f6f4 v[134:137], v[2:9], v[206:213], v[134:137]
	v_mfma_f32_16x16x128_f8f6f4 v[130:133], v[174:181], v[206:213], v[130:133]
	v_mfma_f32_16x16x128_f8f6f4 v[98:101], v[198:205], v[206:213], v[98:101]
	v_mfma_f32_16x16x128_f8f6f4 v[102:105], v[190:197], v[206:213], v[102:105]
	s_setprio 0
	s_setprio 1
	v_mfma_f32_16x16x128_f8f6f4 v[94:97], v[190:197], v[214:221], v[94:97]
	v_mfma_f32_16x16x128_f8f6f4 v[90:93], v[198:205], v[214:221], v[90:93]
	v_mfma_f32_16x16x128_f8f6f4 v[122:125], v[174:181], v[214:221], v[122:125]
	v_mfma_f32_16x16x128_f8f6f4 v[126:129], v[2:9], v[214:221], v[126:129]
	s_setprio 0
	s_setprio 1
	v_mfma_f32_16x16x128_f8f6f4 v[118:121], v[2:9], v[222:229], v[118:121]
	v_mfma_f32_16x16x128_f8f6f4 v[114:117], v[174:181], v[222:229], v[114:117]
	v_mfma_f32_16x16x128_f8f6f4 v[82:85], v[198:205], v[222:229], v[82:85]
	v_mfma_f32_16x16x128_f8f6f4 v[86:89], v[190:197], v[222:229], v[86:89]
	s_setprio 0
	s_setprio 1
	v_mfma_f32_16x16x128_f8f6f4 v[78:81], v[190:197], v[230:237], v[78:81]
	v_mfma_f32_16x16x128_f8f6f4 v[74:77], v[198:205], v[230:237], v[74:77]
	v_mfma_f32_16x16x128_f8f6f4 v[106:109], v[174:181], v[230:237], v[106:109]
	v_mfma_f32_16x16x128_f8f6f4 v[110:113], v[2:9], v[230:237], v[110:113]
	s_barrier
	s_setprio 0
	s_mov_b32 m0, s83
	v_lshl_add_u64 v[182:183], v[182:183], 0, s[26:27]
	s_add_u32 s54, s54, 0x158080
	ds_read_b128 v[206:209], v188 offset:49152
	ds_read_b128 v[210:213], v188 offset:50176
	ds_read_b128 v[214:217], v188 offset:51200
	ds_read_b128 v[218:221], v188 offset:52224
	ds_read_b128 v[222:225], v188 offset:53248
	ds_read_b128 v[226:229], v188 offset:54272
	ds_read_b128 v[230:233], v188 offset:55296
	ds_read_b128 v[234:237], v188 offset:56320
	global_load_lds_dwordx4 v[182:183], off
	v_lshl_add_u64 v[182:183], v[238:239], 0, s[26:27]
	s_mov_b32 m0, s84
	s_addc_u32 s55, s55, 0
	global_load_lds_dwordx4 v[182:183], off
	v_lshl_add_u64 v[182:183], s[54:55], 0, v[156:157]
	s_mov_b32 m0, s87
	s_nop 0
	global_load_lds_dwordx4 v[182:183], off
	v_lshl_add_u64 v[182:183], s[54:55], 0, v[160:161]
	s_mov_b32 m0, s88
	s_nop 0
	global_load_lds_dwordx4 v[182:183], off
	v_lshl_add_u64 v[182:183], v[242:243], 0, s[26:27]
	s_mov_b32 m0, s85
	s_nop 0
	global_load_lds_dwordx4 v[182:183], off
	v_lshl_add_u64 v[182:183], v[244:245], 0, s[26:27]
	s_mov_b32 m0, s86
	s_nop 0
	global_load_lds_dwordx4 v[182:183], off
	s_waitcnt vmcnt(8)
	s_waitcnt lgkmcnt(0)
	s_setprio 1
	s_barrier
	v_mfma_f32_16x16x128_f8f6f4 v[70:73], v[2:9], v[206:213], v[70:73]
	v_mfma_f32_16x16x128_f8f6f4 v[66:69], v[174:181], v[206:213], v[66:69]
	v_mfma_f32_16x16x128_f8f6f4 v[34:37], v[198:205], v[206:213], v[34:37]
	v_mfma_f32_16x16x128_f8f6f4 v[38:41], v[190:197], v[206:213], v[38:41]
	s_setprio 0
	s_setprio 1
	v_mfma_f32_16x16x128_f8f6f4 v[30:33], v[190:197], v[214:221], v[30:33]
	v_mfma_f32_16x16x128_f8f6f4 v[26:29], v[198:205], v[214:221], v[26:29]
	v_mfma_f32_16x16x128_f8f6f4 v[58:61], v[174:181], v[214:221], v[58:61]
	v_mfma_f32_16x16x128_f8f6f4 v[62:65], v[2:9], v[214:221], v[62:65]
	s_setprio 0
	s_setprio 1
	v_mfma_f32_16x16x128_f8f6f4 v[54:57], v[2:9], v[222:229], v[54:57]
	v_mfma_f32_16x16x128_f8f6f4 v[50:53], v[174:181], v[222:229], v[50:53]
	v_mfma_f32_16x16x128_f8f6f4 v[18:21], v[198:205], v[222:229], v[18:21]
	v_mfma_f32_16x16x128_f8f6f4 v[22:25], v[190:197], v[222:229], v[22:25]
	s_setprio 0
	s_setprio 1
	v_mfma_f32_16x16x128_f8f6f4 v[14:17], v[190:197], v[230:237], v[14:17]
	v_mfma_f32_16x16x128_f8f6f4 v[10:13], v[198:205], v[230:237], v[10:13]
	v_mfma_f32_16x16x128_f8f6f4 v[42:45], v[174:181], v[230:237], v[42:45]
	v_mfma_f32_16x16x128_f8f6f4 v[46:49], v[2:9], v[230:237], v[46:49]
	s_barrier
	s_setprio 0
	s_cmp_lt_u32 s95, 3
	s_cbranch_scc1 .LBB0_287
	s_add_u32 s54, s79, s9
	s_addc_u32 s55, s80, s8
	s_add_u32 s52, s52, 0x158180
	s_addc_u32 s53, s53, 0
	s_add_u32 s8, s50, 0x200
	v_lshl_add_u64 v[174:175], v[172:173], 2, s[54:55]
	s_addc_u32 s9, s51, 0
	s_mov_b32 s72, 4
	s_cmp_eq_u32 s95, s72
	s_cselect_b64 s[50:51], -1, 0
	s_cmp_lg_u32 s95, s72
	s_cbranch_scc1 .LBB0_285

.LBB0_285:
	ds_read_b128 v[2:5], v187
	ds_read_b128 v[6:9], v187 offset:1024
	ds_read_b128 v[190:193], v187 offset:2048
	ds_read_b128 v[194:197], v187 offset:3072
	ds_read_b128 v[198:201], v187 offset:16384
	ds_read_b128 v[202:205], v187 offset:17408
	ds_read_b128 v[206:209], v187 offset:18432
	ds_read_b128 v[210:213], v187 offset:19456
	s_add_u32 s54, s52, 0xffea8080
	s_addc_u32 s55, s53, -1
	s_and_b64 s[50:51], s[50:51], exec
	s_cselect_b32 s50, s4, s8
	s_cselect_b32 s55, s1, s55
	s_cselect_b32 s54, s0, s54
	s_cselect_b32 s51, s5, s9
	s_mov_b32 m0, s49
	v_lshl_add_u64 v[238:239], s[52:53], 0, v[162:163]
	ds_read_b128 v[176:179], v188
	ds_read_b128 v[180:183], v188 offset:1024
	ds_read_b128 v[214:217], v188 offset:2048
	ds_read_b128 v[218:221], v188 offset:3072
	ds_read_b128 v[222:225], v188 offset:4096
	ds_read_b128 v[226:229], v188 offset:5120
	ds_read_b128 v[230:233], v188 offset:6144
	ds_read_b128 v[234:237], v188 offset:7168
	global_load_lds_dwordx4 v[238:239], off
	v_lshl_add_u64 v[238:239], s[52:53], 0, v[164:165]
	s_mov_b32 m0, s71
	s_nop 0
	global_load_lds_dwordx4 v[238:239], off
	s_waitcnt vmcnt(8)
	s_waitcnt lgkmcnt(0)
	s_setprio 1
	s_barrier
	v_mfma_f32_16x16x128_f8f6f4 v[134:137], v[2:9], v[176:183], v[134:137]
	v_mfma_f32_16x16x128_f8f6f4 v[130:133], v[190:197], v[176:183], v[130:133]
	v_mfma_f32_16x16x128_f8f6f4 v[98:101], v[206:213], v[176:183], v[98:101]
	v_mfma_f32_16x16x128_f8f6f4 v[102:105], v[198:205], v[176:183], v[102:105]
	s_setprio 0
	s_setprio 1
	v_mfma_f32_16x16x128_f8f6f4 v[94:97], v[198:205], v[214:221], v[94:97]
	v_mfma_f32_16x16x128_f8f6f4 v[90:93], v[206:213], v[214:221], v[90:93]
	v_mfma_f32_16x16x128_f8f6f4 v[122:125], v[190:197], v[214:221], v[122:125]
	v_mfma_f32_16x16x128_f8f6f4 v[126:129], v[2:9], v[214:221], v[126:129]
	s_setprio 0
	s_setprio 1
	v_mfma_f32_16x16x128_f8f6f4 v[118:121], v[2:9], v[222:229], v[118:121]
	v_mfma_f32_16x16x128_f8f6f4 v[114:117], v[190:197], v[222:229], v[114:117]
	v_mfma_f32_16x16x128_f8f6f4 v[82:85], v[206:213], v[222:229], v[82:85]
	v_mfma_f32_16x16x128_f8f6f4 v[86:89], v[198:205], v[222:229], v[86:89]
	s_setprio 0
	s_setprio 1
	v_mfma_f32_16x16x128_f8f6f4 v[78:81], v[198:205], v[230:237], v[78:81]
	v_mfma_f32_16x16x128_f8f6f4 v[74:77], v[206:213], v[230:237], v[74:77]
	v_mfma_f32_16x16x128_f8f6f4 v[106:109], v[190:197], v[230:237], v[106:109]
	v_mfma_f32_16x16x128_f8f6f4 v[110:113], v[2:9], v[230:237], v[110:113]
	s_barrier
	s_setprio 0
	s_mov_b32 m0, s47
	v_lshl_add_u64 v[176:177], s[50:51], 0, v[156:157]
	s_add_u32 s62, s50, 0x158000
	ds_read_b128 v[214:217], v188 offset:16384
	ds_read_b128 v[218:221], v188 offset:17408
	ds_read_b128 v[222:225], v188 offset:18432
	ds_read_b128 v[226:229], v188 offset:19456
	ds_read_b128 v[230:233], v188 offset:20480
	ds_read_b128 v[234:237], v188 offset:21504
	ds_read_b128 v[242:245], v188 offset:22528
	ds_read_b128 v[246:249], v188 offset:23552
	global_load_lds_dwordx4 v[176:177], off
	v_lshl_add_u64 v[178:179], s[50:51], 0, v[160:161]
	s_mov_b32 m0, s68
	s_addc_u32 s63, s51, 0
	global_load_lds_dwordx4 v[178:179], off
	v_lshl_add_u64 v[180:181], s[62:63], 0, v[156:157]
	s_mov_b32 m0, s69
	v_lshl_add_u64 v[182:183], s[54:55], 0, v[158:159]
	global_load_lds_dwordx4 v[180:181], off
	v_lshl_add_u64 v[180:181], s[62:63], 0, v[160:161]
	s_mov_b32 m0, s74
	s_nop 0
	global_load_lds_dwordx4 v[180:181], off
	v_lshl_add_u64 v[180:181], s[54:55], 0, v[154:155]
	s_mov_b32 m0, s33
	s_nop 0
	global_load_lds_dwordx4 v[180:181], off
	s_mov_b32 m0, s75
	s_nop 0
	global_load_lds_dwordx4 v[182:183], off
	s_waitcnt vmcnt(8)
	s_waitcnt lgkmcnt(0)
	s_setprio 1
	s_barrier
	v_mfma_f32_16x16x128_f8f6f4 v[70:73], v[2:9], v[214:221], v[70:73]
	v_mfma_f32_16x16x128_f8f6f4 v[66:69], v[190:197], v[214:221], v[66:69]
	v_mfma_f32_16x16x128_f8f6f4 v[34:37], v[206:213], v[214:221], v[34:37]
	v_mfma_f32_16x16x128_f8f6f4 v[38:41], v[198:205], v[214:221], v[38:41]
	s_setprio 0
	s_setprio 1
	v_mfma_f32_16x16x128_f8f6f4 v[30:33], v[198:205], v[222:229], v[30:33]
	v_mfma_f32_16x16x128_f8f6f4 v[26:29], v[206:213], v[222:229], v[26:29]
	v_mfma_f32_16x16x128_f8f6f4 v[58:61], v[190:197], v[222:229], v[58:61]
	v_mfma_f32_16x16x128_f8f6f4 v[62:65], v[2:9], v[222:229], v[62:65]
	s_setprio 0
	s_setprio 1
	v_mfma_f32_16x16x128_f8f6f4 v[54:57], v[2:9], v[230:237], v[54:57]
	v_mfma_f32_16x16x128_f8f6f4 v[50:53], v[190:197], v[230:237], v[50:53]
	v_mfma_f32_16x16x128_f8f6f4 v[18:21], v[206:213], v[230:237], v[18:21]
	v_mfma_f32_16x16x128_f8f6f4 v[22:25], v[198:205], v[230:237], v[22:25]
	s_setprio 0
	s_setprio 1
	v_mfma_f32_16x16x128_f8f6f4 v[14:17], v[198:205], v[242:249], v[14:17]
	v_mfma_f32_16x16x128_f8f6f4 v[10:13], v[206:213], v[242:249], v[10:13]
	v_mfma_f32_16x16x128_f8f6f4 v[42:45], v[190:197], v[242:249], v[42:45]
	v_mfma_f32_16x16x128_f8f6f4 v[46:49], v[2:9], v[242:249], v[46:49]
	s_barrier
	s_setprio 0
	ds_read_b128 v[190:193], v187 offset:32768
	ds_read_b128 v[194:197], v187 offset:33792
	ds_read_b128 v[198:201], v187 offset:34816
	ds_read_b128 v[202:205], v187 offset:35840
	ds_read_b128 v[2:5], v187 offset:49152
	ds_read_b128 v[6:9], v187 offset:50176
	ds_read_b128 v[206:209], v187 offset:51200
	ds_read_b128 v[210:213], v187 offset:52224
	s_add_u32 s54, s54, 0x158000
	s_addc_u32 s55, s55, 0
	s_mov_b32 m0, s76
	v_lshl_add_u64 v[238:239], s[54:55], 0, v[154:155]
	ds_read_b128 v[214:217], v188 offset:32768
	ds_read_b128 v[218:221], v188 offset:33792
	ds_read_b128 v[222:225], v188 offset:34816
	ds_read_b128 v[226:229], v188 offset:35840
	ds_read_b128 v[230:233], v188 offset:36864
	ds_read_b128 v[234:237], v188 offset:37888
	ds_read_b128 v[242:245], v188 offset:38912
	ds_read_b128 v[246:249], v188 offset:39936
	global_load_lds_dwordx4 v[238:239], off
	v_lshl_add_u64 v[238:239], s[54:55], 0, v[158:159]
	s_mov_b32 m0, s77
	s_nop 0
	global_load_lds_dwordx4 v[238:239], off
	s_waitcnt vmcnt(8)
	s_waitcnt lgkmcnt(0)
	s_setprio 1
	s_barrier
	v_mfma_f32_16x16x128_f8f6f4 v[134:137], v[190:197], v[214:221], v[134:137]
	v_mfma_f32_16x16x128_f8f6f4 v[130:133], v[198:205], v[214:221], v[130:133]
	v_mfma_f32_16x16x128_f8f6f4 v[98:101], v[206:213], v[214:221], v[98:101]
	v_mfma_f32_16x16x128_f8f6f4 v[102:105], v[2:9], v[214:221], v[102:105]
	s_setprio 0
	s_setprio 1
	v_mfma_f32_16x16x128_f8f6f4 v[94:97], v[2:9], v[222:229], v[94:97]
	v_mfma_f32_16x16x128_f8f6f4 v[90:93], v[206:213], v[222:229], v[90:93]
	v_mfma_f32_16x16x128_f8f6f4 v[122:125], v[198:205], v[222:229], v[122:125]
	v_mfma_f32_16x16x128_f8f6f4 v[126:129], v[190:197], v[222:229], v[126:129]
	s_setprio 0
	s_setprio 1
	v_mfma_f32_16x16x128_f8f6f4 v[118:121], v[190:197], v[230:237], v[118:121]
	v_mfma_f32_16x16x128_f8f6f4 v[114:117], v[198:205], v[230:237], v[114:117]
	v_mfma_f32_16x16x128_f8f6f4 v[82:85], v[206:213], v[230:237], v[82:85]
	v_mfma_f32_16x16x128_f8f6f4 v[86:89], v[2:9], v[230:237], v[86:89]
	s_setprio 0
	s_setprio 1
	v_mfma_f32_16x16x128_f8f6f4 v[78:81], v[2:9], v[242:249], v[78:81]
	v_mfma_f32_16x16x128_f8f6f4 v[74:77], v[206:213], v[242:249], v[74:77]
	v_mfma_f32_16x16x128_f8f6f4 v[106:109], v[198:205], v[242:249], v[106:109]
	v_mfma_f32_16x16x128_f8f6f4 v[110:113], v[190:197], v[242:249], v[110:113]
	s_barrier
	s_setprio 0
	s_mov_b32 m0, s83
	v_lshl_add_u64 v[176:177], v[176:177], 0, s[26:27]
	s_add_u32 s50, s50, 0x158080
	ds_read_b128 v[214:217], v188 offset:49152
	ds_read_b128 v[218:221], v188 offset:50176
	ds_read_b128 v[222:225], v188 offset:51200
	ds_read_b128 v[226:229], v188 offset:52224
	ds_read_b128 v[230:233], v188 offset:53248
	ds_read_b128 v[234:237], v188 offset:54272
	ds_read_b128 v[242:245], v188 offset:55296
	ds_read_b128 v[246:249], v188 offset:56320
	global_load_lds_dwordx4 v[176:177], off
	v_lshl_add_u64 v[176:177], v[178:179], 0, s[26:27]
	s_mov_b32 m0, s84
	s_addc_u32 s51, s51, 0
	global_load_lds_dwordx4 v[176:177], off
	v_lshl_add_u64 v[176:177], s[50:51], 0, v[156:157]
	s_mov_b32 m0, s87
	s_nop 0
	global_load_lds_dwordx4 v[176:177], off
	v_lshl_add_u64 v[176:177], s[50:51], 0, v[160:161]
	s_mov_b32 m0, s88
	s_nop 0
	global_load_lds_dwordx4 v[176:177], off
	v_lshl_add_u64 v[176:177], v[180:181], 0, s[26:27]
	s_mov_b32 m0, s85
	s_nop 0
	global_load_lds_dwordx4 v[176:177], off
	v_lshl_add_u64 v[176:177], v[182:183], 0, s[26:27]
	s_mov_b32 m0, s86
	s_nop 0
	global_load_lds_dwordx4 v[176:177], off
	s_waitcnt vmcnt(8)
	s_waitcnt lgkmcnt(0)
	s_setprio 1
	s_barrier
	v_mfma_f32_16x16x128_f8f6f4 v[70:73], v[190:197], v[214:221], v[70:73]
	v_mfma_f32_16x16x128_f8f6f4 v[66:69], v[198:205], v[214:221], v[66:69]
	v_mfma_f32_16x16x128_f8f6f4 v[34:37], v[206:213], v[214:221], v[34:37]
	v_mfma_f32_16x16x128_f8f6f4 v[38:41], v[2:9], v[214:221], v[38:41]
	s_setprio 0
	s_setprio 1
	v_mfma_f32_16x16x128_f8f6f4 v[30:33], v[2:9], v[222:229], v[30:33]
	v_mfma_f32_16x16x128_f8f6f4 v[26:29], v[206:213], v[222:229], v[26:29]
	v_mfma_f32_16x16x128_f8f6f4 v[58:61], v[198:205], v[222:229], v[58:61]
	v_mfma_f32_16x16x128_f8f6f4 v[62:65], v[190:197], v[222:229], v[62:65]
	s_setprio 0
	s_setprio 1
	v_mfma_f32_16x16x128_f8f6f4 v[54:57], v[190:197], v[230:237], v[54:57]
	v_mfma_f32_16x16x128_f8f6f4 v[50:53], v[198:205], v[230:237], v[50:53]
	v_mfma_f32_16x16x128_f8f6f4 v[18:21], v[206:213], v[230:237], v[18:21]
	v_mfma_f32_16x16x128_f8f6f4 v[22:25], v[2:9], v[230:237], v[22:25]
	s_setprio 0
	s_setprio 1
	v_mfma_f32_16x16x128_f8f6f4 v[14:17], v[2:9], v[242:249], v[14:17]
	v_mfma_f32_16x16x128_f8f6f4 v[10:13], v[206:213], v[242:249], v[10:13]
	v_mfma_f32_16x16x128_f8f6f4 v[42:45], v[198:205], v[242:249], v[42:45]
	v_mfma_f32_16x16x128_f8f6f4 v[46:49], v[190:197], v[242:249], v[46:49]
	s_barrier
	s_setprio 0
	s_add_i32 s50, s72, 2
	s_add_u32 s52, s52, 0x100
	s_addc_u32 s53, s53, 0
	s_add_u32 s8, s8, 0x100
	s_addc_u32 s9, s9, 0
	s_cmp_ge_i32 s72, s95
	s_cbranch_scc1 .LBB0_287
	s_mov_b32 s72, s50
	s_cmp_eq_u32 s95, s72
	s_cselect_b64 s[50:51], -1, 0
	s_cmp_lg_u32 s95, s72
	s_cbranch_scc0 .LBB0_284
	s_branch .LBB0_285

.LBB0_437:
	s_ashr_i32 s47, s46, 31
	ds_read_b128 v[18:21], v200
	ds_read_b128 v[22:25], v200 offset:1024
	ds_read_b128 v[26:29], v200 offset:2048
	ds_read_b128 v[30:33], v200 offset:3072
	ds_read_b128 v[2:5], v200 offset:16384
	ds_read_b128 v[6:9], v200 offset:17408
	ds_read_b128 v[10:13], v200 offset:18432
	ds_read_b128 v[14:17], v200 offset:19456
	s_lshl_b64 s[8:9], s[46:47], 20
	s_add_u32 s48, s12, s8
	s_addc_u32 s49, s13, s9
	s_and_b64 s[8:9], s[2:3], exec
	s_cselect_b32 s47, s49, s73
	s_cselect_b32 s71, s48, s72
	s_ashr_i32 s45, s44, 31
	s_lshl_b64 s[8:9], s[44:45], 20
	s_add_u32 s50, s39, s8
	s_addc_u32 s51, s76, s9
	s_and_b64 s[8:9], s[2:3], exec
	s_cselect_b32 s45, s51, s55
	s_cselect_b32 s94, s50, s54
	s_add_u32 s8, s72, 0x80080
	s_addc_u32 s9, s73, 0
	s_mov_b32 m0, s33
	v_lshl_add_u64 v[226:227], s[8:9], 0, v[162:163]
	ds_read_b128 v[180:183], v201
	ds_read_b128 v[184:187], v201 offset:1024
	ds_read_b128 v[202:205], v201 offset:2048
	ds_read_b128 v[206:209], v201 offset:3072
	ds_read_b128 v[210:213], v201 offset:4096
	ds_read_b128 v[214:217], v201 offset:5120
	ds_read_b128 v[218:221], v201 offset:6144
	ds_read_b128 v[222:225], v201 offset:7168
	global_load_lds_dwordx4 v[226:227], off
	v_lshl_add_u64 v[226:227], s[8:9], 0, v[166:167]
	s_mov_b32 m0, s93
	s_nop 0
	global_load_lds_dwordx4 v[226:227], off
	s_waitcnt vmcnt(8)
	s_waitcnt lgkmcnt(0)
	s_setprio 1
	s_barrier
	v_mfma_f32_16x16x128_f8f6f4 v[158:161], v[18:25], v[180:187], 0
	v_mfma_f32_16x16x128_f8f6f4 v[154:157], v[26:33], v[180:187], 0
	v_mfma_f32_16x16x128_f8f6f4 v[122:125], v[10:17], v[180:187], 0
	v_mfma_f32_16x16x128_f8f6f4 v[126:129], v[2:9], v[180:187], 0
	s_setprio 0
	s_setprio 1
	v_mfma_f32_16x16x128_f8f6f4 v[118:121], v[2:9], v[202:209], 0
	v_mfma_f32_16x16x128_f8f6f4 v[114:117], v[10:17], v[202:209], 0
	v_mfma_f32_16x16x128_f8f6f4 v[146:149], v[26:33], v[202:209], 0
	v_mfma_f32_16x16x128_f8f6f4 v[150:153], v[18:25], v[202:209], 0
	s_setprio 0
	s_setprio 1
	v_mfma_f32_16x16x128_f8f6f4 v[142:145], v[18:25], v[210:217], 0
	v_mfma_f32_16x16x128_f8f6f4 v[138:141], v[26:33], v[210:217], 0
	v_mfma_f32_16x16x128_f8f6f4 v[106:109], v[10:17], v[210:217], 0
	v_mfma_f32_16x16x128_f8f6f4 v[110:113], v[2:9], v[210:217], 0
	s_setprio 0
	s_setprio 1
	v_mfma_f32_16x16x128_f8f6f4 v[102:105], v[2:9], v[218:225], 0
	v_mfma_f32_16x16x128_f8f6f4 v[98:101], v[10:17], v[218:225], 0
	v_mfma_f32_16x16x128_f8f6f4 v[130:133], v[26:33], v[218:225], 0
	v_mfma_f32_16x16x128_f8f6f4 v[134:137], v[18:25], v[218:225], 0
	s_barrier
	s_setprio 0
	v_lshl_add_u64 v[180:181], s[54:55], 0, v[164:165]
	s_mov_b32 m0, s78
	v_lshl_add_u64 v[182:183], v[180:181], 0, s[26:27]
	ds_read_b128 v[202:205], v201 offset:16384
	ds_read_b128 v[206:209], v201 offset:17408
	ds_read_b128 v[210:213], v201 offset:18432
	ds_read_b128 v[214:217], v201 offset:19456
	ds_read_b128 v[218:221], v201 offset:20480
	ds_read_b128 v[222:225], v201 offset:21504
	ds_read_b128 v[226:229], v201 offset:22528
	ds_read_b128 v[230:233], v201 offset:23552
	global_load_lds_dwordx4 v[182:183], off
	v_lshl_add_u64 v[182:183], s[54:55], 0, v[168:169]
	s_add_u32 s8, s54, 0x80100
	v_lshl_add_u64 v[184:185], v[182:183], 0, s[26:27]
	s_mov_b32 m0, s79
	s_addc_u32 s9, s55, 0
	global_load_lds_dwordx4 v[184:185], off
	v_lshl_add_u64 v[184:185], s[8:9], 0, v[164:165]
	s_mov_b32 m0, s80
	s_nop 0
	global_load_lds_dwordx4 v[184:185], off
	v_lshl_add_u64 v[184:185], s[8:9], 0, v[168:169]
	s_mov_b32 m0, s81
	s_nop 0
	global_load_lds_dwordx4 v[184:185], off
	v_lshl_add_u64 v[184:185], s[72:73], 0, v[162:163]
	v_lshl_add_u64 v[186:187], v[184:185], 0, s[26:27]
	s_mov_b32 m0, s53
	s_nop 0
	global_load_lds_dwordx4 v[186:187], off
	v_lshl_add_u64 v[186:187], s[72:73], 0, v[166:167]
	v_lshl_add_u64 v[234:235], v[186:187], 0, s[26:27]
	s_mov_b32 m0, s82
	s_nop 0
	global_load_lds_dwordx4 v[234:235], off
	s_waitcnt vmcnt(8)
	s_waitcnt lgkmcnt(0)
	s_setprio 1
	s_barrier
	v_mfma_f32_16x16x128_f8f6f4 v[94:97], v[18:25], v[202:209], 0
	v_mfma_f32_16x16x128_f8f6f4 v[90:93], v[26:33], v[202:209], 0
	v_mfma_f32_16x16x128_f8f6f4 v[58:61], v[10:17], v[202:209], 0
	v_mfma_f32_16x16x128_f8f6f4 v[62:65], v[2:9], v[202:209], 0
	s_setprio 0
	s_setprio 1
	v_mfma_f32_16x16x128_f8f6f4 v[54:57], v[2:9], v[210:217], 0
	v_mfma_f32_16x16x128_f8f6f4 v[50:53], v[10:17], v[210:217], 0
	v_mfma_f32_16x16x128_f8f6f4 v[82:85], v[26:33], v[210:217], 0
	v_mfma_f32_16x16x128_f8f6f4 v[86:89], v[18:25], v[210:217], 0
	s_setprio 0
	s_setprio 1
	v_mfma_f32_16x16x128_f8f6f4 v[78:81], v[18:25], v[218:225], 0
	v_mfma_f32_16x16x128_f8f6f4 v[74:77], v[26:33], v[218:225], 0
	v_mfma_f32_16x16x128_f8f6f4 v[42:45], v[10:17], v[218:225], 0
	v_mfma_f32_16x16x128_f8f6f4 v[46:49], v[2:9], v[218:225], 0
	s_setprio 0
	s_setprio 1
	v_mfma_f32_16x16x128_f8f6f4 v[38:41], v[2:9], v[226:233], 0
	v_mfma_f32_16x16x128_f8f6f4 v[34:37], v[10:17], v[226:233], 0
	v_mfma_f32_16x16x128_f8f6f4 v[66:69], v[26:33], v[226:233], 0
	v_mfma_f32_16x16x128_f8f6f4 v[70:73], v[18:25], v[226:233], 0
	s_barrier
	s_setprio 0
	ds_read_b128 v[18:21], v200 offset:32768
	ds_read_b128 v[22:25], v200 offset:33792
	ds_read_b128 v[26:29], v200 offset:34816
	ds_read_b128 v[30:33], v200 offset:35840
	ds_read_b128 v[2:5], v200 offset:49152
	ds_read_b128 v[6:9], v200 offset:50176
	ds_read_b128 v[10:13], v200 offset:51200
	ds_read_b128 v[14:17], v200 offset:52224
	s_add_u32 s8, s72, 0x80100
	s_addc_u32 s9, s73, 0
	s_mov_b32 m0, s83
	v_lshl_add_u64 v[234:235], s[8:9], 0, v[162:163]
	ds_read_b128 v[202:205], v201 offset:32768
	ds_read_b128 v[206:209], v201 offset:33792
	ds_read_b128 v[210:213], v201 offset:34816
	ds_read_b128 v[214:217], v201 offset:35840
	ds_read_b128 v[218:221], v201 offset:36864
	ds_read_b128 v[222:225], v201 offset:37888
	ds_read_b128 v[226:229], v201 offset:38912
	ds_read_b128 v[230:233], v201 offset:39936
	global_load_lds_dwordx4 v[234:235], off
	v_lshl_add_u64 v[234:235], s[8:9], 0, v[166:167]
	s_mov_b32 m0, s84
	s_nop 0
	global_load_lds_dwordx4 v[234:235], off
	s_waitcnt vmcnt(8)
	s_waitcnt lgkmcnt(0)
	s_setprio 1
	s_barrier
	v_mfma_f32_16x16x128_f8f6f4 v[158:161], v[18:25], v[202:209], v[158:161]
	v_mfma_f32_16x16x128_f8f6f4 v[154:157], v[26:33], v[202:209], v[154:157]
	v_mfma_f32_16x16x128_f8f6f4 v[122:125], v[10:17], v[202:209], v[122:125]
	v_mfma_f32_16x16x128_f8f6f4 v[126:129], v[2:9], v[202:209], v[126:129]
	s_setprio 0
	s_setprio 1
	v_mfma_f32_16x16x128_f8f6f4 v[118:121], v[2:9], v[210:217], v[118:121]
	v_mfma_f32_16x16x128_f8f6f4 v[114:117], v[10:17], v[210:217], v[114:117]
	v_mfma_f32_16x16x128_f8f6f4 v[146:149], v[26:33], v[210:217], v[146:149]
	v_mfma_f32_16x16x128_f8f6f4 v[150:153], v[18:25], v[210:217], v[150:153]
	s_setprio 0
	s_setprio 1
	v_mfma_f32_16x16x128_f8f6f4 v[142:145], v[18:25], v[218:225], v[142:145]
	v_mfma_f32_16x16x128_f8f6f4 v[138:141], v[26:33], v[218:225], v[138:141]
	v_mfma_f32_16x16x128_f8f6f4 v[106:109], v[10:17], v[218:225], v[106:109]
	v_mfma_f32_16x16x128_f8f6f4 v[110:113], v[2:9], v[218:225], v[110:113]
	s_setprio 0
	s_setprio 1
	v_mfma_f32_16x16x128_f8f6f4 v[102:105], v[2:9], v[226:233], v[102:105]
	v_mfma_f32_16x16x128_f8f6f4 v[98:101], v[10:17], v[226:233], v[98:101]
	v_mfma_f32_16x16x128_f8f6f4 v[130:133], v[26:33], v[226:233], v[130:133]
	v_mfma_f32_16x16x128_f8f6f4 v[134:137], v[18:25], v[226:233], v[134:137]
	s_barrier
	s_setprio 0
	s_mov_b32 m0, s87
	v_lshl_add_u64 v[180:181], v[180:181], 0, s[36:37]
	s_add_u32 s8, s54, 0x80180
	ds_read_b128 v[202:205], v201 offset:49152
	ds_read_b128 v[206:209], v201 offset:50176
	ds_read_b128 v[210:213], v201 offset:51200
	ds_read_b128 v[214:217], v201 offset:52224
	ds_read_b128 v[218:221], v201 offset:53248
	ds_read_b128 v[222:225], v201 offset:54272
	ds_read_b128 v[226:229], v201 offset:55296
	ds_read_b128 v[230:233], v201 offset:56320
	global_load_lds_dwordx4 v[180:181], off
	v_lshl_add_u64 v[180:181], v[182:183], 0, s[36:37]
	s_mov_b32 m0, s88
	s_addc_u32 s9, s55, 0
	global_load_lds_dwordx4 v[180:181], off
	v_lshl_add_u64 v[180:181], s[8:9], 0, v[164:165]
	s_mov_b32 m0, s91
	s_nop 0
	global_load_lds_dwordx4 v[180:181], off
	v_lshl_add_u64 v[180:181], s[8:9], 0, v[168:169]
	s_mov_b32 m0, s92
	s_nop 0
	global_load_lds_dwordx4 v[180:181], off
	v_lshl_add_u64 v[180:181], v[184:185], 0, s[36:37]
	s_mov_b32 m0, s89
	s_nop 0
	global_load_lds_dwordx4 v[180:181], off
	v_lshl_add_u64 v[180:181], v[186:187], 0, s[36:37]
	s_mov_b32 m0, s90
	s_nop 0
	global_load_lds_dwordx4 v[180:181], off
	s_waitcnt vmcnt(8)
	s_waitcnt lgkmcnt(0)
	s_setprio 1
	s_barrier
	v_mfma_f32_16x16x128_f8f6f4 v[94:97], v[18:25], v[202:209], v[94:97]
	v_mfma_f32_16x16x128_f8f6f4 v[90:93], v[26:33], v[202:209], v[90:93]
	v_mfma_f32_16x16x128_f8f6f4 v[58:61], v[10:17], v[202:209], v[58:61]
	v_mfma_f32_16x16x128_f8f6f4 v[62:65], v[2:9], v[202:209], v[62:65]
	s_setprio 0
	s_setprio 1
	v_mfma_f32_16x16x128_f8f6f4 v[54:57], v[2:9], v[210:217], v[54:57]
	v_mfma_f32_16x16x128_f8f6f4 v[50:53], v[10:17], v[210:217], v[50:53]
	v_mfma_f32_16x16x128_f8f6f4 v[82:85], v[26:33], v[210:217], v[82:85]
	v_mfma_f32_16x16x128_f8f6f4 v[86:89], v[18:25], v[210:217], v[86:89]
	s_setprio 0
	s_setprio 1
	v_mfma_f32_16x16x128_f8f6f4 v[78:81], v[18:25], v[218:225], v[78:81]
	v_mfma_f32_16x16x128_f8f6f4 v[74:77], v[26:33], v[218:225], v[74:77]
	v_mfma_f32_16x16x128_f8f6f4 v[42:45], v[10:17], v[218:225], v[42:45]
	v_mfma_f32_16x16x128_f8f6f4 v[46:49], v[2:9], v[218:225], v[46:49]
	s_setprio 0
	s_setprio 1
	v_mfma_f32_16x16x128_f8f6f4 v[38:41], v[2:9], v[226:233], v[38:41]
	v_mfma_f32_16x16x128_f8f6f4 v[34:37], v[10:17], v[226:233], v[34:37]
	v_mfma_f32_16x16x128_f8f6f4 v[66:69], v[26:33], v[226:233], v[66:69]
	v_mfma_f32_16x16x128_f8f6f4 v[70:73], v[18:25], v[226:233], v[70:73]
	s_barrier
	s_setprio 0
	s_add_u32 s72, s72, 0x80180
	s_addc_u32 s73, s73, 0
	s_add_u32 s8, s54, 0x200
	s_addc_u32 s9, s55, 0
	s_mov_b32 s62, 0
.LBB0_438:
	ds_read_b128 v[2:5], v200
	ds_read_b128 v[6:9], v200 offset:1024
	ds_read_b128 v[18:21], v200 offset:2048
	ds_read_b128 v[22:25], v200 offset:3072
	ds_read_b128 v[26:29], v200 offset:16384
	ds_read_b128 v[30:33], v200 offset:17408
	ds_read_b128 v[180:183], v200 offset:18432
	ds_read_b128 v[184:187], v200 offset:19456
	s_add_u32 s54, s72, 0xfff80080
	s_addc_u32 s55, s73, -1
	s_cmp_eq_u32 s62, 28
	s_cselect_b32 s75, s47, s55
	s_cselect_b32 s74, s71, s54
	s_cselect_b32 s55, s45, s9
	s_cselect_b32 s54, s94, s8
	s_mov_b32 m0, s33
	v_lshl_add_u64 v[226:227], s[72:73], 0, v[170:171]
	ds_read_b128 v[10:13], v201
	ds_read_b128 v[14:17], v201 offset:1024
	ds_read_b128 v[202:205], v201 offset:2048
	ds_read_b128 v[206:209], v201 offset:3072
	ds_read_b128 v[210:213], v201 offset:4096
	ds_read_b128 v[214:217], v201 offset:5120
	ds_read_b128 v[218:221], v201 offset:6144
	ds_read_b128 v[222:225], v201 offset:7168
	global_load_lds_dwordx4 v[226:227], off
	v_lshl_add_u64 v[226:227], s[72:73], 0, v[172:173]
	s_mov_b32 m0, s93
	s_nop 0
	global_load_lds_dwordx4 v[226:227], off
	s_waitcnt vmcnt(8)
	s_waitcnt lgkmcnt(0)
	s_setprio 1
	s_barrier
	v_mfma_f32_16x16x128_f8f6f4 v[158:161], v[2:9], v[10:17], v[158:161]
	v_mfma_f32_16x16x128_f8f6f4 v[154:157], v[18:25], v[10:17], v[154:157]
	v_mfma_f32_16x16x128_f8f6f4 v[122:125], v[180:187], v[10:17], v[122:125]
	v_mfma_f32_16x16x128_f8f6f4 v[126:129], v[26:33], v[10:17], v[126:129]
	s_setprio 0
	s_setprio 1
	v_mfma_f32_16x16x128_f8f6f4 v[118:121], v[26:33], v[202:209], v[118:121]
	v_mfma_f32_16x16x128_f8f6f4 v[114:117], v[180:187], v[202:209], v[114:117]
	v_mfma_f32_16x16x128_f8f6f4 v[146:149], v[18:25], v[202:209], v[146:149]
	v_mfma_f32_16x16x128_f8f6f4 v[150:153], v[2:9], v[202:209], v[150:153]
	s_setprio 0
	s_setprio 1
	v_mfma_f32_16x16x128_f8f6f4 v[142:145], v[2:9], v[210:217], v[142:145]
	v_mfma_f32_16x16x128_f8f6f4 v[138:141], v[18:25], v[210:217], v[138:141]
	v_mfma_f32_16x16x128_f8f6f4 v[106:109], v[180:187], v[210:217], v[106:109]
	v_mfma_f32_16x16x128_f8f6f4 v[110:113], v[26:33], v[210:217], v[110:113]
	s_setprio 0
	s_setprio 1
	v_mfma_f32_16x16x128_f8f6f4 v[102:105], v[26:33], v[218:225], v[102:105]
	v_mfma_f32_16x16x128_f8f6f4 v[98:101], v[180:187], v[218:225], v[98:101]
	v_mfma_f32_16x16x128_f8f6f4 v[130:133], v[18:25], v[218:225], v[130:133]
	v_mfma_f32_16x16x128_f8f6f4 v[134:137], v[2:9], v[218:225], v[134:137]
	s_barrier
	s_setprio 0
	s_mov_b32 m0, s78
	v_lshl_add_u64 v[10:11], s[54:55], 0, v[164:165]
	s_add_u32 s96, s54, 0x80000
	ds_read_b128 v[202:205], v201 offset:16384
	ds_read_b128 v[206:209], v201 offset:17408
	ds_read_b128 v[210:213], v201 offset:18432
	ds_read_b128 v[214:217], v201 offset:19456
	ds_read_b128 v[218:221], v201 offset:20480
	ds_read_b128 v[222:225], v201 offset:21504
	ds_read_b128 v[226:229], v201 offset:22528
	ds_read_b128 v[230:233], v201 offset:23552
	global_load_lds_dwordx4 v[10:11], off
	v_lshl_add_u64 v[12:13], s[54:55], 0, v[168:169]
	s_mov_b32 m0, s79
	s_addc_u32 s97, s55, 0
	global_load_lds_dwordx4 v[12:13], off
	v_lshl_add_u64 v[14:15], s[96:97], 0, v[164:165]
	s_mov_b32 m0, s80
	v_lshl_add_u64 v[16:17], s[74:75], 0, v[166:167]
	global_load_lds_dwordx4 v[14:15], off
	v_lshl_add_u64 v[14:15], s[96:97], 0, v[168:169]
	s_mov_b32 m0, s81
	s_nop 0
	global_load_lds_dwordx4 v[14:15], off
	v_lshl_add_u64 v[14:15], s[74:75], 0, v[162:163]
	s_mov_b32 m0, s53
	s_nop 0
	global_load_lds_dwordx4 v[14:15], off
	s_mov_b32 m0, s82
	s_nop 0
	global_load_lds_dwordx4 v[16:17], off
	s_waitcnt vmcnt(8)
	s_waitcnt lgkmcnt(0)
	s_setprio 1
	s_barrier
	v_mfma_f32_16x16x128_f8f6f4 v[94:97], v[2:9], v[202:209], v[94:97]
	v_mfma_f32_16x16x128_f8f6f4 v[90:93], v[18:25], v[202:209], v[90:93]
	v_mfma_f32_16x16x128_f8f6f4 v[58:61], v[180:187], v[202:209], v[58:61]
	v_mfma_f32_16x16x128_f8f6f4 v[62:65], v[26:33], v[202:209], v[62:65]
	s_setprio 0
	s_setprio 1
	v_mfma_f32_16x16x128_f8f6f4 v[54:57], v[26:33], v[210:217], v[54:57]
	v_mfma_f32_16x16x128_f8f6f4 v[50:53], v[180:187], v[210:217], v[50:53]
	v_mfma_f32_16x16x128_f8f6f4 v[82:85], v[18:25], v[210:217], v[82:85]
	v_mfma_f32_16x16x128_f8f6f4 v[86:89], v[2:9], v[210:217], v[86:89]
	s_setprio 0
	s_setprio 1
	v_mfma_f32_16x16x128_f8f6f4 v[78:81], v[2:9], v[218:225], v[78:81]
	v_mfma_f32_16x16x128_f8f6f4 v[74:77], v[18:25], v[218:225], v[74:77]
	v_mfma_f32_16x16x128_f8f6f4 v[42:45], v[180:187], v[218:225], v[42:45]
	v_mfma_f32_16x16x128_f8f6f4 v[46:49], v[26:33], v[218:225], v[46:49]
	s_setprio 0
	s_setprio 1
	v_mfma_f32_16x16x128_f8f6f4 v[38:41], v[26:33], v[226:233], v[38:41]
	v_mfma_f32_16x16x128_f8f6f4 v[34:37], v[180:187], v[226:233], v[34:37]
	v_mfma_f32_16x16x128_f8f6f4 v[66:69], v[18:25], v[226:233], v[66:69]
	v_mfma_f32_16x16x128_f8f6f4 v[70:73], v[2:9], v[226:233], v[70:73]
	s_barrier
	s_setprio 0
	ds_read_b128 v[18:21], v200 offset:32768
	ds_read_b128 v[22:25], v200 offset:33792
	ds_read_b128 v[26:29], v200 offset:34816
	ds_read_b128 v[30:33], v200 offset:35840
	ds_read_b128 v[2:5], v200 offset:49152
	ds_read_b128 v[6:9], v200 offset:50176
	ds_read_b128 v[180:183], v200 offset:51200
	ds_read_b128 v[184:187], v200 offset:52224
	s_add_u32 s74, s74, 0x80000
	s_addc_u32 s75, s75, 0
	s_mov_b32 m0, s83
	v_lshl_add_u64 v[234:235], s[74:75], 0, v[162:163]
	ds_read_b128 v[202:205], v201 offset:32768
	ds_read_b128 v[206:209], v201 offset:33792
	ds_read_b128 v[210:213], v201 offset:34816
	ds_read_b128 v[214:217], v201 offset:35840
	ds_read_b128 v[218:221], v201 offset:36864
	ds_read_b128 v[222:225], v201 offset:37888
	ds_read_b128 v[226:229], v201 offset:38912
	ds_read_b128 v[230:233], v201 offset:39936
	global_load_lds_dwordx4 v[234:235], off
	v_lshl_add_u64 v[234:235], s[74:75], 0, v[166:167]
	s_mov_b32 m0, s84
	s_nop 0
	global_load_lds_dwordx4 v[234:235], off
	s_waitcnt vmcnt(8)
	s_waitcnt lgkmcnt(0)
	s_setprio 1
	s_barrier
	v_mfma_f32_16x16x128_f8f6f4 v[158:161], v[18:25], v[202:209], v[158:161]
	v_mfma_f32_16x16x128_f8f6f4 v[154:157], v[26:33], v[202:209], v[154:157]
	v_mfma_f32_16x16x128_f8f6f4 v[122:125], v[180:187], v[202:209], v[122:125]
	v_mfma_f32_16x16x128_f8f6f4 v[126:129], v[2:9], v[202:209], v[126:129]
	s_setprio 0
	s_setprio 1
	v_mfma_f32_16x16x128_f8f6f4 v[118:121], v[2:9], v[210:217], v[118:121]
	v_mfma_f32_16x16x128_f8f6f4 v[114:117], v[180:187], v[210:217], v[114:117]
	v_mfma_f32_16x16x128_f8f6f4 v[146:149], v[26:33], v[210:217], v[146:149]
	v_mfma_f32_16x16x128_f8f6f4 v[150:153], v[18:25], v[210:217], v[150:153]
	s_setprio 0
	s_setprio 1
	v_mfma_f32_16x16x128_f8f6f4 v[142:145], v[18:25], v[218:225], v[142:145]
	v_mfma_f32_16x16x128_f8f6f4 v[138:141], v[26:33], v[218:225], v[138:141]
	v_mfma_f32_16x16x128_f8f6f4 v[106:109], v[180:187], v[218:225], v[106:109]
	v_mfma_f32_16x16x128_f8f6f4 v[110:113], v[2:9], v[218:225], v[110:113]
	s_setprio 0
	s_setprio 1
	v_mfma_f32_16x16x128_f8f6f4 v[102:105], v[2:9], v[226:233], v[102:105]
	v_mfma_f32_16x16x128_f8f6f4 v[98:101], v[180:187], v[226:233], v[98:101]
	v_mfma_f32_16x16x128_f8f6f4 v[130:133], v[26:33], v[226:233], v[130:133]
	v_mfma_f32_16x16x128_f8f6f4 v[134:137], v[18:25], v[226:233], v[134:137]
	s_barrier
	s_setprio 0
	s_mov_b32 m0, s87
	v_lshl_add_u64 v[10:11], v[10:11], 0, s[4:5]
	s_add_u32 s54, s54, 0x80080
	ds_read_b128 v[202:205], v201 offset:49152
	ds_read_b128 v[206:209], v201 offset:50176
	ds_read_b128 v[210:213], v201 offset:51200
	ds_read_b128 v[214:217], v201 offset:52224
	ds_read_b128 v[218:221], v201 offset:53248
	ds_read_b128 v[222:225], v201 offset:54272
	ds_read_b128 v[226:229], v201 offset:55296
	ds_read_b128 v[230:233], v201 offset:56320
	global_load_lds_dwordx4 v[10:11], off
	v_lshl_add_u64 v[10:11], v[12:13], 0, s[4:5]
	s_mov_b32 m0, s88
	s_addc_u32 s55, s55, 0
	global_load_lds_dwordx4 v[10:11], off
	v_lshl_add_u64 v[10:11], s[54:55], 0, v[164:165]
	s_mov_b32 m0, s91
	s_nop 0
	global_load_lds_dwordx4 v[10:11], off
	v_lshl_add_u64 v[10:11], s[54:55], 0, v[168:169]
	s_mov_b32 m0, s92
	s_nop 0
	global_load_lds_dwordx4 v[10:11], off
	v_lshl_add_u64 v[10:11], v[14:15], 0, s[4:5]
	s_mov_b32 m0, s89
	s_nop 0
	global_load_lds_dwordx4 v[10:11], off
	v_lshl_add_u64 v[10:11], v[16:17], 0, s[4:5]
	s_mov_b32 m0, s90
	s_nop 0
	global_load_lds_dwordx4 v[10:11], off
	s_waitcnt vmcnt(8)
	s_waitcnt lgkmcnt(0)
	s_setprio 1
	s_barrier
	v_mfma_f32_16x16x128_f8f6f4 v[94:97], v[18:25], v[202:209], v[94:97]
	v_mfma_f32_16x16x128_f8f6f4 v[90:93], v[26:33], v[202:209], v[90:93]
	v_mfma_f32_16x16x128_f8f6f4 v[58:61], v[180:187], v[202:209], v[58:61]
	v_mfma_f32_16x16x128_f8f6f4 v[62:65], v[2:9], v[202:209], v[62:65]
	s_setprio 0
	s_setprio 1
	v_mfma_f32_16x16x128_f8f6f4 v[54:57], v[2:9], v[210:217], v[54:57]
	v_mfma_f32_16x16x128_f8f6f4 v[50:53], v[180:187], v[210:217], v[50:53]
	v_mfma_f32_16x16x128_f8f6f4 v[82:85], v[26:33], v[210:217], v[82:85]
	v_mfma_f32_16x16x128_f8f6f4 v[86:89], v[18:25], v[210:217], v[86:89]
	s_setprio 0
	s_setprio 1
	v_mfma_f32_16x16x128_f8f6f4 v[78:81], v[18:25], v[218:225], v[78:81]
	v_mfma_f32_16x16x128_f8f6f4 v[74:77], v[26:33], v[218:225], v[74:77]
	v_mfma_f32_16x16x128_f8f6f4 v[42:45], v[180:187], v[218:225], v[42:45]
	v_mfma_f32_16x16x128_f8f6f4 v[46:49], v[2:9], v[218:225], v[46:49]
	s_setprio 0
	s_setprio 1
	v_mfma_f32_16x16x128_f8f6f4 v[38:41], v[2:9], v[226:233], v[38:41]
	v_mfma_f32_16x16x128_f8f6f4 v[34:37], v[180:187], v[226:233], v[34:37]
	v_mfma_f32_16x16x128_f8f6f4 v[66:69], v[26:33], v[226:233], v[66:69]
	v_mfma_f32_16x16x128_f8f6f4 v[70:73], v[18:25], v[226:233], v[70:73]
	s_barrier
	s_setprio 0
	s_add_i32 s62, s62, 2
	s_add_u32 s72, s72, 0x100
	s_addc_u32 s73, s73, 0
	s_add_u32 s8, s8, 0x100
	s_addc_u32 s9, s9, 0
	s_cmp_gt_u32 s62, 29
	s_cbranch_scc0 .LBB0_438
	s_and_b64 vcc, exec, s[6:7]
	s_cbranch_vccz .LBB0_441
	s_barrier

.LBB0_600:
	s_ashr_i32 s55, s54, 31
	ds_read_b128 v[18:21], v200
	ds_read_b128 v[22:25], v200 offset:1024
	ds_read_b128 v[26:29], v200 offset:2048
	ds_read_b128 v[30:33], v200 offset:3072
	ds_read_b128 v[2:5], v200 offset:16384
	ds_read_b128 v[6:9], v200 offset:17408
	ds_read_b128 v[10:13], v200 offset:18432
	ds_read_b128 v[14:17], v200 offset:19456
	s_lshl_b64 s[4:5], s[54:55], 18
	s_add_u32 s72, s38, s4
	s_addc_u32 s73, s39, s5
	s_and_b64 s[4:5], s[2:3], exec
	s_cselect_b32 s4, s73, s81
	s_cselect_b32 s5, s72, s80
	s_ashr_i32 s53, s52, 31
	s_lshl_b64 s[8:9], s[52:53], 18
	s_add_u32 s74, s94, s8
	v_readlane_b32 s8, v254, 6
	s_addc_u32 s75, s8, s9
	s_and_b64 s[8:9], s[2:3], exec
	s_cselect_b32 s53, s75, s79
	s_cselect_b32 s55, s74, s78
	s_add_u32 s8, s80, 0x20080
	s_addc_u32 s9, s81, 0
	s_mov_b32 m0, s96
	v_lshl_add_u64 v[226:227], s[8:9], 0, v[162:163]
	ds_read_b128 v[182:185], v201
	ds_read_b128 v[186:189], v201 offset:1024
	ds_read_b128 v[202:205], v201 offset:2048
	ds_read_b128 v[206:209], v201 offset:3072
	ds_read_b128 v[210:213], v201 offset:4096
	ds_read_b128 v[214:217], v201 offset:5120
	ds_read_b128 v[218:221], v201 offset:6144
	ds_read_b128 v[222:225], v201 offset:7168
	global_load_lds_dwordx4 v[226:227], off
	v_lshl_add_u64 v[226:227], s[8:9], 0, v[166:167]
	s_mov_b32 m0, s61
	s_nop 0
	global_load_lds_dwordx4 v[226:227], off
	s_waitcnt vmcnt(8)
	s_waitcnt lgkmcnt(0)
	s_setprio 1
	s_barrier
	v_mfma_f32_16x16x128_f8f6f4 v[158:161], v[18:25], v[182:189], 0
	v_mfma_f32_16x16x128_f8f6f4 v[154:157], v[26:33], v[182:189], 0
	v_mfma_f32_16x16x128_f8f6f4 v[122:125], v[10:17], v[182:189], 0
	v_mfma_f32_16x16x128_f8f6f4 v[126:129], v[2:9], v[182:189], 0
	s_setprio 0
	s_setprio 1
	v_mfma_f32_16x16x128_f8f6f4 v[118:121], v[2:9], v[202:209], 0
	v_mfma_f32_16x16x128_f8f6f4 v[114:117], v[10:17], v[202:209], 0
	v_mfma_f32_16x16x128_f8f6f4 v[146:149], v[26:33], v[202:209], 0
	v_mfma_f32_16x16x128_f8f6f4 v[150:153], v[18:25], v[202:209], 0
	s_setprio 0
	s_setprio 1
	v_mfma_f32_16x16x128_f8f6f4 v[142:145], v[18:25], v[210:217], 0
	v_mfma_f32_16x16x128_f8f6f4 v[138:141], v[26:33], v[210:217], 0
	v_mfma_f32_16x16x128_f8f6f4 v[106:109], v[10:17], v[210:217], 0
	v_mfma_f32_16x16x128_f8f6f4 v[110:113], v[2:9], v[210:217], 0
	s_setprio 0
	s_setprio 1
	v_mfma_f32_16x16x128_f8f6f4 v[102:105], v[2:9], v[218:225], 0
	v_mfma_f32_16x16x128_f8f6f4 v[98:101], v[10:17], v[218:225], 0
	v_mfma_f32_16x16x128_f8f6f4 v[130:133], v[26:33], v[218:225], 0
	v_mfma_f32_16x16x128_f8f6f4 v[134:137], v[18:25], v[218:225], 0
	s_barrier
	s_setprio 0
	v_lshl_add_u64 v[182:183], s[78:79], 0, v[164:165]
	s_mov_b32 m0, s68
	v_lshl_add_u64 v[184:185], v[182:183], 0, s[46:47]
	ds_read_b128 v[202:205], v201 offset:16384
	ds_read_b128 v[206:209], v201 offset:17408
	ds_read_b128 v[210:213], v201 offset:18432
	ds_read_b128 v[214:217], v201 offset:19456
	ds_read_b128 v[218:221], v201 offset:20480
	ds_read_b128 v[222:225], v201 offset:21504
	ds_read_b128 v[226:229], v201 offset:22528
	ds_read_b128 v[230:233], v201 offset:23552
	global_load_lds_dwordx4 v[184:185], off
	v_lshl_add_u64 v[184:185], s[78:79], 0, v[168:169]
	s_add_u32 s8, s78, 0x20100
	v_lshl_add_u64 v[186:187], v[184:185], 0, s[46:47]
	s_mov_b32 m0, s69
	s_addc_u32 s9, s79, 0
	global_load_lds_dwordx4 v[186:187], off
	v_lshl_add_u64 v[186:187], s[8:9], 0, v[164:165]
	s_mov_b32 m0, s77
	s_nop 0
	global_load_lds_dwordx4 v[186:187], off
	v_lshl_add_u64 v[186:187], s[8:9], 0, v[168:169]
	s_mov_b32 m0, s84
	s_nop 0
	global_load_lds_dwordx4 v[186:187], off
	v_lshl_add_u64 v[186:187], s[80:81], 0, v[162:163]
	v_lshl_add_u64 v[188:189], v[186:187], 0, s[46:47]
	s_mov_b32 m0, s33
	s_nop 0
	global_load_lds_dwordx4 v[188:189], off
	v_lshl_add_u64 v[188:189], s[80:81], 0, v[166:167]
	v_lshl_add_u64 v[234:235], v[188:189], 0, s[46:47]
	s_mov_b32 m0, s85
	s_nop 0
	global_load_lds_dwordx4 v[234:235], off
	s_waitcnt vmcnt(8)
	s_waitcnt lgkmcnt(0)
	s_setprio 1
	s_barrier
	v_mfma_f32_16x16x128_f8f6f4 v[94:97], v[18:25], v[202:209], 0
	v_mfma_f32_16x16x128_f8f6f4 v[90:93], v[26:33], v[202:209], 0
	v_mfma_f32_16x16x128_f8f6f4 v[58:61], v[10:17], v[202:209], 0
	v_mfma_f32_16x16x128_f8f6f4 v[62:65], v[2:9], v[202:209], 0
	s_setprio 0
	s_setprio 1
	v_mfma_f32_16x16x128_f8f6f4 v[54:57], v[2:9], v[210:217], 0
	v_mfma_f32_16x16x128_f8f6f4 v[50:53], v[10:17], v[210:217], 0
	v_mfma_f32_16x16x128_f8f6f4 v[82:85], v[26:33], v[210:217], 0
	v_mfma_f32_16x16x128_f8f6f4 v[86:89], v[18:25], v[210:217], 0
	s_setprio 0
	s_setprio 1
	v_mfma_f32_16x16x128_f8f6f4 v[78:81], v[18:25], v[218:225], 0
	v_mfma_f32_16x16x128_f8f6f4 v[74:77], v[26:33], v[218:225], 0
	v_mfma_f32_16x16x128_f8f6f4 v[42:45], v[10:17], v[218:225], 0
	v_mfma_f32_16x16x128_f8f6f4 v[46:49], v[2:9], v[218:225], 0
	s_setprio 0
	s_setprio 1
	v_mfma_f32_16x16x128_f8f6f4 v[38:41], v[2:9], v[226:233], 0
	v_mfma_f32_16x16x128_f8f6f4 v[34:37], v[10:17], v[226:233], 0
	v_mfma_f32_16x16x128_f8f6f4 v[66:69], v[26:33], v[226:233], 0
	v_mfma_f32_16x16x128_f8f6f4 v[70:73], v[18:25], v[226:233], 0
	s_barrier
	s_setprio 0
	ds_read_b128 v[18:21], v200 offset:32768
	ds_read_b128 v[22:25], v200 offset:33792
	ds_read_b128 v[26:29], v200 offset:34816
	ds_read_b128 v[30:33], v200 offset:35840
	ds_read_b128 v[2:5], v200 offset:49152
	ds_read_b128 v[6:9], v200 offset:50176
	ds_read_b128 v[10:13], v200 offset:51200
	ds_read_b128 v[14:17], v200 offset:52224
	s_add_u32 s8, s80, 0x20100
	s_addc_u32 s9, s81, 0
	s_mov_b32 m0, s86
	v_lshl_add_u64 v[234:235], s[8:9], 0, v[162:163]
	ds_read_b128 v[202:205], v201 offset:32768
	ds_read_b128 v[206:209], v201 offset:33792
	ds_read_b128 v[210:213], v201 offset:34816
	ds_read_b128 v[214:217], v201 offset:35840
	ds_read_b128 v[218:221], v201 offset:36864
	ds_read_b128 v[222:225], v201 offset:37888
	ds_read_b128 v[226:229], v201 offset:38912
	ds_read_b128 v[230:233], v201 offset:39936
	global_load_lds_dwordx4 v[234:235], off
	v_lshl_add_u64 v[234:235], s[8:9], 0, v[166:167]
	s_mov_b32 m0, s87
	s_nop 0
	global_load_lds_dwordx4 v[234:235], off
	s_waitcnt vmcnt(8)
	s_waitcnt lgkmcnt(0)
	s_setprio 1
	s_barrier
	v_mfma_f32_16x16x128_f8f6f4 v[158:161], v[18:25], v[202:209], v[158:161]
	v_mfma_f32_16x16x128_f8f6f4 v[154:157], v[26:33], v[202:209], v[154:157]
	v_mfma_f32_16x16x128_f8f6f4 v[122:125], v[10:17], v[202:209], v[122:125]
	v_mfma_f32_16x16x128_f8f6f4 v[126:129], v[2:9], v[202:209], v[126:129]
	s_setprio 0
	s_setprio 1
	v_mfma_f32_16x16x128_f8f6f4 v[118:121], v[2:9], v[210:217], v[118:121]
	v_mfma_f32_16x16x128_f8f6f4 v[114:117], v[10:17], v[210:217], v[114:117]
	v_mfma_f32_16x16x128_f8f6f4 v[146:149], v[26:33], v[210:217], v[146:149]
	v_mfma_f32_16x16x128_f8f6f4 v[150:153], v[18:25], v[210:217], v[150:153]
	s_setprio 0
	s_setprio 1
	v_mfma_f32_16x16x128_f8f6f4 v[142:145], v[18:25], v[218:225], v[142:145]
	v_mfma_f32_16x16x128_f8f6f4 v[138:141], v[26:33], v[218:225], v[138:141]
	v_mfma_f32_16x16x128_f8f6f4 v[106:109], v[10:17], v[218:225], v[106:109]
	v_mfma_f32_16x16x128_f8f6f4 v[110:113], v[2:9], v[218:225], v[110:113]
	s_setprio 0
	s_setprio 1
	v_mfma_f32_16x16x128_f8f6f4 v[102:105], v[2:9], v[226:233], v[102:105]
	v_mfma_f32_16x16x128_f8f6f4 v[98:101], v[10:17], v[226:233], v[98:101]
	v_mfma_f32_16x16x128_f8f6f4 v[130:133], v[26:33], v[226:233], v[130:133]
	v_mfma_f32_16x16x128_f8f6f4 v[134:137], v[18:25], v[226:233], v[134:137]
	s_barrier
	s_setprio 0
	s_mov_b32 m0, s89
	v_lshl_add_u64 v[182:183], v[182:183], 0, s[48:49]
	s_add_u32 s8, s78, 0x20180
	ds_read_b128 v[202:205], v201 offset:49152
	ds_read_b128 v[206:209], v201 offset:50176
	ds_read_b128 v[210:213], v201 offset:51200
	ds_read_b128 v[214:217], v201 offset:52224
	ds_read_b128 v[218:221], v201 offset:53248
	ds_read_b128 v[222:225], v201 offset:54272
	ds_read_b128 v[226:229], v201 offset:55296
	ds_read_b128 v[230:233], v201 offset:56320
	global_load_lds_dwordx4 v[182:183], off
	v_lshl_add_u64 v[182:183], v[184:185], 0, s[48:49]
	s_mov_b32 m0, s90
	s_addc_u32 s9, s79, 0
	global_load_lds_dwordx4 v[182:183], off
	v_lshl_add_u64 v[182:183], s[8:9], 0, v[164:165]
	s_mov_b32 m0, s93
	s_nop 0
	global_load_lds_dwordx4 v[182:183], off
	v_lshl_add_u64 v[182:183], s[8:9], 0, v[168:169]
	s_mov_b32 m0, s95
	s_nop 0
	global_load_lds_dwordx4 v[182:183], off
	v_lshl_add_u64 v[182:183], v[186:187], 0, s[48:49]
	s_mov_b32 m0, s91
	s_nop 0
	global_load_lds_dwordx4 v[182:183], off
	v_lshl_add_u64 v[182:183], v[188:189], 0, s[48:49]
	s_mov_b32 m0, s92
	s_nop 0
	global_load_lds_dwordx4 v[182:183], off
	s_waitcnt vmcnt(8)
	s_waitcnt lgkmcnt(0)
	s_setprio 1
	s_barrier
	v_mfma_f32_16x16x128_f8f6f4 v[94:97], v[18:25], v[202:209], v[94:97]
	v_mfma_f32_16x16x128_f8f6f4 v[90:93], v[26:33], v[202:209], v[90:93]
	v_mfma_f32_16x16x128_f8f6f4 v[58:61], v[10:17], v[202:209], v[58:61]
	v_mfma_f32_16x16x128_f8f6f4 v[62:65], v[2:9], v[202:209], v[62:65]
	s_setprio 0
	s_setprio 1
	v_mfma_f32_16x16x128_f8f6f4 v[54:57], v[2:9], v[210:217], v[54:57]
	v_mfma_f32_16x16x128_f8f6f4 v[50:53], v[10:17], v[210:217], v[50:53]
	v_mfma_f32_16x16x128_f8f6f4 v[82:85], v[26:33], v[210:217], v[82:85]
	v_mfma_f32_16x16x128_f8f6f4 v[86:89], v[18:25], v[210:217], v[86:89]
	s_setprio 0
	s_setprio 1
	v_mfma_f32_16x16x128_f8f6f4 v[78:81], v[18:25], v[218:225], v[78:81]
	v_mfma_f32_16x16x128_f8f6f4 v[74:77], v[26:33], v[218:225], v[74:77]
	v_mfma_f32_16x16x128_f8f6f4 v[42:45], v[10:17], v[218:225], v[42:45]
	v_mfma_f32_16x16x128_f8f6f4 v[46:49], v[2:9], v[218:225], v[46:49]
	s_setprio 0
	s_setprio 1
	v_mfma_f32_16x16x128_f8f6f4 v[38:41], v[2:9], v[226:233], v[38:41]
	v_mfma_f32_16x16x128_f8f6f4 v[34:37], v[10:17], v[226:233], v[34:37]
	v_mfma_f32_16x16x128_f8f6f4 v[66:69], v[26:33], v[226:233], v[66:69]
	v_mfma_f32_16x16x128_f8f6f4 v[70:73], v[18:25], v[226:233], v[70:73]
	s_barrier
	s_setprio 0
	s_add_u32 s80, s80, 0x20180
	s_addc_u32 s81, s81, 0
	s_add_u32 s8, s78, 0x200
	s_addc_u32 s9, s79, 0
	s_mov_b32 s62, 0
.LBB0_601:
	ds_read_b128 v[2:5], v200
	ds_read_b128 v[6:9], v200 offset:1024
	ds_read_b128 v[18:21], v200 offset:2048
	ds_read_b128 v[22:25], v200 offset:3072
	ds_read_b128 v[26:29], v200 offset:16384
	ds_read_b128 v[30:33], v200 offset:17408
	ds_read_b128 v[182:185], v200 offset:18432
	ds_read_b128 v[186:189], v200 offset:19456
	s_add_u32 s63, s80, 0xfffe0080
	s_addc_u32 s71, s81, -1
	s_cmp_eq_u32 s62, 4
	s_cselect_b32 s83, s4, s71
	s_cselect_b32 s82, s5, s63
	s_cselect_b32 s79, s53, s9
	s_cselect_b32 s78, s55, s8
	s_mov_b32 m0, s96
	v_lshl_add_u64 v[226:227], s[80:81], 0, v[170:171]
	ds_read_b128 v[10:13], v201
	ds_read_b128 v[14:17], v201 offset:1024
	ds_read_b128 v[202:205], v201 offset:2048
	ds_read_b128 v[206:209], v201 offset:3072
	ds_read_b128 v[210:213], v201 offset:4096
	ds_read_b128 v[214:217], v201 offset:5120
	ds_read_b128 v[218:221], v201 offset:6144
	ds_read_b128 v[222:225], v201 offset:7168
	global_load_lds_dwordx4 v[226:227], off
	v_lshl_add_u64 v[226:227], s[80:81], 0, v[172:173]
	s_mov_b32 m0, s61
	s_nop 0
	global_load_lds_dwordx4 v[226:227], off
	s_waitcnt vmcnt(8)
	s_waitcnt lgkmcnt(0)
	s_setprio 1
	s_barrier
	v_mfma_f32_16x16x128_f8f6f4 v[158:161], v[2:9], v[10:17], v[158:161]
	v_mfma_f32_16x16x128_f8f6f4 v[154:157], v[18:25], v[10:17], v[154:157]
	v_mfma_f32_16x16x128_f8f6f4 v[122:125], v[182:189], v[10:17], v[122:125]
	v_mfma_f32_16x16x128_f8f6f4 v[126:129], v[26:33], v[10:17], v[126:129]
	s_setprio 0
	s_setprio 1
	v_mfma_f32_16x16x128_f8f6f4 v[118:121], v[26:33], v[202:209], v[118:121]
	v_mfma_f32_16x16x128_f8f6f4 v[114:117], v[182:189], v[202:209], v[114:117]
	v_mfma_f32_16x16x128_f8f6f4 v[146:149], v[18:25], v[202:209], v[146:149]
	v_mfma_f32_16x16x128_f8f6f4 v[150:153], v[2:9], v[202:209], v[150:153]
	s_setprio 0
	s_setprio 1
	v_mfma_f32_16x16x128_f8f6f4 v[142:145], v[2:9], v[210:217], v[142:145]
	v_mfma_f32_16x16x128_f8f6f4 v[138:141], v[18:25], v[210:217], v[138:141]
	v_mfma_f32_16x16x128_f8f6f4 v[106:109], v[182:189], v[210:217], v[106:109]
	v_mfma_f32_16x16x128_f8f6f4 v[110:113], v[26:33], v[210:217], v[110:113]
	s_setprio 0
	s_setprio 1
	v_mfma_f32_16x16x128_f8f6f4 v[102:105], v[26:33], v[218:225], v[102:105]
	v_mfma_f32_16x16x128_f8f6f4 v[98:101], v[182:189], v[218:225], v[98:101]
	v_mfma_f32_16x16x128_f8f6f4 v[130:133], v[18:25], v[218:225], v[130:133]
	v_mfma_f32_16x16x128_f8f6f4 v[134:137], v[2:9], v[218:225], v[134:137]
	s_barrier
	s_setprio 0
	s_mov_b32 m0, s68
	v_lshl_add_u64 v[10:11], s[78:79], 0, v[164:165]
	s_add_u32 vcc_lo, s78, 0x20000
	ds_read_b128 v[202:205], v201 offset:16384
	ds_read_b128 v[206:209], v201 offset:17408
	ds_read_b128 v[210:213], v201 offset:18432
	ds_read_b128 v[214:217], v201 offset:19456
	ds_read_b128 v[218:221], v201 offset:20480
	ds_read_b128 v[222:225], v201 offset:21504
	ds_read_b128 v[226:229], v201 offset:22528
	ds_read_b128 v[230:233], v201 offset:23552
	global_load_lds_dwordx4 v[10:11], off
	v_lshl_add_u64 v[12:13], s[78:79], 0, v[168:169]
	s_mov_b32 m0, s69
	s_addc_u32 vcc_hi, s79, 0
	global_load_lds_dwordx4 v[12:13], off
	v_lshl_add_u64 v[14:15], vcc, 0, v[164:165]
	s_mov_b32 m0, s77
	v_lshl_add_u64 v[16:17], s[82:83], 0, v[166:167]
	global_load_lds_dwordx4 v[14:15], off
	v_lshl_add_u64 v[14:15], vcc, 0, v[168:169]
	s_mov_b32 m0, s84
	s_nop 0
	global_load_lds_dwordx4 v[14:15], off
	v_lshl_add_u64 v[14:15], s[82:83], 0, v[162:163]
	s_mov_b32 m0, s33
	s_nop 0
	global_load_lds_dwordx4 v[14:15], off
	s_mov_b32 m0, s85
	s_nop 0
	global_load_lds_dwordx4 v[16:17], off
	s_waitcnt vmcnt(8)
	s_waitcnt lgkmcnt(0)
	s_setprio 1
	s_barrier
	v_mfma_f32_16x16x128_f8f6f4 v[94:97], v[2:9], v[202:209], v[94:97]
	v_mfma_f32_16x16x128_f8f6f4 v[90:93], v[18:25], v[202:209], v[90:93]
	v_mfma_f32_16x16x128_f8f6f4 v[58:61], v[182:189], v[202:209], v[58:61]
	v_mfma_f32_16x16x128_f8f6f4 v[62:65], v[26:33], v[202:209], v[62:65]
	s_setprio 0
	s_setprio 1
	v_mfma_f32_16x16x128_f8f6f4 v[54:57], v[26:33], v[210:217], v[54:57]
	v_mfma_f32_16x16x128_f8f6f4 v[50:53], v[182:189], v[210:217], v[50:53]
	v_mfma_f32_16x16x128_f8f6f4 v[82:85], v[18:25], v[210:217], v[82:85]
	v_mfma_f32_16x16x128_f8f6f4 v[86:89], v[2:9], v[210:217], v[86:89]
	s_setprio 0
	s_setprio 1
	v_mfma_f32_16x16x128_f8f6f4 v[78:81], v[2:9], v[218:225], v[78:81]
	v_mfma_f32_16x16x128_f8f6f4 v[74:77], v[18:25], v[218:225], v[74:77]
	v_mfma_f32_16x16x128_f8f6f4 v[42:45], v[182:189], v[218:225], v[42:45]
	v_mfma_f32_16x16x128_f8f6f4 v[46:49], v[26:33], v[218:225], v[46:49]
	s_setprio 0
	s_setprio 1
	v_mfma_f32_16x16x128_f8f6f4 v[38:41], v[26:33], v[226:233], v[38:41]
	v_mfma_f32_16x16x128_f8f6f4 v[34:37], v[182:189], v[226:233], v[34:37]
	v_mfma_f32_16x16x128_f8f6f4 v[66:69], v[18:25], v[226:233], v[66:69]
	v_mfma_f32_16x16x128_f8f6f4 v[70:73], v[2:9], v[226:233], v[70:73]
	s_barrier
	s_setprio 0
	ds_read_b128 v[18:21], v200 offset:32768
	ds_read_b128 v[22:25], v200 offset:33792
	ds_read_b128 v[26:29], v200 offset:34816
	ds_read_b128 v[30:33], v200 offset:35840
	ds_read_b128 v[2:5], v200 offset:49152
	ds_read_b128 v[6:9], v200 offset:50176
	ds_read_b128 v[182:185], v200 offset:51200
	ds_read_b128 v[186:189], v200 offset:52224
	s_add_u32 s82, s82, 0x20000
	s_addc_u32 s83, s83, 0
	s_mov_b32 m0, s86
	v_lshl_add_u64 v[234:235], s[82:83], 0, v[162:163]
	ds_read_b128 v[202:205], v201 offset:32768
	ds_read_b128 v[206:209], v201 offset:33792
	ds_read_b128 v[210:213], v201 offset:34816
	ds_read_b128 v[214:217], v201 offset:35840
	ds_read_b128 v[218:221], v201 offset:36864
	ds_read_b128 v[222:225], v201 offset:37888
	ds_read_b128 v[226:229], v201 offset:38912
	ds_read_b128 v[230:233], v201 offset:39936
	global_load_lds_dwordx4 v[234:235], off
	v_lshl_add_u64 v[234:235], s[82:83], 0, v[166:167]
	s_mov_b32 m0, s87
	s_nop 0
	global_load_lds_dwordx4 v[234:235], off
	s_waitcnt vmcnt(8)
	s_waitcnt lgkmcnt(0)
	s_setprio 1
	s_barrier
	v_mfma_f32_16x16x128_f8f6f4 v[158:161], v[18:25], v[202:209], v[158:161]
	v_mfma_f32_16x16x128_f8f6f4 v[154:157], v[26:33], v[202:209], v[154:157]
	v_mfma_f32_16x16x128_f8f6f4 v[122:125], v[182:189], v[202:209], v[122:125]
	v_mfma_f32_16x16x128_f8f6f4 v[126:129], v[2:9], v[202:209], v[126:129]
	s_setprio 0
	s_setprio 1
	v_mfma_f32_16x16x128_f8f6f4 v[118:121], v[2:9], v[210:217], v[118:121]
	v_mfma_f32_16x16x128_f8f6f4 v[114:117], v[182:189], v[210:217], v[114:117]
	v_mfma_f32_16x16x128_f8f6f4 v[146:149], v[26:33], v[210:217], v[146:149]
	v_mfma_f32_16x16x128_f8f6f4 v[150:153], v[18:25], v[210:217], v[150:153]
	s_setprio 0
	s_setprio 1
	v_mfma_f32_16x16x128_f8f6f4 v[142:145], v[18:25], v[218:225], v[142:145]
	v_mfma_f32_16x16x128_f8f6f4 v[138:141], v[26:33], v[218:225], v[138:141]
	v_mfma_f32_16x16x128_f8f6f4 v[106:109], v[182:189], v[218:225], v[106:109]
	v_mfma_f32_16x16x128_f8f6f4 v[110:113], v[2:9], v[218:225], v[110:113]
	s_setprio 0
	s_setprio 1
	v_mfma_f32_16x16x128_f8f6f4 v[102:105], v[2:9], v[226:233], v[102:105]
	v_mfma_f32_16x16x128_f8f6f4 v[98:101], v[182:189], v[226:233], v[98:101]
	v_mfma_f32_16x16x128_f8f6f4 v[130:133], v[26:33], v[226:233], v[130:133]
	v_mfma_f32_16x16x128_f8f6f4 v[134:137], v[18:25], v[226:233], v[134:137]
	s_barrier
	s_setprio 0
	s_mov_b32 m0, s89
	v_lshl_add_u64 v[10:11], v[10:11], 0, s[42:43]
	s_add_u32 s78, s78, 0x20080
	ds_read_b128 v[202:205], v201 offset:49152
	ds_read_b128 v[206:209], v201 offset:50176
	ds_read_b128 v[210:213], v201 offset:51200
	ds_read_b128 v[214:217], v201 offset:52224
	ds_read_b128 v[218:221], v201 offset:53248
	ds_read_b128 v[222:225], v201 offset:54272
	ds_read_b128 v[226:229], v201 offset:55296
	ds_read_b128 v[230:233], v201 offset:56320
	global_load_lds_dwordx4 v[10:11], off
	v_lshl_add_u64 v[10:11], v[12:13], 0, s[42:43]
	s_mov_b32 m0, s90
	s_addc_u32 s79, s79, 0
	global_load_lds_dwordx4 v[10:11], off
	v_lshl_add_u64 v[10:11], s[78:79], 0, v[164:165]
	s_mov_b32 m0, s93
	s_nop 0
	global_load_lds_dwordx4 v[10:11], off
	v_lshl_add_u64 v[10:11], s[78:79], 0, v[168:169]
	s_mov_b32 m0, s95
	s_nop 0
	global_load_lds_dwordx4 v[10:11], off
	v_lshl_add_u64 v[10:11], v[14:15], 0, s[42:43]
	s_mov_b32 m0, s91
	s_nop 0
	global_load_lds_dwordx4 v[10:11], off
	v_lshl_add_u64 v[10:11], v[16:17], 0, s[42:43]
	s_mov_b32 m0, s92
	s_nop 0
	global_load_lds_dwordx4 v[10:11], off
	s_waitcnt vmcnt(8)
	s_waitcnt lgkmcnt(0)
	s_setprio 1
	s_barrier
	v_mfma_f32_16x16x128_f8f6f4 v[94:97], v[18:25], v[202:209], v[94:97]
	v_mfma_f32_16x16x128_f8f6f4 v[90:93], v[26:33], v[202:209], v[90:93]
	v_mfma_f32_16x16x128_f8f6f4 v[58:61], v[182:189], v[202:209], v[58:61]
	v_mfma_f32_16x16x128_f8f6f4 v[62:65], v[2:9], v[202:209], v[62:65]
	s_setprio 0
	s_setprio 1
	v_mfma_f32_16x16x128_f8f6f4 v[54:57], v[2:9], v[210:217], v[54:57]
	v_mfma_f32_16x16x128_f8f6f4 v[50:53], v[182:189], v[210:217], v[50:53]
	v_mfma_f32_16x16x128_f8f6f4 v[82:85], v[26:33], v[210:217], v[82:85]
	v_mfma_f32_16x16x128_f8f6f4 v[86:89], v[18:25], v[210:217], v[86:89]
	s_setprio 0
	s_setprio 1
	v_mfma_f32_16x16x128_f8f6f4 v[78:81], v[18:25], v[218:225], v[78:81]
	v_mfma_f32_16x16x128_f8f6f4 v[74:77], v[26:33], v[218:225], v[74:77]
	v_mfma_f32_16x16x128_f8f6f4 v[42:45], v[182:189], v[218:225], v[42:45]
	v_mfma_f32_16x16x128_f8f6f4 v[46:49], v[2:9], v[218:225], v[46:49]
	s_setprio 0
	s_setprio 1
	v_mfma_f32_16x16x128_f8f6f4 v[38:41], v[2:9], v[226:233], v[38:41]
	v_mfma_f32_16x16x128_f8f6f4 v[34:37], v[182:189], v[226:233], v[34:37]
	v_mfma_f32_16x16x128_f8f6f4 v[66:69], v[26:33], v[226:233], v[66:69]
	v_mfma_f32_16x16x128_f8f6f4 v[70:73], v[18:25], v[226:233], v[70:73]
	s_barrier
	s_setprio 0
	s_add_i32 s62, s62, 2
	s_add_u32 s80, s80, 0x100
	s_addc_u32 s81, s81, 0
	s_add_u32 s8, s8, 0x100
	s_addc_u32 s9, s9, 0
	s_cmp_gt_u32 s62, 5
	s_cbranch_scc0 .LBB0_601
	s_and_b64 vcc, exec, s[44:45]
	s_cbranch_vccz .LBB0_604
	s_barrier

.LBB0_616:
	ds_read_b128 v[18:21], v188
	ds_read_b128 v[22:25], v188 offset:1024
	ds_read_b128 v[26:29], v188 offset:2048
	ds_read_b128 v[30:33], v188 offset:3072
	ds_read_b128 v[2:5], v188 offset:16384
	ds_read_b128 v[6:9], v188 offset:17408
	ds_read_b128 v[10:13], v188 offset:18432
	ds_read_b128 v[14:17], v188 offset:19456
	s_ashr_i32 s55, s54, 31
	s_lshl_b64 s[62:63], s[54:55], 17
	s_add_u32 s72, s36, s62
	s_addc_u32 s73, s37, s63
	s_and_b64 s[62:63], s[2:3], exec
	s_cselect_b32 s85, s73, s79
	s_cselect_b32 s84, s72, s78
	s_ashr_i32 s53, s52, 31
	s_lshl_b64 s[62:63], s[52:53], 17
	s_add_u32 s74, s94, s62
	v_readlane_b32 s5, v254, 8
	s_addc_u32 s75, s5, s63
	s_and_b64 s[62:63], s[2:3], exec
	s_cselect_b32 s83, s75, s81
	s_cselect_b32 s82, s74, s80
	s_add_u32 s62, s78, 0x10080
	s_addc_u32 s63, s79, 0
	s_mov_b32 m0, s96
	v_lshl_add_u64 v[174:175], s[62:63], 0, v[166:167]
	ds_read_b128 v[196:199], v189
	ds_read_b128 v[200:203], v189 offset:1024
	ds_read_b128 v[204:207], v189 offset:2048
	ds_read_b128 v[208:211], v189 offset:3072
	ds_read_b128 v[212:215], v189 offset:4096
	ds_read_b128 v[216:219], v189 offset:5120
	ds_read_b128 v[220:223], v189 offset:6144
	ds_read_b128 v[224:227], v189 offset:7168
	global_load_lds_dwordx4 v[174:175], off
	v_lshl_add_u64 v[174:175], s[62:63], 0, v[168:169]
	s_mov_b32 m0, s97
	s_nop 0
	global_load_lds_dwordx4 v[174:175], off
	s_waitcnt vmcnt(8)
	s_waitcnt lgkmcnt(0)
	s_setprio 1
	s_barrier
	v_mfma_f32_16x16x128_f8f6f4 v[158:161], v[18:25], v[196:203], 0
	v_mfma_f32_16x16x128_f8f6f4 v[154:157], v[26:33], v[196:203], 0
	v_mfma_f32_16x16x128_f8f6f4 v[122:125], v[10:17], v[196:203], 0
	v_mfma_f32_16x16x128_f8f6f4 v[126:129], v[2:9], v[196:203], 0
	s_setprio 0
	s_setprio 1
	v_mfma_f32_16x16x128_f8f6f4 v[118:121], v[2:9], v[204:211], 0
	v_mfma_f32_16x16x128_f8f6f4 v[114:117], v[10:17], v[204:211], 0
	v_mfma_f32_16x16x128_f8f6f4 v[146:149], v[26:33], v[204:211], 0
	v_mfma_f32_16x16x128_f8f6f4 v[150:153], v[18:25], v[204:211], 0
	s_setprio 0
	s_setprio 1
	v_mfma_f32_16x16x128_f8f6f4 v[142:145], v[18:25], v[212:219], 0
	v_mfma_f32_16x16x128_f8f6f4 v[138:141], v[26:33], v[212:219], 0
	v_mfma_f32_16x16x128_f8f6f4 v[106:109], v[10:17], v[212:219], 0
	v_mfma_f32_16x16x128_f8f6f4 v[110:113], v[2:9], v[212:219], 0
	s_setprio 0
	s_setprio 1
	v_mfma_f32_16x16x128_f8f6f4 v[102:105], v[2:9], v[220:227], 0
	v_mfma_f32_16x16x128_f8f6f4 v[98:101], v[10:17], v[220:227], 0
	v_mfma_f32_16x16x128_f8f6f4 v[130:133], v[26:33], v[220:227], 0
	v_mfma_f32_16x16x128_f8f6f4 v[134:137], v[18:25], v[220:227], 0
	s_barrier
	s_setprio 0
	v_lshl_add_u64 v[174:175], s[80:81], 0, v[162:163]
	s_mov_b32 m0, s61
	v_lshl_add_u64 v[176:177], v[174:175], 0, s[46:47]
	ds_read_b128 v[196:199], v189 offset:16384
	ds_read_b128 v[200:203], v189 offset:17408
	ds_read_b128 v[204:207], v189 offset:18432
	ds_read_b128 v[208:211], v189 offset:19456
	ds_read_b128 v[212:215], v189 offset:20480
	ds_read_b128 v[216:219], v189 offset:21504
	ds_read_b128 v[220:223], v189 offset:22528
	ds_read_b128 v[224:227], v189 offset:23552
	global_load_lds_dwordx4 v[176:177], off
	v_lshl_add_u64 v[176:177], s[80:81], 0, v[164:165]
	s_add_u32 s62, s80, 0x10100
	v_lshl_add_u64 v[182:183], v[176:177], 0, s[46:47]
	s_mov_b32 m0, s68
	s_addc_u32 s63, s81, 0
	global_load_lds_dwordx4 v[182:183], off
	v_lshl_add_u64 v[182:183], s[62:63], 0, v[162:163]
	s_mov_b32 m0, s69
	s_nop 0
	global_load_lds_dwordx4 v[182:183], off
	v_lshl_add_u64 v[182:183], s[62:63], 0, v[164:165]
	s_mov_b32 m0, s77
	s_nop 0
	global_load_lds_dwordx4 v[182:183], off
	v_lshl_add_u64 v[182:183], s[78:79], 0, v[166:167]
	v_lshl_add_u64 v[184:185], v[182:183], 0, s[46:47]
	s_mov_b32 m0, s51
	s_nop 0
	global_load_lds_dwordx4 v[184:185], off
	v_lshl_add_u64 v[184:185], s[78:79], 0, v[168:169]
	v_lshl_add_u64 v[228:229], v[184:185], 0, s[46:47]
	s_mov_b32 m0, s86
	s_nop 0
	global_load_lds_dwordx4 v[228:229], off
	s_waitcnt vmcnt(8)
	s_waitcnt lgkmcnt(0)
	s_setprio 1
	s_barrier
	v_mfma_f32_16x16x128_f8f6f4 v[94:97], v[18:25], v[196:203], 0
	v_mfma_f32_16x16x128_f8f6f4 v[90:93], v[26:33], v[196:203], 0
	v_mfma_f32_16x16x128_f8f6f4 v[58:61], v[10:17], v[196:203], 0
	v_mfma_f32_16x16x128_f8f6f4 v[62:65], v[2:9], v[196:203], 0
	s_setprio 0
	s_setprio 1
	v_mfma_f32_16x16x128_f8f6f4 v[54:57], v[2:9], v[204:211], 0
	v_mfma_f32_16x16x128_f8f6f4 v[50:53], v[10:17], v[204:211], 0
	v_mfma_f32_16x16x128_f8f6f4 v[82:85], v[26:33], v[204:211], 0
	v_mfma_f32_16x16x128_f8f6f4 v[86:89], v[18:25], v[204:211], 0
	s_setprio 0
	s_setprio 1
	v_mfma_f32_16x16x128_f8f6f4 v[78:81], v[18:25], v[212:219], 0
	v_mfma_f32_16x16x128_f8f6f4 v[74:77], v[26:33], v[212:219], 0
	v_mfma_f32_16x16x128_f8f6f4 v[42:45], v[10:17], v[212:219], 0
	v_mfma_f32_16x16x128_f8f6f4 v[46:49], v[2:9], v[212:219], 0
	s_setprio 0
	s_setprio 1
	v_mfma_f32_16x16x128_f8f6f4 v[38:41], v[2:9], v[220:227], 0
	v_mfma_f32_16x16x128_f8f6f4 v[34:37], v[10:17], v[220:227], 0
	v_mfma_f32_16x16x128_f8f6f4 v[66:69], v[26:33], v[220:227], 0
	v_mfma_f32_16x16x128_f8f6f4 v[70:73], v[18:25], v[220:227], 0
	s_barrier
	s_setprio 0
	ds_read_b128 v[2:5], v188 offset:32768
	ds_read_b128 v[6:9], v188 offset:33792
	ds_read_b128 v[10:13], v188 offset:34816
	ds_read_b128 v[14:17], v188 offset:35840
	ds_read_b128 v[18:21], v188 offset:49152
	ds_read_b128 v[22:25], v188 offset:50176
	ds_read_b128 v[26:29], v188 offset:51200
	ds_read_b128 v[30:33], v188 offset:52224
	s_add_u32 s62, s78, 0x10100
	s_addc_u32 s63, s79, 0
	s_mov_b32 m0, s87
	v_lshl_add_u64 v[228:229], s[62:63], 0, v[166:167]
	ds_read_b128 v[196:199], v189 offset:32768
	ds_read_b128 v[200:203], v189 offset:33792
	ds_read_b128 v[204:207], v189 offset:34816
	ds_read_b128 v[208:211], v189 offset:35840
	ds_read_b128 v[212:215], v189 offset:36864
	ds_read_b128 v[216:219], v189 offset:37888
	ds_read_b128 v[220:223], v189 offset:38912
	ds_read_b128 v[224:227], v189 offset:39936
	global_load_lds_dwordx4 v[228:229], off
	v_lshl_add_u64 v[228:229], s[62:63], 0, v[168:169]
	s_mov_b32 m0, s88
	s_nop 0
	global_load_lds_dwordx4 v[228:229], off
	s_waitcnt vmcnt(8)
	s_waitcnt lgkmcnt(0)
	s_setprio 1
	s_barrier
	v_mfma_f32_16x16x128_f8f6f4 v[158:161], v[2:9], v[196:203], v[158:161]
	v_mfma_f32_16x16x128_f8f6f4 v[154:157], v[10:17], v[196:203], v[154:157]
	v_mfma_f32_16x16x128_f8f6f4 v[122:125], v[26:33], v[196:203], v[122:125]
	v_mfma_f32_16x16x128_f8f6f4 v[126:129], v[18:25], v[196:203], v[126:129]
	s_setprio 0
	s_setprio 1
	v_mfma_f32_16x16x128_f8f6f4 v[118:121], v[18:25], v[204:211], v[118:121]
	v_mfma_f32_16x16x128_f8f6f4 v[114:117], v[26:33], v[204:211], v[114:117]
	v_mfma_f32_16x16x128_f8f6f4 v[146:149], v[10:17], v[204:211], v[146:149]
	v_mfma_f32_16x16x128_f8f6f4 v[150:153], v[2:9], v[204:211], v[150:153]
	s_setprio 0
	s_setprio 1
	v_mfma_f32_16x16x128_f8f6f4 v[142:145], v[2:9], v[212:219], v[142:145]
	v_mfma_f32_16x16x128_f8f6f4 v[138:141], v[10:17], v[212:219], v[138:141]
	v_mfma_f32_16x16x128_f8f6f4 v[106:109], v[26:33], v[212:219], v[106:109]
	v_mfma_f32_16x16x128_f8f6f4 v[110:113], v[18:25], v[212:219], v[110:113]
	s_setprio 0
	s_setprio 1
	v_mfma_f32_16x16x128_f8f6f4 v[102:105], v[18:25], v[220:227], v[102:105]
	v_mfma_f32_16x16x128_f8f6f4 v[98:101], v[26:33], v[220:227], v[98:101]
	v_mfma_f32_16x16x128_f8f6f4 v[130:133], v[10:17], v[220:227], v[130:133]
	v_mfma_f32_16x16x128_f8f6f4 v[134:137], v[2:9], v[220:227], v[134:137]
	s_barrier
	s_setprio 0
	s_mov_b32 m0, s89
	v_lshl_add_u64 v[174:175], v[174:175], 0, s[48:49]
	s_add_u32 s62, s80, 0x10180
	ds_read_b128 v[196:199], v189 offset:49152
	ds_read_b128 v[200:203], v189 offset:50176
	ds_read_b128 v[204:207], v189 offset:51200
	ds_read_b128 v[208:211], v189 offset:52224
	ds_read_b128 v[212:215], v189 offset:53248
	ds_read_b128 v[216:219], v189 offset:54272
	ds_read_b128 v[220:223], v189 offset:55296
	ds_read_b128 v[224:227], v189 offset:56320
	global_load_lds_dwordx4 v[174:175], off
	v_lshl_add_u64 v[174:175], v[176:177], 0, s[48:49]
	s_mov_b32 m0, s90
	s_addc_u32 s63, s81, 0
	global_load_lds_dwordx4 v[174:175], off
	v_lshl_add_u64 v[174:175], s[62:63], 0, v[162:163]
	s_mov_b32 m0, s93
	s_nop 0
	global_load_lds_dwordx4 v[174:175], off
	v_lshl_add_u64 v[174:175], s[62:63], 0, v[164:165]
	s_mov_b32 m0, s95
	s_nop 0
	global_load_lds_dwordx4 v[174:175], off
	v_lshl_add_u64 v[174:175], v[182:183], 0, s[48:49]
	s_mov_b32 m0, s91
	s_nop 0
	global_load_lds_dwordx4 v[174:175], off
	v_lshl_add_u64 v[174:175], v[184:185], 0, s[48:49]
	s_mov_b32 m0, s92
	s_nop 0
	global_load_lds_dwordx4 v[174:175], off
	s_waitcnt vmcnt(8)
	s_waitcnt lgkmcnt(0)
	s_setprio 1
	s_barrier
	v_mfma_f32_16x16x128_f8f6f4 v[94:97], v[2:9], v[196:203], v[94:97]
	v_mfma_f32_16x16x128_f8f6f4 v[90:93], v[10:17], v[196:203], v[90:93]
	v_mfma_f32_16x16x128_f8f6f4 v[58:61], v[26:33], v[196:203], v[58:61]
	v_mfma_f32_16x16x128_f8f6f4 v[62:65], v[18:25], v[196:203], v[62:65]
	s_setprio 0
	s_setprio 1
	v_mfma_f32_16x16x128_f8f6f4 v[54:57], v[18:25], v[204:211], v[54:57]
	v_mfma_f32_16x16x128_f8f6f4 v[50:53], v[26:33], v[204:211], v[50:53]
	v_mfma_f32_16x16x128_f8f6f4 v[82:85], v[10:17], v[204:211], v[82:85]
	v_mfma_f32_16x16x128_f8f6f4 v[86:89], v[2:9], v[204:211], v[86:89]
	s_setprio 0
	s_setprio 1
	v_mfma_f32_16x16x128_f8f6f4 v[78:81], v[2:9], v[212:219], v[78:81]
	v_mfma_f32_16x16x128_f8f6f4 v[74:77], v[10:17], v[212:219], v[74:77]
	v_mfma_f32_16x16x128_f8f6f4 v[42:45], v[26:33], v[212:219], v[42:45]
	v_mfma_f32_16x16x128_f8f6f4 v[46:49], v[18:25], v[212:219], v[46:49]
	s_setprio 0
	s_setprio 1
	v_mfma_f32_16x16x128_f8f6f4 v[38:41], v[18:25], v[220:227], v[38:41]
	v_mfma_f32_16x16x128_f8f6f4 v[34:37], v[26:33], v[220:227], v[34:37]
	v_mfma_f32_16x16x128_f8f6f4 v[66:69], v[10:17], v[220:227], v[66:69]
	v_mfma_f32_16x16x128_f8f6f4 v[70:73], v[2:9], v[220:227], v[70:73]
	s_barrier
	s_setprio 0
	ds_read_b128 v[2:5], v188
	ds_read_b128 v[6:9], v188 offset:1024
	ds_read_b128 v[10:13], v188 offset:2048
	ds_read_b128 v[14:17], v188 offset:3072
	ds_read_b128 v[18:21], v188 offset:16384
	ds_read_b128 v[22:25], v188 offset:17408
	ds_read_b128 v[26:29], v188 offset:18432
	ds_read_b128 v[30:33], v188 offset:19456
	s_add_u32 s62, s78, 0x10180
	s_addc_u32 s63, s79, 0
	s_mov_b32 m0, s96
	v_lshl_add_u64 v[174:175], s[62:63], 0, v[166:167]
	ds_read_b128 v[196:199], v189
	ds_read_b128 v[200:203], v189 offset:1024
	ds_read_b128 v[204:207], v189 offset:2048
	ds_read_b128 v[208:211], v189 offset:3072
	ds_read_b128 v[212:215], v189 offset:4096
	ds_read_b128 v[216:219], v189 offset:5120
	ds_read_b128 v[220:223], v189 offset:6144
	ds_read_b128 v[224:227], v189 offset:7168
	global_load_lds_dwordx4 v[174:175], off
	v_lshl_add_u64 v[174:175], s[62:63], 0, v[168:169]
	s_mov_b32 m0, s97
	s_nop 0
	global_load_lds_dwordx4 v[174:175], off
	s_waitcnt vmcnt(8)
	s_waitcnt lgkmcnt(0)
	s_setprio 1
	s_barrier
	v_mfma_f32_16x16x128_f8f6f4 v[158:161], v[2:9], v[196:203], v[158:161]
	v_mfma_f32_16x16x128_f8f6f4 v[154:157], v[10:17], v[196:203], v[154:157]
	v_mfma_f32_16x16x128_f8f6f4 v[122:125], v[26:33], v[196:203], v[122:125]
	v_mfma_f32_16x16x128_f8f6f4 v[126:129], v[18:25], v[196:203], v[126:129]
	s_setprio 0
	s_setprio 1
	v_mfma_f32_16x16x128_f8f6f4 v[118:121], v[18:25], v[204:211], v[118:121]
	v_mfma_f32_16x16x128_f8f6f4 v[114:117], v[26:33], v[204:211], v[114:117]
	v_mfma_f32_16x16x128_f8f6f4 v[146:149], v[10:17], v[204:211], v[146:149]
	v_mfma_f32_16x16x128_f8f6f4 v[150:153], v[2:9], v[204:211], v[150:153]
	s_setprio 0
	s_setprio 1
	v_mfma_f32_16x16x128_f8f6f4 v[142:145], v[2:9], v[212:219], v[142:145]
	v_mfma_f32_16x16x128_f8f6f4 v[138:141], v[10:17], v[212:219], v[138:141]
	v_mfma_f32_16x16x128_f8f6f4 v[106:109], v[26:33], v[212:219], v[106:109]
	v_mfma_f32_16x16x128_f8f6f4 v[110:113], v[18:25], v[212:219], v[110:113]
	s_setprio 0
	s_setprio 1
	v_mfma_f32_16x16x128_f8f6f4 v[102:105], v[18:25], v[220:227], v[102:105]
	v_mfma_f32_16x16x128_f8f6f4 v[98:101], v[26:33], v[220:227], v[98:101]
	v_mfma_f32_16x16x128_f8f6f4 v[130:133], v[10:17], v[220:227], v[130:133]
	v_mfma_f32_16x16x128_f8f6f4 v[134:137], v[2:9], v[220:227], v[134:137]
	s_barrier
	s_setprio 0
	s_mov_b32 m0, s61
	v_lshl_add_u64 v[174:175], s[82:83], 0, v[162:163]
	s_add_u32 s62, s82, 0x10000
	ds_read_b128 v[196:199], v189 offset:16384
	ds_read_b128 v[200:203], v189 offset:17408
	ds_read_b128 v[204:207], v189 offset:18432
	ds_read_b128 v[208:211], v189 offset:19456
	ds_read_b128 v[212:215], v189 offset:20480
	ds_read_b128 v[216:219], v189 offset:21504
	ds_read_b128 v[220:223], v189 offset:22528
	ds_read_b128 v[224:227], v189 offset:23552
	global_load_lds_dwordx4 v[174:175], off
	v_lshl_add_u64 v[176:177], s[82:83], 0, v[164:165]
	s_mov_b32 m0, s68
	s_addc_u32 s63, s83, 0
	global_load_lds_dwordx4 v[176:177], off
	v_lshl_add_u64 v[182:183], s[62:63], 0, v[162:163]
	s_mov_b32 m0, s69
	v_lshl_add_u64 v[184:185], s[84:85], 0, v[168:169]
	global_load_lds_dwordx4 v[182:183], off
	v_lshl_add_u64 v[182:183], s[62:63], 0, v[164:165]
	s_mov_b32 m0, s77
	s_nop 0
	global_load_lds_dwordx4 v[182:183], off
	v_lshl_add_u64 v[182:183], s[84:85], 0, v[166:167]
	s_mov_b32 m0, s51
	s_nop 0
	global_load_lds_dwordx4 v[182:183], off
	s_mov_b32 m0, s86
	s_nop 0
	global_load_lds_dwordx4 v[184:185], off
	s_waitcnt vmcnt(8)
	s_waitcnt lgkmcnt(0)
	s_setprio 1
	s_barrier
	v_mfma_f32_16x16x128_f8f6f4 v[94:97], v[2:9], v[196:203], v[94:97]
	v_mfma_f32_16x16x128_f8f6f4 v[90:93], v[10:17], v[196:203], v[90:93]
	v_mfma_f32_16x16x128_f8f6f4 v[58:61], v[26:33], v[196:203], v[58:61]
	v_mfma_f32_16x16x128_f8f6f4 v[62:65], v[18:25], v[196:203], v[62:65]
	s_setprio 0
	s_setprio 1
	v_mfma_f32_16x16x128_f8f6f4 v[54:57], v[18:25], v[204:211], v[54:57]
	v_mfma_f32_16x16x128_f8f6f4 v[50:53], v[26:33], v[204:211], v[50:53]
	v_mfma_f32_16x16x128_f8f6f4 v[82:85], v[10:17], v[204:211], v[82:85]
	v_mfma_f32_16x16x128_f8f6f4 v[86:89], v[2:9], v[204:211], v[86:89]
	s_setprio 0
	s_setprio 1
	v_mfma_f32_16x16x128_f8f6f4 v[78:81], v[2:9], v[212:219], v[78:81]
	v_mfma_f32_16x16x128_f8f6f4 v[74:77], v[10:17], v[212:219], v[74:77]
	v_mfma_f32_16x16x128_f8f6f4 v[42:45], v[26:33], v[212:219], v[42:45]
	v_mfma_f32_16x16x128_f8f6f4 v[46:49], v[18:25], v[212:219], v[46:49]
	s_setprio 0
	s_setprio 1
	v_mfma_f32_16x16x128_f8f6f4 v[38:41], v[18:25], v[220:227], v[38:41]
	v_mfma_f32_16x16x128_f8f6f4 v[34:37], v[26:33], v[220:227], v[34:37]
	v_mfma_f32_16x16x128_f8f6f4 v[66:69], v[10:17], v[220:227], v[66:69]
	v_mfma_f32_16x16x128_f8f6f4 v[70:73], v[2:9], v[220:227], v[70:73]
	s_barrier
	s_setprio 0
	ds_read_b128 v[2:5], v188 offset:32768
	ds_read_b128 v[6:9], v188 offset:33792
	ds_read_b128 v[10:13], v188 offset:34816
	ds_read_b128 v[14:17], v188 offset:35840
	ds_read_b128 v[18:21], v188 offset:49152
	ds_read_b128 v[22:25], v188 offset:50176
	ds_read_b128 v[26:29], v188 offset:51200
	ds_read_b128 v[30:33], v188 offset:52224
	s_add_u32 s62, s84, 0x10000
	s_addc_u32 s63, s85, 0
	s_mov_b32 m0, s87
	v_lshl_add_u64 v[228:229], s[62:63], 0, v[166:167]
	ds_read_b128 v[196:199], v189 offset:32768
	ds_read_b128 v[200:203], v189 offset:33792
	ds_read_b128 v[204:207], v189 offset:34816
	ds_read_b128 v[208:211], v189 offset:35840
	ds_read_b128 v[212:215], v189 offset:36864
	ds_read_b128 v[216:219], v189 offset:37888
	ds_read_b128 v[220:223], v189 offset:38912
	ds_read_b128 v[224:227], v189 offset:39936
	global_load_lds_dwordx4 v[228:229], off
	v_lshl_add_u64 v[228:229], s[62:63], 0, v[168:169]
	s_mov_b32 m0, s88
	s_nop 0
	global_load_lds_dwordx4 v[228:229], off
	s_waitcnt vmcnt(8)
	s_waitcnt lgkmcnt(0)
	s_setprio 1
	s_barrier
	v_mfma_f32_16x16x128_f8f6f4 v[158:161], v[2:9], v[196:203], v[158:161]
	v_mfma_f32_16x16x128_f8f6f4 v[154:157], v[10:17], v[196:203], v[154:157]
	v_mfma_f32_16x16x128_f8f6f4 v[122:125], v[26:33], v[196:203], v[122:125]
	v_mfma_f32_16x16x128_f8f6f4 v[126:129], v[18:25], v[196:203], v[126:129]
	s_setprio 0
	s_setprio 1
	v_mfma_f32_16x16x128_f8f6f4 v[118:121], v[18:25], v[204:211], v[118:121]
	v_mfma_f32_16x16x128_f8f6f4 v[114:117], v[26:33], v[204:211], v[114:117]
	v_mfma_f32_16x16x128_f8f6f4 v[146:149], v[10:17], v[204:211], v[146:149]
	v_mfma_f32_16x16x128_f8f6f4 v[150:153], v[2:9], v[204:211], v[150:153]
	s_setprio 0
	s_setprio 1
	v_mfma_f32_16x16x128_f8f6f4 v[142:145], v[2:9], v[212:219], v[142:145]
	v_mfma_f32_16x16x128_f8f6f4 v[138:141], v[10:17], v[212:219], v[138:141]
	v_mfma_f32_16x16x128_f8f6f4 v[106:109], v[26:33], v[212:219], v[106:109]
	v_mfma_f32_16x16x128_f8f6f4 v[110:113], v[18:25], v[212:219], v[110:113]
	s_setprio 0
	s_setprio 1
	v_mfma_f32_16x16x128_f8f6f4 v[102:105], v[18:25], v[220:227], v[102:105]
	v_mfma_f32_16x16x128_f8f6f4 v[98:101], v[26:33], v[220:227], v[98:101]
	v_mfma_f32_16x16x128_f8f6f4 v[130:133], v[10:17], v[220:227], v[130:133]
	v_mfma_f32_16x16x128_f8f6f4 v[134:137], v[2:9], v[220:227], v[134:137]
	s_barrier
	s_setprio 0
	s_mov_b32 m0, s89
	v_lshl_add_u64 v[174:175], v[174:175], 0, s[40:41]
	s_add_u32 s62, s82, 0x10080
	ds_read_b128 v[196:199], v189 offset:49152
	ds_read_b128 v[200:203], v189 offset:50176
	ds_read_b128 v[204:207], v189 offset:51200
	ds_read_b128 v[208:211], v189 offset:52224
	ds_read_b128 v[212:215], v189 offset:53248
	ds_read_b128 v[216:219], v189 offset:54272
	ds_read_b128 v[220:223], v189 offset:55296
	ds_read_b128 v[224:227], v189 offset:56320
	global_load_lds_dwordx4 v[174:175], off
	v_lshl_add_u64 v[174:175], v[176:177], 0, s[40:41]
	s_mov_b32 m0, s90
	s_addc_u32 s63, s83, 0
	global_load_lds_dwordx4 v[174:175], off
	v_lshl_add_u64 v[174:175], s[62:63], 0, v[162:163]
	s_mov_b32 m0, s93
	s_nop 0
	global_load_lds_dwordx4 v[174:175], off
	v_lshl_add_u64 v[174:175], s[62:63], 0, v[164:165]
	s_mov_b32 m0, s95
	s_nop 0
	global_load_lds_dwordx4 v[174:175], off
	v_lshl_add_u64 v[174:175], v[182:183], 0, s[40:41]
	s_mov_b32 m0, s91
	s_nop 0
	global_load_lds_dwordx4 v[174:175], off
	v_lshl_add_u64 v[174:175], v[184:185], 0, s[40:41]
	s_mov_b32 m0, s92
	s_nop 0
	global_load_lds_dwordx4 v[174:175], off
	s_waitcnt vmcnt(8)
	s_waitcnt lgkmcnt(0)
	s_setprio 1
	s_barrier
	v_mfma_f32_16x16x128_f8f6f4 v[94:97], v[2:9], v[196:203], v[94:97]
	v_mfma_f32_16x16x128_f8f6f4 v[90:93], v[10:17], v[196:203], v[90:93]
	v_mfma_f32_16x16x128_f8f6f4 v[58:61], v[26:33], v[196:203], v[58:61]
	v_mfma_f32_16x16x128_f8f6f4 v[62:65], v[18:25], v[196:203], v[62:65]
	s_setprio 0
	s_setprio 1
	v_mfma_f32_16x16x128_f8f6f4 v[54:57], v[18:25], v[204:211], v[54:57]
	v_mfma_f32_16x16x128_f8f6f4 v[50:53], v[26:33], v[204:211], v[50:53]
	v_mfma_f32_16x16x128_f8f6f4 v[82:85], v[10:17], v[204:211], v[82:85]
	v_mfma_f32_16x16x128_f8f6f4 v[86:89], v[2:9], v[204:211], v[86:89]
	s_setprio 0
	s_setprio 1
	v_mfma_f32_16x16x128_f8f6f4 v[78:81], v[2:9], v[212:219], v[78:81]
	v_mfma_f32_16x16x128_f8f6f4 v[74:77], v[10:17], v[212:219], v[74:77]
	v_mfma_f32_16x16x128_f8f6f4 v[42:45], v[26:33], v[212:219], v[42:45]
	v_mfma_f32_16x16x128_f8f6f4 v[46:49], v[18:25], v[212:219], v[46:49]
	s_setprio 0
	s_setprio 1
	v_mfma_f32_16x16x128_f8f6f4 v[38:41], v[18:25], v[220:227], v[38:41]
	v_mfma_f32_16x16x128_f8f6f4 v[34:37], v[26:33], v[220:227], v[34:37]
	v_mfma_f32_16x16x128_f8f6f4 v[66:69], v[10:17], v[220:227], v[66:69]
	v_mfma_f32_16x16x128_f8f6f4 v[70:73], v[2:9], v[220:227], v[70:73]
	s_barrier
	s_setprio 0
	s_andn2_b64 vcc, exec, s[42:43]
	s_cbranch_vccnz .LBB0_618
	s_barrier

.LBB0_630:
	s_ashr_i32 s54, s48, 1
	s_ashr_i32 s51, s50, 31
	s_ashr_i32 s55, s54, 31
	s_lshl_b64 s[52:53], s[50:51], 19
	s_lshl_b64 s[54:55], s[54:55], 9
	s_waitcnt vmcnt(0)
	ds_read_b128 v[18:21], v181
	ds_read_b128 v[22:25], v181 offset:1024
	ds_read_b128 v[26:29], v181 offset:2048
	ds_read_b128 v[30:33], v181 offset:3072
	ds_read_b128 v[2:5], v181 offset:16384
	ds_read_b128 v[6:9], v181 offset:17408
	ds_read_b128 v[10:13], v181 offset:18432
	ds_read_b128 v[14:17], v181 offset:19456
	s_add_u32 s5, s26, s52
	s_addc_u32 s33, s27, s53
	s_add_u32 s52, s5, s54
	s_addc_u32 s53, s33, s55
	s_and_b64 s[54:55], s[2:3], exec
	s_cselect_b32 s81, s53, s75
	s_cselect_b32 s80, s52, s74
	s_ashr_i32 s49, s48, 31
	s_lshl_b64 s[54:55], s[48:49], 17
	v_readlane_b32 s5, v254, 9
	s_add_u32 s54, s5, s54
	v_readlane_b32 s5, v254, 10
	s_addc_u32 s55, s5, s55
	s_and_b64 s[62:63], s[2:3], exec
	s_cselect_b32 s79, s55, s77
	s_cselect_b32 s78, s54, s76
	s_add_u32 s62, s74, 0x40080
	s_addc_u32 s63, s75, 0
	s_add_i32 s33, s8, 0xc000
	v_lshl_add_u64 v[174:175], s[62:63], 0, v[166:167]
	s_mov_b32 m0, s33
	s_add_i32 s5, s8, 0xe000
	ds_read_b128 v[190:193], v187
	ds_read_b128 v[194:197], v187 offset:1024
	ds_read_b128 v[198:201], v187 offset:2048
	ds_read_b128 v[202:205], v187 offset:3072
	ds_read_b128 v[206:209], v187 offset:4096
	ds_read_b128 v[210:213], v187 offset:5120
	ds_read_b128 v[214:217], v187 offset:6144
	ds_read_b128 v[218:221], v187 offset:7168
	global_load_lds_dwordx4 v[174:175], off
	v_lshl_add_u64 v[174:175], s[62:63], 0, v[168:169]
	s_mov_b32 m0, s5
	s_nop 0
	global_load_lds_dwordx4 v[174:175], off
	s_waitcnt vmcnt(8)
	s_waitcnt lgkmcnt(0)
	s_setprio 1
	s_barrier
	v_mfma_f32_16x16x128_f8f6f4 v[158:161], v[18:25], v[190:197], 0
	v_mfma_f32_16x16x128_f8f6f4 v[154:157], v[26:33], v[190:197], 0
	v_mfma_f32_16x16x128_f8f6f4 v[122:125], v[10:17], v[190:197], 0
	v_mfma_f32_16x16x128_f8f6f4 v[126:129], v[2:9], v[190:197], 0
	s_setprio 0
	s_setprio 1
	v_mfma_f32_16x16x128_f8f6f4 v[118:121], v[2:9], v[198:205], 0
	v_mfma_f32_16x16x128_f8f6f4 v[114:117], v[10:17], v[198:205], 0
	v_mfma_f32_16x16x128_f8f6f4 v[146:149], v[26:33], v[198:205], 0
	v_mfma_f32_16x16x128_f8f6f4 v[150:153], v[18:25], v[198:205], 0
	s_setprio 0
	s_setprio 1
	v_mfma_f32_16x16x128_f8f6f4 v[142:145], v[18:25], v[206:213], 0
	v_mfma_f32_16x16x128_f8f6f4 v[138:141], v[26:33], v[206:213], 0
	v_mfma_f32_16x16x128_f8f6f4 v[106:109], v[10:17], v[206:213], 0
	v_mfma_f32_16x16x128_f8f6f4 v[110:113], v[2:9], v[206:213], 0
	s_setprio 0
	s_setprio 1
	v_mfma_f32_16x16x128_f8f6f4 v[102:105], v[2:9], v[214:221], 0
	v_mfma_f32_16x16x128_f8f6f4 v[98:101], v[10:17], v[214:221], 0
	v_mfma_f32_16x16x128_f8f6f4 v[130:133], v[26:33], v[214:221], 0
	v_mfma_f32_16x16x128_f8f6f4 v[134:137], v[18:25], v[214:221], 0
	s_barrier
	s_setprio 0
	v_lshl_add_u64 v[174:175], s[76:77], 0, v[162:163]
	s_mov_b32 m0, s9
	v_lshl_add_u64 v[176:177], v[174:175], 0, s[44:45]
	ds_read_b128 v[190:193], v187 offset:16384
	ds_read_b128 v[194:197], v187 offset:17408
	ds_read_b128 v[198:201], v187 offset:18432
	ds_read_b128 v[202:205], v187 offset:19456
	ds_read_b128 v[206:209], v187 offset:20480
	ds_read_b128 v[210:213], v187 offset:21504
	ds_read_b128 v[214:217], v187 offset:22528
	ds_read_b128 v[218:221], v187 offset:23552
	global_load_lds_dwordx4 v[176:177], off
	v_lshl_add_u64 v[176:177], s[76:77], 0, v[164:165]
	s_add_u32 s62, s76, 0x10100
	v_lshl_add_u64 v[182:183], v[176:177], 0, s[44:45]
	s_mov_b32 m0, s61
	s_addc_u32 s63, s77, 0
	global_load_lds_dwordx4 v[182:183], off
	v_lshl_add_u64 v[182:183], s[62:63], 0, v[162:163]
	s_mov_b32 m0, s68
	s_nop 0
	global_load_lds_dwordx4 v[182:183], off
	v_lshl_add_u64 v[182:183], s[62:63], 0, v[164:165]
	s_mov_b32 m0, s69
	s_nop 0
	global_load_lds_dwordx4 v[182:183], off
	v_lshl_add_u64 v[182:183], s[74:75], 0, v[166:167]
	v_lshl_add_u64 v[184:185], v[182:183], 0, s[44:45]
	s_mov_b32 m0, s8
	s_nop 0
	global_load_lds_dwordx4 v[184:185], off
	v_lshl_add_u64 v[184:185], s[74:75], 0, v[168:169]
	v_lshl_add_u64 v[222:223], v[184:185], 0, s[44:45]
	s_mov_b32 m0, s71
	s_nop 0
	global_load_lds_dwordx4 v[222:223], off
	s_waitcnt vmcnt(8)
	s_waitcnt lgkmcnt(0)
	s_setprio 1
	s_barrier
	v_mfma_f32_16x16x128_f8f6f4 v[94:97], v[18:25], v[190:197], 0
	v_mfma_f32_16x16x128_f8f6f4 v[90:93], v[26:33], v[190:197], 0
	v_mfma_f32_16x16x128_f8f6f4 v[58:61], v[10:17], v[190:197], 0
	v_mfma_f32_16x16x128_f8f6f4 v[62:65], v[2:9], v[190:197], 0
	s_setprio 0
	s_setprio 1
	v_mfma_f32_16x16x128_f8f6f4 v[54:57], v[2:9], v[198:205], 0
	v_mfma_f32_16x16x128_f8f6f4 v[50:53], v[10:17], v[198:205], 0
	v_mfma_f32_16x16x128_f8f6f4 v[82:85], v[26:33], v[198:205], 0
	v_mfma_f32_16x16x128_f8f6f4 v[86:89], v[18:25], v[198:205], 0
	s_setprio 0
	s_setprio 1
	v_mfma_f32_16x16x128_f8f6f4 v[78:81], v[18:25], v[206:213], 0
	v_mfma_f32_16x16x128_f8f6f4 v[74:77], v[26:33], v[206:213], 0
	v_mfma_f32_16x16x128_f8f6f4 v[42:45], v[10:17], v[206:213], 0
	v_mfma_f32_16x16x128_f8f6f4 v[46:49], v[2:9], v[206:213], 0
	s_setprio 0
	s_setprio 1
	v_mfma_f32_16x16x128_f8f6f4 v[38:41], v[2:9], v[214:221], 0
	v_mfma_f32_16x16x128_f8f6f4 v[34:37], v[10:17], v[214:221], 0
	v_mfma_f32_16x16x128_f8f6f4 v[66:69], v[26:33], v[214:221], 0
	v_mfma_f32_16x16x128_f8f6f4 v[70:73], v[18:25], v[214:221], 0
	s_barrier
	s_setprio 0
	ds_read_b128 v[2:5], v181 offset:32768
	ds_read_b128 v[6:9], v181 offset:33792
	ds_read_b128 v[10:13], v181 offset:34816
	ds_read_b128 v[14:17], v181 offset:35840
	ds_read_b128 v[18:21], v181 offset:49152
	ds_read_b128 v[22:25], v181 offset:50176
	ds_read_b128 v[26:29], v181 offset:51200
	ds_read_b128 v[30:33], v181 offset:52224
	s_add_u32 s62, s74, 0x40100
	s_addc_u32 s63, s75, 0
	s_mov_b32 m0, s73
	v_lshl_add_u64 v[222:223], s[62:63], 0, v[166:167]
	ds_read_b128 v[190:193], v187 offset:32768
	ds_read_b128 v[194:197], v187 offset:33792
	ds_read_b128 v[198:201], v187 offset:34816
	ds_read_b128 v[202:205], v187 offset:35840
	ds_read_b128 v[206:209], v187 offset:36864
	ds_read_b128 v[210:213], v187 offset:37888
	ds_read_b128 v[214:217], v187 offset:38912
	ds_read_b128 v[218:221], v187 offset:39936
	global_load_lds_dwordx4 v[222:223], off
	v_lshl_add_u64 v[222:223], s[62:63], 0, v[168:169]
	s_mov_b32 m0, s82
	s_nop 0
	global_load_lds_dwordx4 v[222:223], off
	s_waitcnt vmcnt(8)
	s_waitcnt lgkmcnt(0)
	s_setprio 1
	s_barrier
	v_mfma_f32_16x16x128_f8f6f4 v[158:161], v[2:9], v[190:197], v[158:161]
	v_mfma_f32_16x16x128_f8f6f4 v[154:157], v[10:17], v[190:197], v[154:157]
	v_mfma_f32_16x16x128_f8f6f4 v[122:125], v[26:33], v[190:197], v[122:125]
	v_mfma_f32_16x16x128_f8f6f4 v[126:129], v[18:25], v[190:197], v[126:129]
	s_setprio 0
	s_setprio 1
	v_mfma_f32_16x16x128_f8f6f4 v[118:121], v[18:25], v[198:205], v[118:121]
	v_mfma_f32_16x16x128_f8f6f4 v[114:117], v[26:33], v[198:205], v[114:117]
	v_mfma_f32_16x16x128_f8f6f4 v[146:149], v[10:17], v[198:205], v[146:149]
	v_mfma_f32_16x16x128_f8f6f4 v[150:153], v[2:9], v[198:205], v[150:153]
	s_setprio 0
	s_setprio 1
	v_mfma_f32_16x16x128_f8f6f4 v[142:145], v[2:9], v[206:213], v[142:145]
	v_mfma_f32_16x16x128_f8f6f4 v[138:141], v[10:17], v[206:213], v[138:141]
	v_mfma_f32_16x16x128_f8f6f4 v[106:109], v[26:33], v[206:213], v[106:109]
	v_mfma_f32_16x16x128_f8f6f4 v[110:113], v[18:25], v[206:213], v[110:113]
	s_setprio 0
	s_setprio 1
	v_mfma_f32_16x16x128_f8f6f4 v[102:105], v[18:25], v[214:221], v[102:105]
	v_mfma_f32_16x16x128_f8f6f4 v[98:101], v[26:33], v[214:221], v[98:101]
	v_mfma_f32_16x16x128_f8f6f4 v[130:133], v[10:17], v[214:221], v[130:133]
	v_mfma_f32_16x16x128_f8f6f4 v[134:137], v[2:9], v[214:221], v[134:137]
	s_barrier
	s_setprio 0
	s_mov_b32 m0, s83
	v_lshl_add_u64 v[174:175], v[174:175], 0, s[46:47]
	s_add_u32 s62, s76, 0x10180
	ds_read_b128 v[190:193], v187 offset:49152
	ds_read_b128 v[194:197], v187 offset:50176
	ds_read_b128 v[198:201], v187 offset:51200
	ds_read_b128 v[202:205], v187 offset:52224
	ds_read_b128 v[206:209], v187 offset:53248
	ds_read_b128 v[210:213], v187 offset:54272
	ds_read_b128 v[214:217], v187 offset:55296
	ds_read_b128 v[218:221], v187 offset:56320
	global_load_lds_dwordx4 v[174:175], off
	v_lshl_add_u64 v[174:175], v[176:177], 0, s[46:47]
	s_mov_b32 m0, s84
	s_addc_u32 s63, s77, 0
	global_load_lds_dwordx4 v[174:175], off
	v_lshl_add_u64 v[174:175], s[62:63], 0, v[162:163]
	s_mov_b32 m0, s87
	s_nop 0
	global_load_lds_dwordx4 v[174:175], off
	v_lshl_add_u64 v[174:175], s[62:63], 0, v[164:165]
	s_mov_b32 m0, s88
	s_nop 0
	global_load_lds_dwordx4 v[174:175], off
	v_lshl_add_u64 v[174:175], v[182:183], 0, s[46:47]
	s_mov_b32 m0, s85
	s_nop 0
	global_load_lds_dwordx4 v[174:175], off
	v_lshl_add_u64 v[174:175], v[184:185], 0, s[46:47]
	s_mov_b32 m0, s86
	s_nop 0
	global_load_lds_dwordx4 v[174:175], off
	s_waitcnt vmcnt(8)
	s_waitcnt lgkmcnt(0)
	s_setprio 1
	s_barrier
	v_mfma_f32_16x16x128_f8f6f4 v[94:97], v[2:9], v[190:197], v[94:97]
	v_mfma_f32_16x16x128_f8f6f4 v[90:93], v[10:17], v[190:197], v[90:93]
	v_mfma_f32_16x16x128_f8f6f4 v[58:61], v[26:33], v[190:197], v[58:61]
	v_mfma_f32_16x16x128_f8f6f4 v[62:65], v[18:25], v[190:197], v[62:65]
	s_setprio 0
	s_setprio 1
	v_mfma_f32_16x16x128_f8f6f4 v[54:57], v[18:25], v[198:205], v[54:57]
	v_mfma_f32_16x16x128_f8f6f4 v[50:53], v[26:33], v[198:205], v[50:53]
	v_mfma_f32_16x16x128_f8f6f4 v[82:85], v[10:17], v[198:205], v[82:85]
	v_mfma_f32_16x16x128_f8f6f4 v[86:89], v[2:9], v[198:205], v[86:89]
	s_setprio 0
	s_setprio 1
	v_mfma_f32_16x16x128_f8f6f4 v[78:81], v[2:9], v[206:213], v[78:81]
	v_mfma_f32_16x16x128_f8f6f4 v[74:77], v[10:17], v[206:213], v[74:77]
	v_mfma_f32_16x16x128_f8f6f4 v[42:45], v[26:33], v[206:213], v[42:45]
	v_mfma_f32_16x16x128_f8f6f4 v[46:49], v[18:25], v[206:213], v[46:49]
	s_setprio 0
	s_setprio 1
	v_mfma_f32_16x16x128_f8f6f4 v[38:41], v[18:25], v[214:221], v[38:41]
	v_mfma_f32_16x16x128_f8f6f4 v[34:37], v[26:33], v[214:221], v[34:37]
	v_mfma_f32_16x16x128_f8f6f4 v[66:69], v[10:17], v[214:221], v[66:69]
	v_mfma_f32_16x16x128_f8f6f4 v[70:73], v[2:9], v[214:221], v[70:73]
	s_barrier
	s_setprio 0
	ds_read_b128 v[2:5], v181
	ds_read_b128 v[6:9], v181 offset:1024
	ds_read_b128 v[10:13], v181 offset:2048
	ds_read_b128 v[14:17], v181 offset:3072
	ds_read_b128 v[18:21], v181 offset:16384
	ds_read_b128 v[22:25], v181 offset:17408
	ds_read_b128 v[26:29], v181 offset:18432
	ds_read_b128 v[30:33], v181 offset:19456
	s_add_u32 s62, s74, 0x40180
	s_addc_u32 s63, s75, 0
	s_mov_b32 m0, s33
	v_lshl_add_u64 v[174:175], s[62:63], 0, v[166:167]
	ds_read_b128 v[190:193], v187
	ds_read_b128 v[194:197], v187 offset:1024
	ds_read_b128 v[198:201], v187 offset:2048
	ds_read_b128 v[202:205], v187 offset:3072
	ds_read_b128 v[206:209], v187 offset:4096
	ds_read_b128 v[210:213], v187 offset:5120
	ds_read_b128 v[214:217], v187 offset:6144
	ds_read_b128 v[218:221], v187 offset:7168
	global_load_lds_dwordx4 v[174:175], off
	v_lshl_add_u64 v[174:175], s[62:63], 0, v[168:169]
	s_mov_b32 m0, s5
	s_nop 0
	global_load_lds_dwordx4 v[174:175], off
	s_waitcnt vmcnt(8)
	s_waitcnt lgkmcnt(0)
	s_setprio 1
	s_barrier
	v_mfma_f32_16x16x128_f8f6f4 v[158:161], v[2:9], v[190:197], v[158:161]
	v_mfma_f32_16x16x128_f8f6f4 v[154:157], v[10:17], v[190:197], v[154:157]
	v_mfma_f32_16x16x128_f8f6f4 v[122:125], v[26:33], v[190:197], v[122:125]
	v_mfma_f32_16x16x128_f8f6f4 v[126:129], v[18:25], v[190:197], v[126:129]
	s_setprio 0
	s_setprio 1
	v_mfma_f32_16x16x128_f8f6f4 v[118:121], v[18:25], v[198:205], v[118:121]
	v_mfma_f32_16x16x128_f8f6f4 v[114:117], v[26:33], v[198:205], v[114:117]
	v_mfma_f32_16x16x128_f8f6f4 v[146:149], v[10:17], v[198:205], v[146:149]
	v_mfma_f32_16x16x128_f8f6f4 v[150:153], v[2:9], v[198:205], v[150:153]
	s_setprio 0
	s_setprio 1
	v_mfma_f32_16x16x128_f8f6f4 v[142:145], v[2:9], v[206:213], v[142:145]
	v_mfma_f32_16x16x128_f8f6f4 v[138:141], v[10:17], v[206:213], v[138:141]
	v_mfma_f32_16x16x128_f8f6f4 v[106:109], v[26:33], v[206:213], v[106:109]
	v_mfma_f32_16x16x128_f8f6f4 v[110:113], v[18:25], v[206:213], v[110:113]
	s_setprio 0
	s_setprio 1
	v_mfma_f32_16x16x128_f8f6f4 v[102:105], v[18:25], v[214:221], v[102:105]
	v_mfma_f32_16x16x128_f8f6f4 v[98:101], v[26:33], v[214:221], v[98:101]
	v_mfma_f32_16x16x128_f8f6f4 v[130:133], v[10:17], v[214:221], v[130:133]
	v_mfma_f32_16x16x128_f8f6f4 v[134:137], v[2:9], v[214:221], v[134:137]
	s_barrier
	s_setprio 0
	s_mov_b32 m0, s9
	v_lshl_add_u64 v[174:175], s[78:79], 0, v[162:163]
	s_add_u32 s62, s78, 0x10000
	ds_read_b128 v[190:193], v187 offset:16384
	ds_read_b128 v[194:197], v187 offset:17408
	ds_read_b128 v[198:201], v187 offset:18432
	ds_read_b128 v[202:205], v187 offset:19456
	ds_read_b128 v[206:209], v187 offset:20480
	ds_read_b128 v[210:213], v187 offset:21504
	ds_read_b128 v[214:217], v187 offset:22528
	ds_read_b128 v[218:221], v187 offset:23552
	global_load_lds_dwordx4 v[174:175], off
	v_lshl_add_u64 v[176:177], s[78:79], 0, v[164:165]
	s_mov_b32 m0, s61
	s_addc_u32 s63, s79, 0
	global_load_lds_dwordx4 v[176:177], off
	v_lshl_add_u64 v[182:183], s[62:63], 0, v[162:163]
	s_mov_b32 m0, s68
	v_lshl_add_u64 v[184:185], s[80:81], 0, v[168:169]
	global_load_lds_dwordx4 v[182:183], off
	v_lshl_add_u64 v[182:183], s[62:63], 0, v[164:165]
	s_mov_b32 m0, s69
	s_nop 0
	global_load_lds_dwordx4 v[182:183], off
	v_lshl_add_u64 v[182:183], s[80:81], 0, v[166:167]
	s_mov_b32 m0, s8
	s_nop 0
	global_load_lds_dwordx4 v[182:183], off
	s_mov_b32 m0, s71
	s_nop 0
	global_load_lds_dwordx4 v[184:185], off
	s_waitcnt vmcnt(8)
	s_waitcnt lgkmcnt(0)
	s_setprio 1
	s_barrier
	v_mfma_f32_16x16x128_f8f6f4 v[94:97], v[2:9], v[190:197], v[94:97]
	v_mfma_f32_16x16x128_f8f6f4 v[90:93], v[10:17], v[190:197], v[90:93]
	v_mfma_f32_16x16x128_f8f6f4 v[58:61], v[26:33], v[190:197], v[58:61]
	v_mfma_f32_16x16x128_f8f6f4 v[62:65], v[18:25], v[190:197], v[62:65]
	s_setprio 0
	s_setprio 1
	v_mfma_f32_16x16x128_f8f6f4 v[54:57], v[18:25], v[198:205], v[54:57]
	v_mfma_f32_16x16x128_f8f6f4 v[50:53], v[26:33], v[198:205], v[50:53]
	v_mfma_f32_16x16x128_f8f6f4 v[82:85], v[10:17], v[198:205], v[82:85]
	v_mfma_f32_16x16x128_f8f6f4 v[86:89], v[2:9], v[198:205], v[86:89]
	s_setprio 0
	s_setprio 1
	v_mfma_f32_16x16x128_f8f6f4 v[78:81], v[2:9], v[206:213], v[78:81]
	v_mfma_f32_16x16x128_f8f6f4 v[74:77], v[10:17], v[206:213], v[74:77]
	v_mfma_f32_16x16x128_f8f6f4 v[42:45], v[26:33], v[206:213], v[42:45]
	v_mfma_f32_16x16x128_f8f6f4 v[46:49], v[18:25], v[206:213], v[46:49]
	s_setprio 0
	s_setprio 1
	v_mfma_f32_16x16x128_f8f6f4 v[38:41], v[18:25], v[214:221], v[38:41]
	v_mfma_f32_16x16x128_f8f6f4 v[34:37], v[26:33], v[214:221], v[34:37]
	v_mfma_f32_16x16x128_f8f6f4 v[66:69], v[10:17], v[214:221], v[66:69]
	v_mfma_f32_16x16x128_f8f6f4 v[70:73], v[2:9], v[214:221], v[70:73]
	s_barrier
	s_setprio 0
	ds_read_b128 v[2:5], v181 offset:32768
	ds_read_b128 v[6:9], v181 offset:33792
	ds_read_b128 v[10:13], v181 offset:34816
	ds_read_b128 v[14:17], v181 offset:35840
	ds_read_b128 v[18:21], v181 offset:49152
	ds_read_b128 v[22:25], v181 offset:50176
	ds_read_b128 v[26:29], v181 offset:51200
	ds_read_b128 v[30:33], v181 offset:52224
	s_add_u32 s62, s80, 0x40000
	s_addc_u32 s63, s81, 0
	s_mov_b32 m0, s73
	v_lshl_add_u64 v[222:223], s[62:63], 0, v[166:167]
	ds_read_b128 v[190:193], v187 offset:32768
	ds_read_b128 v[194:197], v187 offset:33792
	ds_read_b128 v[198:201], v187 offset:34816
	ds_read_b128 v[202:205], v187 offset:35840
	ds_read_b128 v[206:209], v187 offset:36864
	ds_read_b128 v[210:213], v187 offset:37888
	ds_read_b128 v[214:217], v187 offset:38912
	ds_read_b128 v[218:221], v187 offset:39936
	global_load_lds_dwordx4 v[222:223], off
	v_lshl_add_u64 v[222:223], s[62:63], 0, v[168:169]
	s_mov_b32 m0, s82
	s_nop 0
	global_load_lds_dwordx4 v[222:223], off
	s_waitcnt vmcnt(8)
	s_waitcnt lgkmcnt(0)
	s_setprio 1
	s_barrier
	v_mfma_f32_16x16x128_f8f6f4 v[158:161], v[2:9], v[190:197], v[158:161]
	v_mfma_f32_16x16x128_f8f6f4 v[154:157], v[10:17], v[190:197], v[154:157]
	v_mfma_f32_16x16x128_f8f6f4 v[122:125], v[26:33], v[190:197], v[122:125]
	v_mfma_f32_16x16x128_f8f6f4 v[126:129], v[18:25], v[190:197], v[126:129]
	s_setprio 0
	s_setprio 1
	v_mfma_f32_16x16x128_f8f6f4 v[118:121], v[18:25], v[198:205], v[118:121]
	v_mfma_f32_16x16x128_f8f6f4 v[114:117], v[26:33], v[198:205], v[114:117]
	v_mfma_f32_16x16x128_f8f6f4 v[146:149], v[10:17], v[198:205], v[146:149]
	v_mfma_f32_16x16x128_f8f6f4 v[150:153], v[2:9], v[198:205], v[150:153]
	s_setprio 0
	s_setprio 1
	v_mfma_f32_16x16x128_f8f6f4 v[142:145], v[2:9], v[206:213], v[142:145]
	v_mfma_f32_16x16x128_f8f6f4 v[138:141], v[10:17], v[206:213], v[138:141]
	v_mfma_f32_16x16x128_f8f6f4 v[106:109], v[26:33], v[206:213], v[106:109]
	v_mfma_f32_16x16x128_f8f6f4 v[110:113], v[18:25], v[206:213], v[110:113]
	s_setprio 0
	s_setprio 1
	v_mfma_f32_16x16x128_f8f6f4 v[102:105], v[18:25], v[214:221], v[102:105]
	v_mfma_f32_16x16x128_f8f6f4 v[98:101], v[26:33], v[214:221], v[98:101]
	v_mfma_f32_16x16x128_f8f6f4 v[130:133], v[10:17], v[214:221], v[130:133]
	v_mfma_f32_16x16x128_f8f6f4 v[134:137], v[2:9], v[214:221], v[134:137]
	s_barrier
	s_setprio 0
	s_mov_b32 m0, s83
	v_lshl_add_u64 v[174:175], v[174:175], 0, s[38:39]
	s_add_u32 s62, s78, 0x10080
	ds_read_b128 v[190:193], v187 offset:49152
	ds_read_b128 v[194:197], v187 offset:50176
	ds_read_b128 v[198:201], v187 offset:51200
	ds_read_b128 v[202:205], v187 offset:52224
	ds_read_b128 v[206:209], v187 offset:53248
	ds_read_b128 v[210:213], v187 offset:54272
	ds_read_b128 v[214:217], v187 offset:55296
	ds_read_b128 v[218:221], v187 offset:56320
	global_load_lds_dwordx4 v[174:175], off
	v_lshl_add_u64 v[174:175], v[176:177], 0, s[38:39]
	s_mov_b32 m0, s84
	s_addc_u32 s63, s79, 0
	global_load_lds_dwordx4 v[174:175], off
	v_lshl_add_u64 v[174:175], s[62:63], 0, v[162:163]
	s_mov_b32 m0, s87
	s_nop 0
	global_load_lds_dwordx4 v[174:175], off
	v_lshl_add_u64 v[174:175], s[62:63], 0, v[164:165]
	s_mov_b32 m0, s88
	s_nop 0
	global_load_lds_dwordx4 v[174:175], off
	v_lshl_add_u64 v[174:175], v[182:183], 0, s[38:39]
	s_mov_b32 m0, s85
	s_nop 0
	global_load_lds_dwordx4 v[174:175], off
	v_lshl_add_u64 v[174:175], v[184:185], 0, s[38:39]
	s_mov_b32 m0, s86
	s_nop 0
	global_load_lds_dwordx4 v[174:175], off
	s_waitcnt vmcnt(8)
	s_waitcnt lgkmcnt(0)
	s_setprio 1
	s_barrier
	v_mfma_f32_16x16x128_f8f6f4 v[94:97], v[2:9], v[190:197], v[94:97]
	v_mfma_f32_16x16x128_f8f6f4 v[90:93], v[10:17], v[190:197], v[90:93]
	v_mfma_f32_16x16x128_f8f6f4 v[58:61], v[26:33], v[190:197], v[58:61]
	v_mfma_f32_16x16x128_f8f6f4 v[62:65], v[18:25], v[190:197], v[62:65]
	s_setprio 0
	s_setprio 1
	v_mfma_f32_16x16x128_f8f6f4 v[54:57], v[18:25], v[198:205], v[54:57]
	v_mfma_f32_16x16x128_f8f6f4 v[50:53], v[26:33], v[198:205], v[50:53]
	v_mfma_f32_16x16x128_f8f6f4 v[82:85], v[10:17], v[198:205], v[82:85]
	v_mfma_f32_16x16x128_f8f6f4 v[86:89], v[2:9], v[198:205], v[86:89]
	s_setprio 0
	s_setprio 1
	v_mfma_f32_16x16x128_f8f6f4 v[78:81], v[2:9], v[206:213], v[78:81]
	v_mfma_f32_16x16x128_f8f6f4 v[74:77], v[10:17], v[206:213], v[74:77]
	v_mfma_f32_16x16x128_f8f6f4 v[42:45], v[26:33], v[206:213], v[42:45]
	v_mfma_f32_16x16x128_f8f6f4 v[46:49], v[18:25], v[206:213], v[46:49]
	s_setprio 0
	s_setprio 1
	v_mfma_f32_16x16x128_f8f6f4 v[38:41], v[18:25], v[214:221], v[38:41]
	v_mfma_f32_16x16x128_f8f6f4 v[34:37], v[26:33], v[214:221], v[34:37]
	v_mfma_f32_16x16x128_f8f6f4 v[66:69], v[10:17], v[214:221], v[66:69]
	v_mfma_f32_16x16x128_f8f6f4 v[70:73], v[2:9], v[214:221], v[70:73]
	s_barrier
	s_setprio 0
	s_andn2_b64 vcc, exec, s[40:41]
	s_cbranch_vccnz .LBB0_632
	s_barrier

.LBB0_791:
	ds_read_b128 v[2:5], v189
	ds_read_b128 v[6:9], v189 offset:1024
	ds_read_b128 v[192:195], v189 offset:2048
	ds_read_b128 v[196:199], v189 offset:3072
	ds_read_b128 v[200:203], v189 offset:16384
	ds_read_b128 v[204:207], v189 offset:17408
	ds_read_b128 v[208:211], v189 offset:18432
	ds_read_b128 v[212:215], v189 offset:19456
	s_add_u32 s37, s46, 0x100
	s_addc_u32 s39, s47, 0
	s_and_b64 s[50:51], s[48:49], exec
	s_cselect_b32 s51, s1, s39
	s_cselect_b32 s50, s0, s37
	s_add_u32 s37, s44, 0x100
	s_addc_u32 s39, s45, 0
	s_and_b64 s[48:49], s[48:49], exec
	s_cselect_b32 s49, s5, s39
	s_cselect_b32 s48, s4, s37
	s_add_u32 s88, s46, 0x80080
	s_addc_u32 s89, s47, 0
	s_add_i32 s37, s8, 0xc000
	v_lshl_add_u64 v[174:175], s[88:89], 0, v[154:155]
	s_mov_b32 m0, s37
	s_add_i32 s39, s8, 0xe000
	ds_read_b128 v[216:219], v190
	ds_read_b128 v[220:223], v190 offset:1024
	ds_read_b128 v[224:227], v190 offset:2048
	ds_read_b128 v[228:231], v190 offset:3072
	ds_read_b128 v[242:245], v190 offset:4096
	ds_read_b128 v[246:249], v190 offset:5120
	ds_read_b128 v[232:235], v190 offset:6144
	ds_read_b128 v[236:239], v190 offset:7168
	global_load_lds_dwordx4 v[174:175], off
	v_lshl_add_u64 v[174:175], s[88:89], 0, v[158:159]
	s_mov_b32 m0, s39
	s_nop 0
	global_load_lds_dwordx4 v[174:175], off
	s_waitcnt vmcnt(8)
	s_waitcnt lgkmcnt(0)
	s_setprio 1
	s_barrier
	v_mfma_f32_16x16x128_f8f6f4 v[134:137], v[2:9], v[216:223], 0
	v_mfma_f32_16x16x128_f8f6f4 v[130:133], v[192:199], v[216:223], 0
	v_mfma_f32_16x16x128_f8f6f4 v[98:101], v[208:215], v[216:223], 0
	v_mfma_f32_16x16x128_f8f6f4 v[102:105], v[200:207], v[216:223], 0
	s_setprio 0
	s_setprio 1
	v_mfma_f32_16x16x128_f8f6f4 v[94:97], v[200:207], v[224:231], 0
	v_mfma_f32_16x16x128_f8f6f4 v[90:93], v[208:215], v[224:231], 0
	v_mfma_f32_16x16x128_f8f6f4 v[122:125], v[192:199], v[224:231], 0
	v_mfma_f32_16x16x128_f8f6f4 v[126:129], v[2:9], v[224:231], 0
	s_setprio 0
	s_setprio 1
	v_mfma_f32_16x16x128_f8f6f4 v[118:121], v[2:9], v[242:249], 0
	v_mfma_f32_16x16x128_f8f6f4 v[114:117], v[192:199], v[242:249], 0
	v_mfma_f32_16x16x128_f8f6f4 v[82:85], v[208:215], v[242:249], 0
	v_mfma_f32_16x16x128_f8f6f4 v[86:89], v[200:207], v[242:249], 0
	s_setprio 0
	s_setprio 1
	v_mfma_f32_16x16x128_f8f6f4 v[78:81], v[200:207], v[232:239], 0
	v_mfma_f32_16x16x128_f8f6f4 v[74:77], v[208:215], v[232:239], 0
	v_mfma_f32_16x16x128_f8f6f4 v[106:109], v[192:199], v[232:239], 0
	v_mfma_f32_16x16x128_f8f6f4 v[110:113], v[2:9], v[232:239], 0
	s_barrier
	s_setprio 0
	s_mov_b32 m0, s9
	v_lshl_add_u64 v[174:175], s[48:49], 0, v[156:157]
	s_add_u32 s88, s48, 0x80000
	ds_read_b128 v[216:219], v190 offset:16384
	ds_read_b128 v[220:223], v190 offset:17408
	ds_read_b128 v[224:227], v190 offset:18432
	ds_read_b128 v[228:231], v190 offset:19456
	ds_read_b128 v[232:235], v190 offset:20480
	ds_read_b128 v[236:239], v190 offset:21504
	ds_read_b128 v[242:245], v190 offset:22528
	ds_read_b128 v[246:249], v190 offset:23552
	global_load_lds_dwordx4 v[174:175], off
	v_lshl_add_u64 v[176:177], s[48:49], 0, v[160:161]
	s_mov_b32 m0, s27
	s_addc_u32 s89, s49, 0
	global_load_lds_dwordx4 v[176:177], off
	v_lshl_add_u64 v[182:183], s[88:89], 0, v[156:157]
	s_mov_b32 m0, s33
	v_lshl_add_u64 v[184:185], s[50:51], 0, v[158:159]
	global_load_lds_dwordx4 v[182:183], off
	v_lshl_add_u64 v[182:183], s[88:89], 0, v[160:161]
	s_mov_b32 m0, s35
	s_nop 0
	global_load_lds_dwordx4 v[182:183], off
	v_lshl_add_u64 v[182:183], s[50:51], 0, v[154:155]
	s_mov_b32 m0, s8
	s_nop 0
	global_load_lds_dwordx4 v[182:183], off
	s_mov_b32 m0, s43
	s_nop 0
	global_load_lds_dwordx4 v[184:185], off
	s_waitcnt vmcnt(8)
	s_waitcnt lgkmcnt(0)
	s_setprio 1
	s_barrier
	v_mfma_f32_16x16x128_f8f6f4 v[70:73], v[2:9], v[216:223], 0
	v_mfma_f32_16x16x128_f8f6f4 v[66:69], v[192:199], v[216:223], 0
	v_mfma_f32_16x16x128_f8f6f4 v[34:37], v[208:215], v[216:223], 0
	v_mfma_f32_16x16x128_f8f6f4 v[38:41], v[200:207], v[216:223], 0
	s_setprio 0
	s_setprio 1
	v_mfma_f32_16x16x128_f8f6f4 v[30:33], v[200:207], v[224:231], 0
	v_mfma_f32_16x16x128_f8f6f4 v[26:29], v[208:215], v[224:231], 0
	v_mfma_f32_16x16x128_f8f6f4 v[58:61], v[192:199], v[224:231], 0
	v_mfma_f32_16x16x128_f8f6f4 v[62:65], v[2:9], v[224:231], 0
	s_setprio 0
	s_setprio 1
	v_mfma_f32_16x16x128_f8f6f4 v[54:57], v[2:9], v[232:239], 0
	v_mfma_f32_16x16x128_f8f6f4 v[50:53], v[192:199], v[232:239], 0
	v_mfma_f32_16x16x128_f8f6f4 v[18:21], v[208:215], v[232:239], 0
	v_mfma_f32_16x16x128_f8f6f4 v[22:25], v[200:207], v[232:239], 0
	s_setprio 0
	s_setprio 1
	v_mfma_f32_16x16x128_f8f6f4 v[14:17], v[200:207], v[242:249], 0
	v_mfma_f32_16x16x128_f8f6f4 v[10:13], v[208:215], v[242:249], 0
	v_mfma_f32_16x16x128_f8f6f4 v[42:45], v[192:199], v[242:249], 0
	v_mfma_f32_16x16x128_f8f6f4 v[46:49], v[2:9], v[242:249], 0
	s_barrier
	s_setprio 0
	ds_read_b128 v[2:5], v189 offset:32768
	ds_read_b128 v[6:9], v189 offset:33792
	ds_read_b128 v[192:195], v189 offset:34816
	ds_read_b128 v[196:199], v189 offset:35840
	ds_read_b128 v[200:203], v189 offset:49152
	ds_read_b128 v[204:207], v189 offset:50176
	ds_read_b128 v[208:211], v189 offset:51200
	ds_read_b128 v[212:215], v189 offset:52224
	s_add_u32 s50, s50, 0x80000
	s_addc_u32 s51, s51, 0
	s_mov_b32 m0, s52
	v_lshl_add_u64 v[186:187], s[50:51], 0, v[154:155]
	ds_read_b128 v[216:219], v190 offset:32768
	ds_read_b128 v[220:223], v190 offset:33792
	ds_read_b128 v[224:227], v190 offset:34816
	ds_read_b128 v[228:231], v190 offset:35840
	ds_read_b128 v[232:235], v190 offset:36864
	ds_read_b128 v[236:239], v190 offset:37888
	ds_read_b128 v[242:245], v190 offset:38912
	ds_read_b128 v[246:249], v190 offset:39936
	global_load_lds_dwordx4 v[186:187], off
	v_lshl_add_u64 v[186:187], s[50:51], 0, v[158:159]
	s_mov_b32 m0, s53
	s_nop 0
	global_load_lds_dwordx4 v[186:187], off
	s_waitcnt vmcnt(8)
	s_waitcnt lgkmcnt(0)
	s_setprio 1
	s_barrier
	v_mfma_f32_16x16x128_f8f6f4 v[134:137], v[2:9], v[216:223], v[134:137]
	v_mfma_f32_16x16x128_f8f6f4 v[130:133], v[192:199], v[216:223], v[130:133]
	v_mfma_f32_16x16x128_f8f6f4 v[98:101], v[208:215], v[216:223], v[98:101]
	v_mfma_f32_16x16x128_f8f6f4 v[102:105], v[200:207], v[216:223], v[102:105]
	s_setprio 0
	s_setprio 1
	v_mfma_f32_16x16x128_f8f6f4 v[94:97], v[200:207], v[224:231], v[94:97]
	v_mfma_f32_16x16x128_f8f6f4 v[90:93], v[208:215], v[224:231], v[90:93]
	v_mfma_f32_16x16x128_f8f6f4 v[122:125], v[192:199], v[224:231], v[122:125]
	v_mfma_f32_16x16x128_f8f6f4 v[126:129], v[2:9], v[224:231], v[126:129]
	s_setprio 0
	s_setprio 1
	v_mfma_f32_16x16x128_f8f6f4 v[118:121], v[2:9], v[232:239], v[118:121]
	v_mfma_f32_16x16x128_f8f6f4 v[114:117], v[192:199], v[232:239], v[114:117]
	v_mfma_f32_16x16x128_f8f6f4 v[82:85], v[208:215], v[232:239], v[82:85]
	v_mfma_f32_16x16x128_f8f6f4 v[86:89], v[200:207], v[232:239], v[86:89]
	s_setprio 0
	s_setprio 1
	v_mfma_f32_16x16x128_f8f6f4 v[78:81], v[200:207], v[242:249], v[78:81]
	v_mfma_f32_16x16x128_f8f6f4 v[74:77], v[208:215], v[242:249], v[74:77]
	v_mfma_f32_16x16x128_f8f6f4 v[106:109], v[192:199], v[242:249], v[106:109]
	v_mfma_f32_16x16x128_f8f6f4 v[110:113], v[2:9], v[242:249], v[110:113]
	s_barrier
	s_setprio 0
	s_mov_b32 m0, s70
	v_lshl_add_u64 v[174:175], v[174:175], 0, s[18:19]
	s_add_u32 s48, s48, 0x80080
	ds_read_b128 v[216:219], v190 offset:49152
	ds_read_b128 v[220:223], v190 offset:50176
	ds_read_b128 v[224:227], v190 offset:51200
	ds_read_b128 v[228:231], v190 offset:52224
	ds_read_b128 v[232:235], v190 offset:53248
	ds_read_b128 v[236:239], v190 offset:54272
	ds_read_b128 v[242:245], v190 offset:55296
	ds_read_b128 v[246:249], v190 offset:56320
	global_load_lds_dwordx4 v[174:175], off
	v_lshl_add_u64 v[174:175], v[176:177], 0, s[18:19]
	s_mov_b32 m0, s71
	s_addc_u32 s49, s49, 0
	global_load_lds_dwordx4 v[174:175], off
	v_lshl_add_u64 v[174:175], s[48:49], 0, v[156:157]
	s_mov_b32 m0, s74
	s_nop 0
	global_load_lds_dwordx4 v[174:175], off
	v_lshl_add_u64 v[174:175], s[48:49], 0, v[160:161]
	s_mov_b32 m0, s75
	s_nop 0
	global_load_lds_dwordx4 v[174:175], off
	v_lshl_add_u64 v[174:175], v[182:183], 0, s[18:19]
	s_mov_b32 m0, s72
	s_nop 0
	global_load_lds_dwordx4 v[174:175], off
	v_lshl_add_u64 v[174:175], v[184:185], 0, s[18:19]
	s_mov_b32 m0, s73
	s_nop 0
	global_load_lds_dwordx4 v[174:175], off
	s_waitcnt vmcnt(8)
	s_waitcnt lgkmcnt(0)
	s_setprio 1
	s_barrier
	v_mfma_f32_16x16x128_f8f6f4 v[70:73], v[2:9], v[216:223], v[70:73]
	v_mfma_f32_16x16x128_f8f6f4 v[66:69], v[192:199], v[216:223], v[66:69]
	v_mfma_f32_16x16x128_f8f6f4 v[34:37], v[208:215], v[216:223], v[34:37]
	v_mfma_f32_16x16x128_f8f6f4 v[38:41], v[200:207], v[216:223], v[38:41]
	s_setprio 0
	s_setprio 1
	v_mfma_f32_16x16x128_f8f6f4 v[30:33], v[200:207], v[224:231], v[30:33]
	v_mfma_f32_16x16x128_f8f6f4 v[26:29], v[208:215], v[224:231], v[26:29]
	v_mfma_f32_16x16x128_f8f6f4 v[58:61], v[192:199], v[224:231], v[58:61]
	v_mfma_f32_16x16x128_f8f6f4 v[62:65], v[2:9], v[224:231], v[62:65]
	s_setprio 0
	s_setprio 1
	v_mfma_f32_16x16x128_f8f6f4 v[54:57], v[2:9], v[232:239], v[54:57]
	v_mfma_f32_16x16x128_f8f6f4 v[50:53], v[192:199], v[232:239], v[50:53]
	v_mfma_f32_16x16x128_f8f6f4 v[18:21], v[208:215], v[232:239], v[18:21]
	v_mfma_f32_16x16x128_f8f6f4 v[22:25], v[200:207], v[232:239], v[22:25]
	s_setprio 0
	s_setprio 1
	v_mfma_f32_16x16x128_f8f6f4 v[14:17], v[200:207], v[242:249], v[14:17]
	v_mfma_f32_16x16x128_f8f6f4 v[10:13], v[208:215], v[242:249], v[10:13]
	v_mfma_f32_16x16x128_f8f6f4 v[42:45], v[192:199], v[242:249], v[42:45]
	v_mfma_f32_16x16x128_f8f6f4 v[46:49], v[2:9], v[242:249], v[46:49]
	s_barrier
	s_setprio 0
	s_cmp_lt_u32 s86, 3
	s_cbranch_scc1 .LBB0_796
	s_add_u32 s48, s55, s62
	s_addc_u32 s49, s61, s41
	s_add_u32 s46, s46, 0x80180
	s_addc_u32 s47, s47, 0
	s_add_u32 s41, s44, 0x200
	v_lshl_add_u64 v[174:175], v[172:173], 2, s[48:49]
	s_addc_u32 s50, s45, 0
	s_mov_b32 s51, 4
	s_cmp_eq_u32 s86, s51
	s_cselect_b64 s[44:45], -1, 0
	s_cmp_lg_u32 s86, s51
	s_cbranch_scc1 .LBB0_794

.LBB0_794:
	ds_read_b128 v[2:5], v189
	ds_read_b128 v[6:9], v189 offset:1024
	ds_read_b128 v[192:195], v189 offset:2048
	ds_read_b128 v[196:199], v189 offset:3072
	ds_read_b128 v[200:203], v189 offset:16384
	ds_read_b128 v[204:207], v189 offset:17408
	ds_read_b128 v[208:211], v189 offset:18432
	ds_read_b128 v[212:215], v189 offset:19456
	s_add_u32 s48, s46, 0xfff80080
	s_addc_u32 s49, s47, -1
	s_and_b64 s[44:45], s[44:45], exec
	s_cselect_b32 s44, s4, s41
	s_cselect_b32 s49, s1, s49
	s_cselect_b32 s48, s0, s48
	s_cselect_b32 s45, s5, s50
	s_mov_b32 m0, s37
	v_lshl_add_u64 v[176:177], s[46:47], 0, v[162:163]
	ds_read_b128 v[216:219], v190
	ds_read_b128 v[220:223], v190 offset:1024
	ds_read_b128 v[224:227], v190 offset:2048
	ds_read_b128 v[228:231], v190 offset:3072
	ds_read_b128 v[232:235], v190 offset:4096
	ds_read_b128 v[236:239], v190 offset:5120
	ds_read_b128 v[242:245], v190 offset:6144
	ds_read_b128 v[246:249], v190 offset:7168
	global_load_lds_dwordx4 v[176:177], off
	v_lshl_add_u64 v[176:177], s[46:47], 0, v[164:165]
	s_mov_b32 m0, s39
	s_nop 0
	global_load_lds_dwordx4 v[176:177], off
	s_waitcnt vmcnt(8)
	s_waitcnt lgkmcnt(0)
	s_setprio 1
	s_barrier
	v_mfma_f32_16x16x128_f8f6f4 v[134:137], v[2:9], v[216:223], v[134:137]
	v_mfma_f32_16x16x128_f8f6f4 v[130:133], v[192:199], v[216:223], v[130:133]
	v_mfma_f32_16x16x128_f8f6f4 v[98:101], v[208:215], v[216:223], v[98:101]
	v_mfma_f32_16x16x128_f8f6f4 v[102:105], v[200:207], v[216:223], v[102:105]
	s_setprio 0
	s_setprio 1
	v_mfma_f32_16x16x128_f8f6f4 v[94:97], v[200:207], v[224:231], v[94:97]
	v_mfma_f32_16x16x128_f8f6f4 v[90:93], v[208:215], v[224:231], v[90:93]
	v_mfma_f32_16x16x128_f8f6f4 v[122:125], v[192:199], v[224:231], v[122:125]
	v_mfma_f32_16x16x128_f8f6f4 v[126:129], v[2:9], v[224:231], v[126:129]
	s_setprio 0
	s_setprio 1
	v_mfma_f32_16x16x128_f8f6f4 v[118:121], v[2:9], v[232:239], v[118:121]
	v_mfma_f32_16x16x128_f8f6f4 v[114:117], v[192:199], v[232:239], v[114:117]
	v_mfma_f32_16x16x128_f8f6f4 v[82:85], v[208:215], v[232:239], v[82:85]
	v_mfma_f32_16x16x128_f8f6f4 v[86:89], v[200:207], v[232:239], v[86:89]
	s_setprio 0
	s_setprio 1
	v_mfma_f32_16x16x128_f8f6f4 v[78:81], v[200:207], v[242:249], v[78:81]
	v_mfma_f32_16x16x128_f8f6f4 v[74:77], v[208:215], v[242:249], v[74:77]
	v_mfma_f32_16x16x128_f8f6f4 v[106:109], v[192:199], v[242:249], v[106:109]
	v_mfma_f32_16x16x128_f8f6f4 v[110:113], v[2:9], v[242:249], v[110:113]
	s_barrier
	s_setprio 0
	s_mov_b32 m0, s9
	v_lshl_add_u64 v[176:177], s[44:45], 0, v[156:157]
	s_add_u32 s62, s44, 0x80000
	ds_read_b128 v[216:219], v190 offset:16384
	ds_read_b128 v[220:223], v190 offset:17408
	ds_read_b128 v[224:227], v190 offset:18432
	ds_read_b128 v[228:231], v190 offset:19456
	ds_read_b128 v[232:235], v190 offset:20480
	ds_read_b128 v[236:239], v190 offset:21504
	ds_read_b128 v[242:245], v190 offset:22528
	ds_read_b128 v[246:249], v190 offset:23552
	global_load_lds_dwordx4 v[176:177], off
	v_lshl_add_u64 v[182:183], s[44:45], 0, v[160:161]
	s_mov_b32 m0, s27
	s_addc_u32 s63, s45, 0
	global_load_lds_dwordx4 v[182:183], off
	v_lshl_add_u64 v[184:185], s[62:63], 0, v[156:157]
	s_mov_b32 m0, s33
	v_lshl_add_u64 v[186:187], s[48:49], 0, v[158:159]
	global_load_lds_dwordx4 v[184:185], off
	v_lshl_add_u64 v[184:185], s[62:63], 0, v[160:161]
	s_mov_b32 m0, s35
	s_nop 0
	global_load_lds_dwordx4 v[184:185], off
	v_lshl_add_u64 v[184:185], s[48:49], 0, v[154:155]
	s_mov_b32 m0, s8
	s_nop 0
	global_load_lds_dwordx4 v[184:185], off
	s_mov_b32 m0, s43
	s_nop 0
	global_load_lds_dwordx4 v[186:187], off
	s_waitcnt vmcnt(8)
	s_waitcnt lgkmcnt(0)
	s_setprio 1
	s_barrier
	v_mfma_f32_16x16x128_f8f6f4 v[70:73], v[2:9], v[216:223], v[70:73]
	v_mfma_f32_16x16x128_f8f6f4 v[66:69], v[192:199], v[216:223], v[66:69]
	v_mfma_f32_16x16x128_f8f6f4 v[34:37], v[208:215], v[216:223], v[34:37]
	v_mfma_f32_16x16x128_f8f6f4 v[38:41], v[200:207], v[216:223], v[38:41]
	s_setprio 0
	s_setprio 1
	v_mfma_f32_16x16x128_f8f6f4 v[30:33], v[200:207], v[224:231], v[30:33]
	v_mfma_f32_16x16x128_f8f6f4 v[26:29], v[208:215], v[224:231], v[26:29]
	v_mfma_f32_16x16x128_f8f6f4 v[58:61], v[192:199], v[224:231], v[58:61]
	v_mfma_f32_16x16x128_f8f6f4 v[62:65], v[2:9], v[224:231], v[62:65]
	s_setprio 0
	s_setprio 1
	v_mfma_f32_16x16x128_f8f6f4 v[54:57], v[2:9], v[232:239], v[54:57]
	v_mfma_f32_16x16x128_f8f6f4 v[50:53], v[192:199], v[232:239], v[50:53]
	v_mfma_f32_16x16x128_f8f6f4 v[18:21], v[208:215], v[232:239], v[18:21]
	v_mfma_f32_16x16x128_f8f6f4 v[22:25], v[200:207], v[232:239], v[22:25]
	s_setprio 0
	s_setprio 1
	v_mfma_f32_16x16x128_f8f6f4 v[14:17], v[200:207], v[242:249], v[14:17]
	v_mfma_f32_16x16x128_f8f6f4 v[10:13], v[208:215], v[242:249], v[10:13]
	v_mfma_f32_16x16x128_f8f6f4 v[42:45], v[192:199], v[242:249], v[42:45]
	v_mfma_f32_16x16x128_f8f6f4 v[46:49], v[2:9], v[242:249], v[46:49]
	s_barrier
	s_setprio 0
	ds_read_b128 v[192:195], v189 offset:32768
	ds_read_b128 v[196:199], v189 offset:33792
	ds_read_b128 v[200:203], v189 offset:34816
	ds_read_b128 v[204:207], v189 offset:35840
	ds_read_b128 v[2:5], v189 offset:49152
	ds_read_b128 v[6:9], v189 offset:50176
	ds_read_b128 v[208:211], v189 offset:51200
	ds_read_b128 v[212:215], v189 offset:52224
	s_add_u32 s48, s48, 0x80000
	s_addc_u32 s49, s49, 0
	s_mov_b32 m0, s52
	v_lshl_add_u64 v[252:253], s[48:49], 0, v[154:155]
	ds_read_b128 v[216:219], v190 offset:32768
	ds_read_b128 v[220:223], v190 offset:33792
	ds_read_b128 v[224:227], v190 offset:34816
	ds_read_b128 v[228:231], v190 offset:35840
	ds_read_b128 v[232:235], v190 offset:36864
	ds_read_b128 v[236:239], v190 offset:37888
	ds_read_b128 v[242:245], v190 offset:38912
	ds_read_b128 v[246:249], v190 offset:39936
	global_load_lds_dwordx4 v[252:253], off
	v_lshl_add_u64 v[252:253], s[48:49], 0, v[158:159]
	s_mov_b32 m0, s53
	s_nop 0
	global_load_lds_dwordx4 v[252:253], off
	s_waitcnt vmcnt(8)
	s_waitcnt lgkmcnt(0)
	s_setprio 1
	s_barrier
	v_mfma_f32_16x16x128_f8f6f4 v[134:137], v[192:199], v[216:223], v[134:137]
	v_mfma_f32_16x16x128_f8f6f4 v[130:133], v[200:207], v[216:223], v[130:133]
	v_mfma_f32_16x16x128_f8f6f4 v[98:101], v[208:215], v[216:223], v[98:101]
	v_mfma_f32_16x16x128_f8f6f4 v[102:105], v[2:9], v[216:223], v[102:105]
	s_setprio 0
	s_setprio 1
	v_mfma_f32_16x16x128_f8f6f4 v[94:97], v[2:9], v[224:231], v[94:97]
	v_mfma_f32_16x16x128_f8f6f4 v[90:93], v[208:215], v[224:231], v[90:93]
	v_mfma_f32_16x16x128_f8f6f4 v[122:125], v[200:207], v[224:231], v[122:125]
	v_mfma_f32_16x16x128_f8f6f4 v[126:129], v[192:199], v[224:231], v[126:129]
	s_setprio 0
	s_setprio 1
	v_mfma_f32_16x16x128_f8f6f4 v[118:121], v[192:199], v[232:239], v[118:121]
	v_mfma_f32_16x16x128_f8f6f4 v[114:117], v[200:207], v[232:239], v[114:117]
	v_mfma_f32_16x16x128_f8f6f4 v[82:85], v[208:215], v[232:239], v[82:85]
	v_mfma_f32_16x16x128_f8f6f4 v[86:89], v[2:9], v[232:239], v[86:89]
	s_setprio 0
	s_setprio 1
	v_mfma_f32_16x16x128_f8f6f4 v[78:81], v[2:9], v[242:249], v[78:81]
	v_mfma_f32_16x16x128_f8f6f4 v[74:77], v[208:215], v[242:249], v[74:77]
	v_mfma_f32_16x16x128_f8f6f4 v[106:109], v[200:207], v[242:249], v[106:109]
	v_mfma_f32_16x16x128_f8f6f4 v[110:113], v[192:199], v[242:249], v[110:113]
	s_barrier
	s_setprio 0
	s_mov_b32 m0, s70
	v_lshl_add_u64 v[176:177], v[176:177], 0, s[18:19]
	s_add_u32 s44, s44, 0x80080
	ds_read_b128 v[216:219], v190 offset:49152
	ds_read_b128 v[220:223], v190 offset:50176
	ds_read_b128 v[224:227], v190 offset:51200
	ds_read_b128 v[228:231], v190 offset:52224
	ds_read_b128 v[232:235], v190 offset:53248
	ds_read_b128 v[236:239], v190 offset:54272
	ds_read_b128 v[242:245], v190 offset:55296
	ds_read_b128 v[246:249], v190 offset:56320
	global_load_lds_dwordx4 v[176:177], off
	v_lshl_add_u64 v[176:177], v[182:183], 0, s[18:19]
	s_mov_b32 m0, s71
	s_addc_u32 s45, s45, 0
	global_load_lds_dwordx4 v[176:177], off
	v_lshl_add_u64 v[176:177], s[44:45], 0, v[156:157]
	s_mov_b32 m0, s74
	s_nop 0
	global_load_lds_dwordx4 v[176:177], off
	v_lshl_add_u64 v[176:177], s[44:45], 0, v[160:161]
	s_mov_b32 m0, s75
	s_nop 0
	global_load_lds_dwordx4 v[176:177], off
	v_lshl_add_u64 v[176:177], v[184:185], 0, s[18:19]
	s_mov_b32 m0, s72
	s_nop 0
	global_load_lds_dwordx4 v[176:177], off
	v_lshl_add_u64 v[176:177], v[186:187], 0, s[18:19]
	s_mov_b32 m0, s73
	s_nop 0
	global_load_lds_dwordx4 v[176:177], off
	s_waitcnt vmcnt(8)
	s_waitcnt lgkmcnt(0)
	s_setprio 1
	s_barrier
	v_mfma_f32_16x16x128_f8f6f4 v[70:73], v[192:199], v[216:223], v[70:73]
	v_mfma_f32_16x16x128_f8f6f4 v[66:69], v[200:207], v[216:223], v[66:69]
	v_mfma_f32_16x16x128_f8f6f4 v[34:37], v[208:215], v[216:223], v[34:37]
	v_mfma_f32_16x16x128_f8f6f4 v[38:41], v[2:9], v[216:223], v[38:41]
	s_setprio 0
	s_setprio 1
	v_mfma_f32_16x16x128_f8f6f4 v[30:33], v[2:9], v[224:231], v[30:33]
	v_mfma_f32_16x16x128_f8f6f4 v[26:29], v[208:215], v[224:231], v[26:29]
	v_mfma_f32_16x16x128_f8f6f4 v[58:61], v[200:207], v[224:231], v[58:61]
	v_mfma_f32_16x16x128_f8f6f4 v[62:65], v[192:199], v[224:231], v[62:65]
	s_setprio 0
	s_setprio 1
	v_mfma_f32_16x16x128_f8f6f4 v[54:57], v[192:199], v[232:239], v[54:57]
	v_mfma_f32_16x16x128_f8f6f4 v[50:53], v[200:207], v[232:239], v[50:53]
	v_mfma_f32_16x16x128_f8f6f4 v[18:21], v[208:215], v[232:239], v[18:21]
	v_mfma_f32_16x16x128_f8f6f4 v[22:25], v[2:9], v[232:239], v[22:25]
	s_setprio 0
	s_setprio 1
	v_mfma_f32_16x16x128_f8f6f4 v[14:17], v[2:9], v[242:249], v[14:17]
	v_mfma_f32_16x16x128_f8f6f4 v[10:13], v[208:215], v[242:249], v[10:13]
	v_mfma_f32_16x16x128_f8f6f4 v[42:45], v[200:207], v[242:249], v[42:45]
	v_mfma_f32_16x16x128_f8f6f4 v[46:49], v[192:199], v[242:249], v[46:49]
	s_barrier
	s_setprio 0
	s_add_i32 s44, s51, 2
	s_add_u32 s46, s46, 0x100
	s_addc_u32 s47, s47, 0
	s_add_u32 s41, s41, 0x100
	s_addc_u32 s50, s50, 0
	s_cmp_ge_i32 s51, s86
	s_cbranch_scc1 .LBB0_796
	s_mov_b32 s51, s44
	s_cmp_eq_u32 s86, s51
	s_cselect_b64 s[44:45], -1, 0
	s_cmp_lg_u32 s86, s51
	s_cbranch_scc0 .LBB0_793
	s_branch .LBB0_794

.LBB0_946:
	s_ashr_i32 s37, s36, 31
	ds_read_b128 v[18:21], v192
	ds_read_b128 v[22:25], v192 offset:1024
	ds_read_b128 v[26:29], v192 offset:2048
	ds_read_b128 v[30:33], v192 offset:3072
	ds_read_b128 v[2:5], v192 offset:16384
	ds_read_b128 v[6:9], v192 offset:17408
	ds_read_b128 v[10:13], v192 offset:18432
	ds_read_b128 v[14:17], v192 offset:19456
	s_lshl_b64 s[38:39], s[36:37], 20
	s_add_u32 s38, s22, s38
	s_addc_u32 s39, s23, s39
	s_and_b64 s[40:41], s[2:3], exec
	s_cselect_b32 s37, s39, s47
	s_cselect_b32 s84, s38, s46
	s_ashr_i32 s27, s26, 31
	s_lshl_b64 s[40:41], s[26:27], 20
	s_add_u32 s40, s25, s40
	s_addc_u32 s41, s35, s41
	s_and_b64 s[48:49], s[2:3], exec
	s_cselect_b32 s27, s41, s45
	s_cselect_b32 s85, s40, s44
	s_add_u32 s48, s46, 0x80080
	s_addc_u32 s49, s47, 0
	s_mov_b32 m0, s80
	v_lshl_add_u64 v[218:219], s[48:49], 0, v[164:165]
	ds_read_b128 v[184:187], v193
	ds_read_b128 v[188:191], v193 offset:1024
	ds_read_b128 v[194:197], v193 offset:2048
	ds_read_b128 v[198:201], v193 offset:3072
	ds_read_b128 v[202:205], v193 offset:4096
	ds_read_b128 v[206:209], v193 offset:5120
	ds_read_b128 v[210:213], v193 offset:6144
	ds_read_b128 v[214:217], v193 offset:7168
	global_load_lds_dwordx4 v[218:219], off
	v_lshl_add_u64 v[218:219], s[48:49], 0, v[168:169]
	s_mov_b32 m0, s81
	s_nop 0
	global_load_lds_dwordx4 v[218:219], off
	s_waitcnt vmcnt(8)
	s_waitcnt lgkmcnt(0)
	s_setprio 1
	s_barrier
	v_mfma_f32_16x16x128_f8f6f4 v[158:161], v[18:25], v[184:191], 0
	v_mfma_f32_16x16x128_f8f6f4 v[154:157], v[26:33], v[184:191], 0
	v_mfma_f32_16x16x128_f8f6f4 v[122:125], v[10:17], v[184:191], 0
	v_mfma_f32_16x16x128_f8f6f4 v[126:129], v[2:9], v[184:191], 0
	s_setprio 0
	s_setprio 1
	v_mfma_f32_16x16x128_f8f6f4 v[118:121], v[2:9], v[194:201], 0
	v_mfma_f32_16x16x128_f8f6f4 v[114:117], v[10:17], v[194:201], 0
	v_mfma_f32_16x16x128_f8f6f4 v[146:149], v[26:33], v[194:201], 0
	v_mfma_f32_16x16x128_f8f6f4 v[150:153], v[18:25], v[194:201], 0
	s_setprio 0
	s_setprio 1
	v_mfma_f32_16x16x128_f8f6f4 v[142:145], v[18:25], v[202:209], 0
	v_mfma_f32_16x16x128_f8f6f4 v[138:141], v[26:33], v[202:209], 0
	v_mfma_f32_16x16x128_f8f6f4 v[106:109], v[10:17], v[202:209], 0
	v_mfma_f32_16x16x128_f8f6f4 v[110:113], v[2:9], v[202:209], 0
	s_setprio 0
	s_setprio 1
	v_mfma_f32_16x16x128_f8f6f4 v[102:105], v[2:9], v[210:217], 0
	v_mfma_f32_16x16x128_f8f6f4 v[98:101], v[10:17], v[210:217], 0
	v_mfma_f32_16x16x128_f8f6f4 v[130:133], v[26:33], v[210:217], 0
	v_mfma_f32_16x16x128_f8f6f4 v[134:137], v[18:25], v[210:217], 0
	s_barrier
	s_setprio 0
	v_lshl_add_u64 v[184:185], s[44:45], 0, v[166:167]
	s_mov_b32 m0, s52
	v_lshl_add_u64 v[186:187], v[184:185], 0, s[14:15]
	ds_read_b128 v[194:197], v193 offset:16384
	ds_read_b128 v[198:201], v193 offset:17408
	ds_read_b128 v[202:205], v193 offset:18432
	ds_read_b128 v[206:209], v193 offset:19456
	ds_read_b128 v[210:213], v193 offset:20480
	ds_read_b128 v[214:217], v193 offset:21504
	ds_read_b128 v[218:221], v193 offset:22528
	ds_read_b128 v[222:225], v193 offset:23552
	global_load_lds_dwordx4 v[186:187], off
	v_lshl_add_u64 v[186:187], s[44:45], 0, v[170:171]
	s_add_u32 s48, s44, 0x80100
	v_lshl_add_u64 v[188:189], v[186:187], 0, s[14:15]
	s_mov_b32 m0, s53
	s_addc_u32 s49, s45, 0
	global_load_lds_dwordx4 v[188:189], off
	v_lshl_add_u64 v[188:189], s[48:49], 0, v[166:167]
	s_mov_b32 m0, s54
	s_nop 0
	global_load_lds_dwordx4 v[188:189], off
	v_lshl_add_u64 v[188:189], s[48:49], 0, v[170:171]
	s_mov_b32 m0, s55
	s_nop 0
	global_load_lds_dwordx4 v[188:189], off
	v_lshl_add_u64 v[188:189], s[46:47], 0, v[164:165]
	v_lshl_add_u64 v[190:191], v[188:189], 0, s[14:15]
	s_mov_b32 m0, s43
	s_nop 0
	global_load_lds_dwordx4 v[190:191], off
	v_lshl_add_u64 v[190:191], s[46:47], 0, v[168:169]
	v_lshl_add_u64 v[226:227], v[190:191], 0, s[14:15]
	s_mov_b32 m0, s61
	s_nop 0
	global_load_lds_dwordx4 v[226:227], off
	s_waitcnt vmcnt(8)
	s_waitcnt lgkmcnt(0)
	s_setprio 1
	s_barrier
	v_mfma_f32_16x16x128_f8f6f4 v[94:97], v[18:25], v[194:201], 0
	v_mfma_f32_16x16x128_f8f6f4 v[90:93], v[26:33], v[194:201], 0
	v_mfma_f32_16x16x128_f8f6f4 v[58:61], v[10:17], v[194:201], 0
	v_mfma_f32_16x16x128_f8f6f4 v[62:65], v[2:9], v[194:201], 0
	s_setprio 0
	s_setprio 1
	v_mfma_f32_16x16x128_f8f6f4 v[54:57], v[2:9], v[202:209], 0
	v_mfma_f32_16x16x128_f8f6f4 v[50:53], v[10:17], v[202:209], 0
	v_mfma_f32_16x16x128_f8f6f4 v[82:85], v[26:33], v[202:209], 0
	v_mfma_f32_16x16x128_f8f6f4 v[86:89], v[18:25], v[202:209], 0
	s_setprio 0
	s_setprio 1
	v_mfma_f32_16x16x128_f8f6f4 v[78:81], v[18:25], v[210:217], 0
	v_mfma_f32_16x16x128_f8f6f4 v[74:77], v[26:33], v[210:217], 0
	v_mfma_f32_16x16x128_f8f6f4 v[42:45], v[10:17], v[210:217], 0
	v_mfma_f32_16x16x128_f8f6f4 v[46:49], v[2:9], v[210:217], 0
	s_setprio 0
	s_setprio 1
	v_mfma_f32_16x16x128_f8f6f4 v[38:41], v[2:9], v[218:225], 0
	v_mfma_f32_16x16x128_f8f6f4 v[34:37], v[10:17], v[218:225], 0
	v_mfma_f32_16x16x128_f8f6f4 v[66:69], v[26:33], v[218:225], 0
	v_mfma_f32_16x16x128_f8f6f4 v[70:73], v[18:25], v[218:225], 0
	s_barrier
	s_setprio 0
	ds_read_b128 v[18:21], v192 offset:32768
	ds_read_b128 v[22:25], v192 offset:33792
	ds_read_b128 v[26:29], v192 offset:34816
	ds_read_b128 v[30:33], v192 offset:35840
	ds_read_b128 v[2:5], v192 offset:49152
	ds_read_b128 v[6:9], v192 offset:50176
	ds_read_b128 v[10:13], v192 offset:51200
	ds_read_b128 v[14:17], v192 offset:52224
	s_add_u32 s48, s46, 0x80100
	s_addc_u32 s49, s47, 0
	s_mov_b32 m0, s68
	v_lshl_add_u64 v[226:227], s[48:49], 0, v[164:165]
	ds_read_b128 v[194:197], v193 offset:32768
	ds_read_b128 v[198:201], v193 offset:33792
	ds_read_b128 v[202:205], v193 offset:34816
	ds_read_b128 v[206:209], v193 offset:35840
	ds_read_b128 v[210:213], v193 offset:36864
	ds_read_b128 v[214:217], v193 offset:37888
	ds_read_b128 v[218:221], v193 offset:38912
	ds_read_b128 v[222:225], v193 offset:39936
	global_load_lds_dwordx4 v[226:227], off
	v_lshl_add_u64 v[226:227], s[48:49], 0, v[168:169]
	s_mov_b32 m0, s69
	s_nop 0
	global_load_lds_dwordx4 v[226:227], off
	s_waitcnt vmcnt(8)
	s_waitcnt lgkmcnt(0)
	s_setprio 1
	s_barrier
	v_mfma_f32_16x16x128_f8f6f4 v[158:161], v[18:25], v[194:201], v[158:161]
	v_mfma_f32_16x16x128_f8f6f4 v[154:157], v[26:33], v[194:201], v[154:157]
	v_mfma_f32_16x16x128_f8f6f4 v[122:125], v[10:17], v[194:201], v[122:125]
	v_mfma_f32_16x16x128_f8f6f4 v[126:129], v[2:9], v[194:201], v[126:129]
	s_setprio 0
	s_setprio 1
	v_mfma_f32_16x16x128_f8f6f4 v[118:121], v[2:9], v[202:209], v[118:121]
	v_mfma_f32_16x16x128_f8f6f4 v[114:117], v[10:17], v[202:209], v[114:117]
	v_mfma_f32_16x16x128_f8f6f4 v[146:149], v[26:33], v[202:209], v[146:149]
	v_mfma_f32_16x16x128_f8f6f4 v[150:153], v[18:25], v[202:209], v[150:153]
	s_setprio 0
	s_setprio 1
	v_mfma_f32_16x16x128_f8f6f4 v[142:145], v[18:25], v[210:217], v[142:145]
	v_mfma_f32_16x16x128_f8f6f4 v[138:141], v[26:33], v[210:217], v[138:141]
	v_mfma_f32_16x16x128_f8f6f4 v[106:109], v[10:17], v[210:217], v[106:109]
	v_mfma_f32_16x16x128_f8f6f4 v[110:113], v[2:9], v[210:217], v[110:113]
	s_setprio 0
	s_setprio 1
	v_mfma_f32_16x16x128_f8f6f4 v[102:105], v[2:9], v[218:225], v[102:105]
	v_mfma_f32_16x16x128_f8f6f4 v[98:101], v[10:17], v[218:225], v[98:101]
	v_mfma_f32_16x16x128_f8f6f4 v[130:133], v[26:33], v[218:225], v[130:133]
	v_mfma_f32_16x16x128_f8f6f4 v[134:137], v[18:25], v[218:225], v[134:137]
	s_barrier
	s_setprio 0
	s_mov_b32 m0, s74
	v_lshl_add_u64 v[184:185], v[184:185], 0, s[18:19]
	s_add_u32 s48, s44, 0x80180
	ds_read_b128 v[194:197], v193 offset:49152
	ds_read_b128 v[198:201], v193 offset:50176
	ds_read_b128 v[202:205], v193 offset:51200
	ds_read_b128 v[206:209], v193 offset:52224
	ds_read_b128 v[210:213], v193 offset:53248
	ds_read_b128 v[214:217], v193 offset:54272
	ds_read_b128 v[218:221], v193 offset:55296
	ds_read_b128 v[222:225], v193 offset:56320
	global_load_lds_dwordx4 v[184:185], off
	v_lshl_add_u64 v[184:185], v[186:187], 0, s[18:19]
	s_mov_b32 m0, s75
	s_addc_u32 s49, s45, 0
	global_load_lds_dwordx4 v[184:185], off
	v_lshl_add_u64 v[184:185], s[48:49], 0, v[166:167]
	s_mov_b32 m0, s78
	s_nop 0
	global_load_lds_dwordx4 v[184:185], off
	v_lshl_add_u64 v[184:185], s[48:49], 0, v[170:171]
	s_mov_b32 m0, s79
	s_nop 0
	global_load_lds_dwordx4 v[184:185], off
	v_lshl_add_u64 v[184:185], v[188:189], 0, s[18:19]
	s_mov_b32 m0, s76
	s_nop 0
	global_load_lds_dwordx4 v[184:185], off
	v_lshl_add_u64 v[184:185], v[190:191], 0, s[18:19]
	s_mov_b32 m0, s77
	s_nop 0
	global_load_lds_dwordx4 v[184:185], off
	s_waitcnt vmcnt(8)
	s_waitcnt lgkmcnt(0)
	s_setprio 1
	s_barrier
	v_mfma_f32_16x16x128_f8f6f4 v[94:97], v[18:25], v[194:201], v[94:97]
	v_mfma_f32_16x16x128_f8f6f4 v[90:93], v[26:33], v[194:201], v[90:93]
	v_mfma_f32_16x16x128_f8f6f4 v[58:61], v[10:17], v[194:201], v[58:61]
	v_mfma_f32_16x16x128_f8f6f4 v[62:65], v[2:9], v[194:201], v[62:65]
	s_setprio 0
	s_setprio 1
	v_mfma_f32_16x16x128_f8f6f4 v[54:57], v[2:9], v[202:209], v[54:57]
	v_mfma_f32_16x16x128_f8f6f4 v[50:53], v[10:17], v[202:209], v[50:53]
	v_mfma_f32_16x16x128_f8f6f4 v[82:85], v[26:33], v[202:209], v[82:85]
	v_mfma_f32_16x16x128_f8f6f4 v[86:89], v[18:25], v[202:209], v[86:89]
	s_setprio 0
	s_setprio 1
	v_mfma_f32_16x16x128_f8f6f4 v[78:81], v[18:25], v[210:217], v[78:81]
	v_mfma_f32_16x16x128_f8f6f4 v[74:77], v[26:33], v[210:217], v[74:77]
	v_mfma_f32_16x16x128_f8f6f4 v[42:45], v[10:17], v[210:217], v[42:45]
	v_mfma_f32_16x16x128_f8f6f4 v[46:49], v[2:9], v[210:217], v[46:49]
	s_setprio 0
	s_setprio 1
	v_mfma_f32_16x16x128_f8f6f4 v[38:41], v[2:9], v[218:225], v[38:41]
	v_mfma_f32_16x16x128_f8f6f4 v[34:37], v[10:17], v[218:225], v[34:37]
	v_mfma_f32_16x16x128_f8f6f4 v[66:69], v[26:33], v[218:225], v[66:69]
	v_mfma_f32_16x16x128_f8f6f4 v[70:73], v[18:25], v[218:225], v[70:73]
	s_barrier
	s_setprio 0
	s_add_u32 s46, s46, 0x80180
	s_addc_u32 s47, s47, 0
	s_add_u32 s62, s44, 0x200
	s_addc_u32 s63, s45, 0
	s_mov_b32 s86, 0
.LBB0_947:
	ds_read_b128 v[2:5], v192
	ds_read_b128 v[6:9], v192 offset:1024
	ds_read_b128 v[18:21], v192 offset:2048
	ds_read_b128 v[22:25], v192 offset:3072
	ds_read_b128 v[26:29], v192 offset:16384
	ds_read_b128 v[30:33], v192 offset:17408
	ds_read_b128 v[184:187], v192 offset:18432
	ds_read_b128 v[188:191], v192 offset:19456
	s_add_u32 s44, s46, 0xfff80080
	s_addc_u32 s45, s47, -1
	s_cmp_eq_u32 s86, 28
	s_cselect_b32 s49, s37, s45
	s_cselect_b32 s48, s84, s44
	s_cselect_b32 s45, s27, s63
	s_cselect_b32 s44, s85, s62
	s_mov_b32 m0, s80
	v_lshl_add_u64 v[218:219], s[46:47], 0, v[172:173]
	ds_read_b128 v[10:13], v193
	ds_read_b128 v[14:17], v193 offset:1024
	ds_read_b128 v[194:197], v193 offset:2048
	ds_read_b128 v[198:201], v193 offset:3072
	ds_read_b128 v[202:205], v193 offset:4096
	ds_read_b128 v[206:209], v193 offset:5120
	ds_read_b128 v[210:213], v193 offset:6144
	ds_read_b128 v[214:217], v193 offset:7168
	global_load_lds_dwordx4 v[218:219], off
	v_lshl_add_u64 v[218:219], s[46:47], 0, v[174:175]
	s_mov_b32 m0, s81
	s_nop 0
	global_load_lds_dwordx4 v[218:219], off
	s_waitcnt vmcnt(8)
	s_waitcnt lgkmcnt(0)
	s_setprio 1
	s_barrier
	v_mfma_f32_16x16x128_f8f6f4 v[158:161], v[2:9], v[10:17], v[158:161]
	v_mfma_f32_16x16x128_f8f6f4 v[154:157], v[18:25], v[10:17], v[154:157]
	v_mfma_f32_16x16x128_f8f6f4 v[122:125], v[184:191], v[10:17], v[122:125]
	v_mfma_f32_16x16x128_f8f6f4 v[126:129], v[26:33], v[10:17], v[126:129]
	s_setprio 0
	s_setprio 1
	v_mfma_f32_16x16x128_f8f6f4 v[118:121], v[26:33], v[194:201], v[118:121]
	v_mfma_f32_16x16x128_f8f6f4 v[114:117], v[184:191], v[194:201], v[114:117]
	v_mfma_f32_16x16x128_f8f6f4 v[146:149], v[18:25], v[194:201], v[146:149]
	v_mfma_f32_16x16x128_f8f6f4 v[150:153], v[2:9], v[194:201], v[150:153]
	s_setprio 0
	s_setprio 1
	v_mfma_f32_16x16x128_f8f6f4 v[142:145], v[2:9], v[202:209], v[142:145]
	v_mfma_f32_16x16x128_f8f6f4 v[138:141], v[18:25], v[202:209], v[138:141]
	v_mfma_f32_16x16x128_f8f6f4 v[106:109], v[184:191], v[202:209], v[106:109]
	v_mfma_f32_16x16x128_f8f6f4 v[110:113], v[26:33], v[202:209], v[110:113]
	s_setprio 0
	s_setprio 1
	v_mfma_f32_16x16x128_f8f6f4 v[102:105], v[26:33], v[210:217], v[102:105]
	v_mfma_f32_16x16x128_f8f6f4 v[98:101], v[184:191], v[210:217], v[98:101]
	v_mfma_f32_16x16x128_f8f6f4 v[130:133], v[18:25], v[210:217], v[130:133]
	v_mfma_f32_16x16x128_f8f6f4 v[134:137], v[2:9], v[210:217], v[134:137]
	s_barrier
	s_setprio 0
	s_mov_b32 m0, s52
	v_lshl_add_u64 v[10:11], s[44:45], 0, v[166:167]
	s_add_u32 s88, s44, 0x80000
	ds_read_b128 v[194:197], v193 offset:16384
	ds_read_b128 v[198:201], v193 offset:17408
	ds_read_b128 v[202:205], v193 offset:18432
	ds_read_b128 v[206:209], v193 offset:19456
	ds_read_b128 v[210:213], v193 offset:20480
	ds_read_b128 v[214:217], v193 offset:21504
	ds_read_b128 v[218:221], v193 offset:22528
	ds_read_b128 v[222:225], v193 offset:23552
	global_load_lds_dwordx4 v[10:11], off
	v_lshl_add_u64 v[12:13], s[44:45], 0, v[170:171]
	s_mov_b32 m0, s53
	s_addc_u32 s89, s45, 0
	global_load_lds_dwordx4 v[12:13], off
	v_lshl_add_u64 v[14:15], s[88:89], 0, v[166:167]
	s_mov_b32 m0, s54
	v_lshl_add_u64 v[16:17], s[48:49], 0, v[168:169]
	global_load_lds_dwordx4 v[14:15], off
	v_lshl_add_u64 v[14:15], s[88:89], 0, v[170:171]
	s_mov_b32 m0, s55
	s_nop 0
	global_load_lds_dwordx4 v[14:15], off
	v_lshl_add_u64 v[14:15], s[48:49], 0, v[164:165]
	s_mov_b32 m0, s43
	s_nop 0
	global_load_lds_dwordx4 v[14:15], off
	s_mov_b32 m0, s61
	s_nop 0
	global_load_lds_dwordx4 v[16:17], off
	s_waitcnt vmcnt(8)
	s_waitcnt lgkmcnt(0)
	s_setprio 1
	s_barrier
	v_mfma_f32_16x16x128_f8f6f4 v[94:97], v[2:9], v[194:201], v[94:97]
	v_mfma_f32_16x16x128_f8f6f4 v[90:93], v[18:25], v[194:201], v[90:93]
	v_mfma_f32_16x16x128_f8f6f4 v[58:61], v[184:191], v[194:201], v[58:61]
	v_mfma_f32_16x16x128_f8f6f4 v[62:65], v[26:33], v[194:201], v[62:65]
	s_setprio 0
	s_setprio 1
	v_mfma_f32_16x16x128_f8f6f4 v[54:57], v[26:33], v[202:209], v[54:57]
	v_mfma_f32_16x16x128_f8f6f4 v[50:53], v[184:191], v[202:209], v[50:53]
	v_mfma_f32_16x16x128_f8f6f4 v[82:85], v[18:25], v[202:209], v[82:85]
	v_mfma_f32_16x16x128_f8f6f4 v[86:89], v[2:9], v[202:209], v[86:89]
	s_setprio 0
	s_setprio 1
	v_mfma_f32_16x16x128_f8f6f4 v[78:81], v[2:9], v[210:217], v[78:81]
	v_mfma_f32_16x16x128_f8f6f4 v[74:77], v[18:25], v[210:217], v[74:77]
	v_mfma_f32_16x16x128_f8f6f4 v[42:45], v[184:191], v[210:217], v[42:45]
	v_mfma_f32_16x16x128_f8f6f4 v[46:49], v[26:33], v[210:217], v[46:49]
	s_setprio 0
	s_setprio 1
	v_mfma_f32_16x16x128_f8f6f4 v[38:41], v[26:33], v[218:225], v[38:41]
	v_mfma_f32_16x16x128_f8f6f4 v[34:37], v[184:191], v[218:225], v[34:37]
	v_mfma_f32_16x16x128_f8f6f4 v[66:69], v[18:25], v[218:225], v[66:69]
	v_mfma_f32_16x16x128_f8f6f4 v[70:73], v[2:9], v[218:225], v[70:73]
	s_barrier
	s_setprio 0
	ds_read_b128 v[18:21], v192 offset:32768
	ds_read_b128 v[22:25], v192 offset:33792
	ds_read_b128 v[26:29], v192 offset:34816
	ds_read_b128 v[30:33], v192 offset:35840
	ds_read_b128 v[2:5], v192 offset:49152
	ds_read_b128 v[6:9], v192 offset:50176
	ds_read_b128 v[184:187], v192 offset:51200
	ds_read_b128 v[188:191], v192 offset:52224
	s_add_u32 s48, s48, 0x80000
	s_addc_u32 s49, s49, 0
	s_mov_b32 m0, s68
	v_lshl_add_u64 v[226:227], s[48:49], 0, v[164:165]
	ds_read_b128 v[194:197], v193 offset:32768
	ds_read_b128 v[198:201], v193 offset:33792
	ds_read_b128 v[202:205], v193 offset:34816
	ds_read_b128 v[206:209], v193 offset:35840
	ds_read_b128 v[210:213], v193 offset:36864
	ds_read_b128 v[214:217], v193 offset:37888
	ds_read_b128 v[218:221], v193 offset:38912
	ds_read_b128 v[222:225], v193 offset:39936
	global_load_lds_dwordx4 v[226:227], off
	v_lshl_add_u64 v[226:227], s[48:49], 0, v[168:169]
	s_mov_b32 m0, s69
	s_nop 0
	global_load_lds_dwordx4 v[226:227], off
	s_waitcnt vmcnt(8)
	s_waitcnt lgkmcnt(0)
	s_setprio 1
	s_barrier
	v_mfma_f32_16x16x128_f8f6f4 v[158:161], v[18:25], v[194:201], v[158:161]
	v_mfma_f32_16x16x128_f8f6f4 v[154:157], v[26:33], v[194:201], v[154:157]
	v_mfma_f32_16x16x128_f8f6f4 v[122:125], v[184:191], v[194:201], v[122:125]
	v_mfma_f32_16x16x128_f8f6f4 v[126:129], v[2:9], v[194:201], v[126:129]
	s_setprio 0
	s_setprio 1
	v_mfma_f32_16x16x128_f8f6f4 v[118:121], v[2:9], v[202:209], v[118:121]
	v_mfma_f32_16x16x128_f8f6f4 v[114:117], v[184:191], v[202:209], v[114:117]
	v_mfma_f32_16x16x128_f8f6f4 v[146:149], v[26:33], v[202:209], v[146:149]
	v_mfma_f32_16x16x128_f8f6f4 v[150:153], v[18:25], v[202:209], v[150:153]
	s_setprio 0
	s_setprio 1
	v_mfma_f32_16x16x128_f8f6f4 v[142:145], v[18:25], v[210:217], v[142:145]
	v_mfma_f32_16x16x128_f8f6f4 v[138:141], v[26:33], v[210:217], v[138:141]
	v_mfma_f32_16x16x128_f8f6f4 v[106:109], v[184:191], v[210:217], v[106:109]
	v_mfma_f32_16x16x128_f8f6f4 v[110:113], v[2:9], v[210:217], v[110:113]
	s_setprio 0
	s_setprio 1
	v_mfma_f32_16x16x128_f8f6f4 v[102:105], v[2:9], v[218:225], v[102:105]
	v_mfma_f32_16x16x128_f8f6f4 v[98:101], v[184:191], v[218:225], v[98:101]
	v_mfma_f32_16x16x128_f8f6f4 v[130:133], v[26:33], v[218:225], v[130:133]
	v_mfma_f32_16x16x128_f8f6f4 v[134:137], v[18:25], v[218:225], v[134:137]
	s_barrier
	s_setprio 0
	s_mov_b32 m0, s74
	v_lshl_add_u64 v[10:11], v[10:11], 0, s[4:5]
	s_add_u32 s44, s44, 0x80080
	ds_read_b128 v[194:197], v193 offset:49152
	ds_read_b128 v[198:201], v193 offset:50176
	ds_read_b128 v[202:205], v193 offset:51200
	ds_read_b128 v[206:209], v193 offset:52224
	ds_read_b128 v[210:213], v193 offset:53248
	ds_read_b128 v[214:217], v193 offset:54272
	ds_read_b128 v[218:221], v193 offset:55296
	ds_read_b128 v[222:225], v193 offset:56320
	global_load_lds_dwordx4 v[10:11], off
	v_lshl_add_u64 v[10:11], v[12:13], 0, s[4:5]
	s_mov_b32 m0, s75
	s_addc_u32 s45, s45, 0
	global_load_lds_dwordx4 v[10:11], off
	v_lshl_add_u64 v[10:11], s[44:45], 0, v[166:167]
	s_mov_b32 m0, s78
	s_nop 0
	global_load_lds_dwordx4 v[10:11], off
	v_lshl_add_u64 v[10:11], s[44:45], 0, v[170:171]
	s_mov_b32 m0, s79
	s_nop 0
	global_load_lds_dwordx4 v[10:11], off
	v_lshl_add_u64 v[10:11], v[14:15], 0, s[4:5]
	s_mov_b32 m0, s76
	s_nop 0
	global_load_lds_dwordx4 v[10:11], off
	v_lshl_add_u64 v[10:11], v[16:17], 0, s[4:5]
	s_mov_b32 m0, s77
	s_nop 0
	global_load_lds_dwordx4 v[10:11], off
	s_waitcnt vmcnt(8)
	s_waitcnt lgkmcnt(0)
	s_setprio 1
	s_barrier
	v_mfma_f32_16x16x128_f8f6f4 v[94:97], v[18:25], v[194:201], v[94:97]
	v_mfma_f32_16x16x128_f8f6f4 v[90:93], v[26:33], v[194:201], v[90:93]
	v_mfma_f32_16x16x128_f8f6f4 v[58:61], v[184:191], v[194:201], v[58:61]
	v_mfma_f32_16x16x128_f8f6f4 v[62:65], v[2:9], v[194:201], v[62:65]
	s_setprio 0
	s_setprio 1
	v_mfma_f32_16x16x128_f8f6f4 v[54:57], v[2:9], v[202:209], v[54:57]
	v_mfma_f32_16x16x128_f8f6f4 v[50:53], v[184:191], v[202:209], v[50:53]
	v_mfma_f32_16x16x128_f8f6f4 v[82:85], v[26:33], v[202:209], v[82:85]
	v_mfma_f32_16x16x128_f8f6f4 v[86:89], v[18:25], v[202:209], v[86:89]
	s_setprio 0
	s_setprio 1
	v_mfma_f32_16x16x128_f8f6f4 v[78:81], v[18:25], v[210:217], v[78:81]
	v_mfma_f32_16x16x128_f8f6f4 v[74:77], v[26:33], v[210:217], v[74:77]
	v_mfma_f32_16x16x128_f8f6f4 v[42:45], v[184:191], v[210:217], v[42:45]
	v_mfma_f32_16x16x128_f8f6f4 v[46:49], v[2:9], v[210:217], v[46:49]
	s_setprio 0
	s_setprio 1
	v_mfma_f32_16x16x128_f8f6f4 v[38:41], v[2:9], v[218:225], v[38:41]
	v_mfma_f32_16x16x128_f8f6f4 v[34:37], v[184:191], v[218:225], v[34:37]
	v_mfma_f32_16x16x128_f8f6f4 v[66:69], v[26:33], v[218:225], v[66:69]
	v_mfma_f32_16x16x128_f8f6f4 v[70:73], v[18:25], v[218:225], v[70:73]
	s_barrier
	s_setprio 0
	s_add_i32 s86, s86, 2
	s_add_u32 s46, s46, 0x100
	s_addc_u32 s47, s47, 0
	s_add_u32 s62, s62, 0x100
	s_addc_u32 s63, s63, 0
	s_cmp_gt_u32 s86, 29
	s_cbranch_scc0 .LBB0_947
	s_and_b64 vcc, exec, s[6:7]
	s_cbranch_vccz .LBB0_950
	s_barrier

.LBB0_1031:
	ds_read_b128 v[2:5], v189
	ds_read_b128 v[6:9], v189 offset:1024
	ds_read_b128 v[192:195], v189 offset:2048
	ds_read_b128 v[196:199], v189 offset:3072
	ds_read_b128 v[200:203], v189 offset:16384
	ds_read_b128 v[204:207], v189 offset:17408
	ds_read_b128 v[208:211], v189 offset:18432
	ds_read_b128 v[212:215], v189 offset:19456
	s_add_u32 s25, s36, 0x100
	s_addc_u32 s83, s37, 0
	s_and_b64 s[40:41], s[38:39], exec
	s_cselect_b32 s41, s1, s83
	s_cselect_b32 s40, s0, s25
	s_add_u32 s25, s26, 0x100
	s_addc_u32 s83, s27, 0
	s_and_b64 s[38:39], s[38:39], exec
	s_cselect_b32 s39, s5, s83
	s_cselect_b32 s38, s4, s25
	s_add_u32 s84, s36, 0x158080
	s_addc_u32 s85, s37, 0
	s_add_i32 s25, s23, 0xc000
	v_lshl_add_u64 v[174:175], s[84:85], 0, v[154:155]
	s_mov_b32 m0, s25
	s_add_i32 s83, s23, 0xe000
	ds_read_b128 v[216:219], v190
	ds_read_b128 v[220:223], v190 offset:1024
	ds_read_b128 v[224:227], v190 offset:2048
	ds_read_b128 v[228:231], v190 offset:3072
	ds_read_b128 v[232:235], v190 offset:4096
	ds_read_b128 v[236:239], v190 offset:5120
	ds_read_b128 v[240:243], v190 offset:6144
	ds_read_b128 v[244:247], v190 offset:7168
	global_load_lds_dwordx4 v[174:175], off
	v_lshl_add_u64 v[174:175], s[84:85], 0, v[158:159]
	s_mov_b32 m0, s83
	s_nop 0
	global_load_lds_dwordx4 v[174:175], off
	s_waitcnt vmcnt(8)
	s_waitcnt lgkmcnt(0)
	s_setprio 1
	s_barrier
	v_mfma_f32_16x16x128_f8f6f4 v[134:137], v[2:9], v[216:223], 0
	v_mfma_f32_16x16x128_f8f6f4 v[130:133], v[192:199], v[216:223], 0
	v_mfma_f32_16x16x128_f8f6f4 v[98:101], v[208:215], v[216:223], 0
	v_mfma_f32_16x16x128_f8f6f4 v[102:105], v[200:207], v[216:223], 0
	s_setprio 0
	s_setprio 1
	v_mfma_f32_16x16x128_f8f6f4 v[94:97], v[200:207], v[224:231], 0
	v_mfma_f32_16x16x128_f8f6f4 v[90:93], v[208:215], v[224:231], 0
	v_mfma_f32_16x16x128_f8f6f4 v[122:125], v[192:199], v[224:231], 0
	v_mfma_f32_16x16x128_f8f6f4 v[126:129], v[2:9], v[224:231], 0
	s_setprio 0
	s_setprio 1
	v_mfma_f32_16x16x128_f8f6f4 v[118:121], v[2:9], v[232:239], 0
	v_mfma_f32_16x16x128_f8f6f4 v[114:117], v[192:199], v[232:239], 0
	v_mfma_f32_16x16x128_f8f6f4 v[82:85], v[208:215], v[232:239], 0
	v_mfma_f32_16x16x128_f8f6f4 v[86:89], v[200:207], v[232:239], 0
	s_setprio 0
	s_setprio 1
	v_mfma_f32_16x16x128_f8f6f4 v[78:81], v[200:207], v[240:247], 0
	v_mfma_f32_16x16x128_f8f6f4 v[74:77], v[208:215], v[240:247], 0
	v_mfma_f32_16x16x128_f8f6f4 v[106:109], v[192:199], v[240:247], 0
	v_mfma_f32_16x16x128_f8f6f4 v[110:113], v[2:9], v[240:247], 0
	s_barrier
	s_setprio 0
	s_mov_b32 m0, s33
	v_lshl_add_u64 v[174:175], s[38:39], 0, v[156:157]
	s_add_u32 s84, s38, 0x158000
	ds_read_b128 v[216:219], v190 offset:16384
	ds_read_b128 v[220:223], v190 offset:17408
	ds_read_b128 v[224:227], v190 offset:18432
	ds_read_b128 v[228:231], v190 offset:19456
	ds_read_b128 v[232:235], v190 offset:20480
	ds_read_b128 v[236:239], v190 offset:21504
	ds_read_b128 v[240:243], v190 offset:22528
	ds_read_b128 v[244:247], v190 offset:23552
	global_load_lds_dwordx4 v[174:175], off
	v_lshl_add_u64 v[176:177], s[38:39], 0, v[160:161]
	s_mov_b32 m0, s35
	s_addc_u32 s85, s39, 0
	global_load_lds_dwordx4 v[176:177], off
	v_lshl_add_u64 v[182:183], s[84:85], 0, v[156:157]
	s_mov_b32 m0, s42
	v_lshl_add_u64 v[184:185], s[40:41], 0, v[158:159]
	global_load_lds_dwordx4 v[182:183], off
	v_lshl_add_u64 v[182:183], s[84:85], 0, v[160:161]
	s_mov_b32 m0, s43
	s_nop 0
	global_load_lds_dwordx4 v[182:183], off
	v_lshl_add_u64 v[182:183], s[40:41], 0, v[154:155]
	s_mov_b32 m0, s23
	s_nop 0
	global_load_lds_dwordx4 v[182:183], off
	s_mov_b32 m0, s44
	s_nop 0
	global_load_lds_dwordx4 v[184:185], off
	s_waitcnt vmcnt(8)
	s_waitcnt lgkmcnt(0)
	s_setprio 1
	s_barrier
	v_mfma_f32_16x16x128_f8f6f4 v[70:73], v[2:9], v[216:223], 0
	v_mfma_f32_16x16x128_f8f6f4 v[66:69], v[192:199], v[216:223], 0
	v_mfma_f32_16x16x128_f8f6f4 v[34:37], v[208:215], v[216:223], 0
	v_mfma_f32_16x16x128_f8f6f4 v[38:41], v[200:207], v[216:223], 0
	s_setprio 0
	s_setprio 1
	v_mfma_f32_16x16x128_f8f6f4 v[30:33], v[200:207], v[224:231], 0
	v_mfma_f32_16x16x128_f8f6f4 v[26:29], v[208:215], v[224:231], 0
	v_mfma_f32_16x16x128_f8f6f4 v[58:61], v[192:199], v[224:231], 0
	v_mfma_f32_16x16x128_f8f6f4 v[62:65], v[2:9], v[224:231], 0
	s_setprio 0
	s_setprio 1
	v_mfma_f32_16x16x128_f8f6f4 v[54:57], v[2:9], v[232:239], 0
	v_mfma_f32_16x16x128_f8f6f4 v[50:53], v[192:199], v[232:239], 0
	v_mfma_f32_16x16x128_f8f6f4 v[18:21], v[208:215], v[232:239], 0
	v_mfma_f32_16x16x128_f8f6f4 v[22:25], v[200:207], v[232:239], 0
	s_setprio 0
	s_setprio 1
	v_mfma_f32_16x16x128_f8f6f4 v[14:17], v[200:207], v[240:247], 0
	v_mfma_f32_16x16x128_f8f6f4 v[10:13], v[208:215], v[240:247], 0
	v_mfma_f32_16x16x128_f8f6f4 v[42:45], v[192:199], v[240:247], 0
	v_mfma_f32_16x16x128_f8f6f4 v[46:49], v[2:9], v[240:247], 0
	s_barrier
	s_setprio 0
	ds_read_b128 v[2:5], v189 offset:32768
	ds_read_b128 v[6:9], v189 offset:33792
	ds_read_b128 v[192:195], v189 offset:34816
	ds_read_b128 v[196:199], v189 offset:35840
	ds_read_b128 v[200:203], v189 offset:49152
	ds_read_b128 v[204:207], v189 offset:50176
	ds_read_b128 v[208:211], v189 offset:51200
	ds_read_b128 v[212:215], v189 offset:52224
	s_add_u32 s40, s40, 0x158000
	s_addc_u32 s41, s41, 0
	s_mov_b32 m0, s45
	v_lshl_add_u64 v[186:187], s[40:41], 0, v[154:155]
	ds_read_b128 v[216:219], v190 offset:32768
	ds_read_b128 v[220:223], v190 offset:33792
	ds_read_b128 v[224:227], v190 offset:34816
	ds_read_b128 v[228:231], v190 offset:35840
	ds_read_b128 v[232:235], v190 offset:36864
	ds_read_b128 v[236:239], v190 offset:37888
	ds_read_b128 v[240:243], v190 offset:38912
	ds_read_b128 v[244:247], v190 offset:39936
	global_load_lds_dwordx4 v[186:187], off
	v_lshl_add_u64 v[186:187], s[40:41], 0, v[158:159]
	s_mov_b32 m0, s46
	s_nop 0
	global_load_lds_dwordx4 v[186:187], off
	s_waitcnt vmcnt(8)
	s_waitcnt lgkmcnt(0)
	s_setprio 1
	s_barrier
	v_mfma_f32_16x16x128_f8f6f4 v[134:137], v[2:9], v[216:223], v[134:137]
	v_mfma_f32_16x16x128_f8f6f4 v[130:133], v[192:199], v[216:223], v[130:133]
	v_mfma_f32_16x16x128_f8f6f4 v[98:101], v[208:215], v[216:223], v[98:101]
	v_mfma_f32_16x16x128_f8f6f4 v[102:105], v[200:207], v[216:223], v[102:105]
	s_setprio 0
	s_setprio 1
	v_mfma_f32_16x16x128_f8f6f4 v[94:97], v[200:207], v[224:231], v[94:97]
	v_mfma_f32_16x16x128_f8f6f4 v[90:93], v[208:215], v[224:231], v[90:93]
	v_mfma_f32_16x16x128_f8f6f4 v[122:125], v[192:199], v[224:231], v[122:125]
	v_mfma_f32_16x16x128_f8f6f4 v[126:129], v[2:9], v[224:231], v[126:129]
	s_setprio 0
	s_setprio 1
	v_mfma_f32_16x16x128_f8f6f4 v[118:121], v[2:9], v[232:239], v[118:121]
	v_mfma_f32_16x16x128_f8f6f4 v[114:117], v[192:199], v[232:239], v[114:117]
	v_mfma_f32_16x16x128_f8f6f4 v[82:85], v[208:215], v[232:239], v[82:85]
	v_mfma_f32_16x16x128_f8f6f4 v[86:89], v[200:207], v[232:239], v[86:89]
	s_setprio 0
	s_setprio 1
	v_mfma_f32_16x16x128_f8f6f4 v[78:81], v[200:207], v[240:247], v[78:81]
	v_mfma_f32_16x16x128_f8f6f4 v[74:77], v[208:215], v[240:247], v[74:77]
	v_mfma_f32_16x16x128_f8f6f4 v[106:109], v[192:199], v[240:247], v[106:109]
	v_mfma_f32_16x16x128_f8f6f4 v[110:113], v[2:9], v[240:247], v[110:113]
	s_barrier
	s_setprio 0
	s_mov_b32 m0, s52
	v_lshl_add_u64 v[174:175], v[174:175], 0, s[14:15]
	s_add_u32 s38, s38, 0x158080
	ds_read_b128 v[216:219], v190 offset:49152
	ds_read_b128 v[220:223], v190 offset:50176
	ds_read_b128 v[224:227], v190 offset:51200
	ds_read_b128 v[228:231], v190 offset:52224
	ds_read_b128 v[232:235], v190 offset:53248
	ds_read_b128 v[236:239], v190 offset:54272
	ds_read_b128 v[240:243], v190 offset:55296
	ds_read_b128 v[244:247], v190 offset:56320
	global_load_lds_dwordx4 v[174:175], off
	v_lshl_add_u64 v[174:175], v[176:177], 0, s[14:15]
	s_mov_b32 m0, s53
	s_addc_u32 s39, s39, 0
	global_load_lds_dwordx4 v[174:175], off
	v_lshl_add_u64 v[174:175], s[38:39], 0, v[156:157]
	s_mov_b32 m0, s56
	s_nop 0
	global_load_lds_dwordx4 v[174:175], off
	v_lshl_add_u64 v[174:175], s[38:39], 0, v[160:161]
	s_mov_b32 m0, s57
	s_nop 0
	global_load_lds_dwordx4 v[174:175], off
	v_lshl_add_u64 v[174:175], v[182:183], 0, s[14:15]
	s_mov_b32 m0, s54
	s_nop 0
	global_load_lds_dwordx4 v[174:175], off
	v_lshl_add_u64 v[174:175], v[184:185], 0, s[14:15]
	s_mov_b32 m0, s55
	s_nop 0
	global_load_lds_dwordx4 v[174:175], off
	s_waitcnt vmcnt(8)
	s_waitcnt lgkmcnt(0)
	s_setprio 1
	s_barrier
	v_mfma_f32_16x16x128_f8f6f4 v[70:73], v[2:9], v[216:223], v[70:73]
	v_mfma_f32_16x16x128_f8f6f4 v[66:69], v[192:199], v[216:223], v[66:69]
	v_mfma_f32_16x16x128_f8f6f4 v[34:37], v[208:215], v[216:223], v[34:37]
	v_mfma_f32_16x16x128_f8f6f4 v[38:41], v[200:207], v[216:223], v[38:41]
	s_setprio 0
	s_setprio 1
	v_mfma_f32_16x16x128_f8f6f4 v[30:33], v[200:207], v[224:231], v[30:33]
	v_mfma_f32_16x16x128_f8f6f4 v[26:29], v[208:215], v[224:231], v[26:29]
	v_mfma_f32_16x16x128_f8f6f4 v[58:61], v[192:199], v[224:231], v[58:61]
	v_mfma_f32_16x16x128_f8f6f4 v[62:65], v[2:9], v[224:231], v[62:65]
	s_setprio 0
	s_setprio 1
	v_mfma_f32_16x16x128_f8f6f4 v[54:57], v[2:9], v[232:239], v[54:57]
	v_mfma_f32_16x16x128_f8f6f4 v[50:53], v[192:199], v[232:239], v[50:53]
	v_mfma_f32_16x16x128_f8f6f4 v[18:21], v[208:215], v[232:239], v[18:21]
	v_mfma_f32_16x16x128_f8f6f4 v[22:25], v[200:207], v[232:239], v[22:25]
	s_setprio 0
	s_setprio 1
	v_mfma_f32_16x16x128_f8f6f4 v[14:17], v[200:207], v[240:247], v[14:17]
	v_mfma_f32_16x16x128_f8f6f4 v[10:13], v[208:215], v[240:247], v[10:13]
	v_mfma_f32_16x16x128_f8f6f4 v[42:45], v[192:199], v[240:247], v[42:45]
	v_mfma_f32_16x16x128_f8f6f4 v[46:49], v[2:9], v[240:247], v[46:49]
	s_barrier
	s_setprio 0
	s_cmp_lt_u32 s82, 3
	s_cbranch_scc1 .LBB0_1036
	s_add_u32 s38, s48, s63
	s_addc_u32 s39, s49, s62
	s_add_u32 s36, s36, 0x158180
	s_addc_u32 s37, s37, 0
	s_add_u32 s40, s26, 0x200
	v_lshl_add_u64 v[174:175], v[172:173], 2, s[38:39]
	s_addc_u32 s41, s27, 0
	s_mov_b32 s84, 4
	s_cmp_eq_u32 s82, s84
	s_cselect_b64 s[26:27], -1, 0
	s_cmp_lg_u32 s82, s84
	s_cbranch_scc1 .LBB0_1034

.LBB0_1034:
	ds_read_b128 v[2:5], v189
	ds_read_b128 v[6:9], v189 offset:1024
	ds_read_b128 v[192:195], v189 offset:2048
	ds_read_b128 v[196:199], v189 offset:3072
	ds_read_b128 v[200:203], v189 offset:16384
	ds_read_b128 v[204:207], v189 offset:17408
	ds_read_b128 v[208:211], v189 offset:18432
	ds_read_b128 v[212:215], v189 offset:19456
	s_add_u32 s38, s36, 0xffea8080
	s_addc_u32 s39, s37, -1
	s_and_b64 s[26:27], s[26:27], exec
	s_cselect_b32 s26, s4, s40
	s_cselect_b32 s39, s1, s39
	s_cselect_b32 s38, s0, s38
	s_cselect_b32 s27, s5, s41
	s_mov_b32 m0, s25
	v_lshl_add_u64 v[176:177], s[36:37], 0, v[162:163]
	ds_read_b128 v[216:219], v190
	ds_read_b128 v[220:223], v190 offset:1024
	ds_read_b128 v[224:227], v190 offset:2048
	ds_read_b128 v[228:231], v190 offset:3072
	ds_read_b128 v[232:235], v190 offset:4096
	ds_read_b128 v[236:239], v190 offset:5120
	ds_read_b128 v[240:243], v190 offset:6144
	ds_read_b128 v[244:247], v190 offset:7168
	global_load_lds_dwordx4 v[176:177], off
	v_lshl_add_u64 v[176:177], s[36:37], 0, v[164:165]
	s_mov_b32 m0, s83
	s_nop 0
	global_load_lds_dwordx4 v[176:177], off
	s_waitcnt vmcnt(8)
	s_waitcnt lgkmcnt(0)
	s_setprio 1
	s_barrier
	v_mfma_f32_16x16x128_f8f6f4 v[134:137], v[2:9], v[216:223], v[134:137]
	v_mfma_f32_16x16x128_f8f6f4 v[130:133], v[192:199], v[216:223], v[130:133]
	v_mfma_f32_16x16x128_f8f6f4 v[98:101], v[208:215], v[216:223], v[98:101]
	v_mfma_f32_16x16x128_f8f6f4 v[102:105], v[200:207], v[216:223], v[102:105]
	s_setprio 0
	s_setprio 1
	v_mfma_f32_16x16x128_f8f6f4 v[94:97], v[200:207], v[224:231], v[94:97]
	v_mfma_f32_16x16x128_f8f6f4 v[90:93], v[208:215], v[224:231], v[90:93]
	v_mfma_f32_16x16x128_f8f6f4 v[122:125], v[192:199], v[224:231], v[122:125]
	v_mfma_f32_16x16x128_f8f6f4 v[126:129], v[2:9], v[224:231], v[126:129]
	s_setprio 0
	s_setprio 1
	v_mfma_f32_16x16x128_f8f6f4 v[118:121], v[2:9], v[232:239], v[118:121]
	v_mfma_f32_16x16x128_f8f6f4 v[114:117], v[192:199], v[232:239], v[114:117]
	v_mfma_f32_16x16x128_f8f6f4 v[82:85], v[208:215], v[232:239], v[82:85]
	v_mfma_f32_16x16x128_f8f6f4 v[86:89], v[200:207], v[232:239], v[86:89]
	s_setprio 0
	s_setprio 1
	v_mfma_f32_16x16x128_f8f6f4 v[78:81], v[200:207], v[240:247], v[78:81]
	v_mfma_f32_16x16x128_f8f6f4 v[74:77], v[208:215], v[240:247], v[74:77]
	v_mfma_f32_16x16x128_f8f6f4 v[106:109], v[192:199], v[240:247], v[106:109]
	v_mfma_f32_16x16x128_f8f6f4 v[110:113], v[2:9], v[240:247], v[110:113]
	s_barrier
	s_setprio 0
	s_mov_b32 m0, s33
	v_lshl_add_u64 v[176:177], s[26:27], 0, v[156:157]
	s_add_u32 s62, s26, 0x158000
	ds_read_b128 v[216:219], v190 offset:16384
	ds_read_b128 v[220:223], v190 offset:17408
	ds_read_b128 v[224:227], v190 offset:18432
	ds_read_b128 v[228:231], v190 offset:19456
	ds_read_b128 v[232:235], v190 offset:20480
	ds_read_b128 v[236:239], v190 offset:21504
	ds_read_b128 v[240:243], v190 offset:22528
	ds_read_b128 v[244:247], v190 offset:23552
	global_load_lds_dwordx4 v[176:177], off
	v_lshl_add_u64 v[182:183], s[26:27], 0, v[160:161]
	s_mov_b32 m0, s35
	s_addc_u32 s63, s27, 0
	global_load_lds_dwordx4 v[182:183], off
	v_lshl_add_u64 v[184:185], s[62:63], 0, v[156:157]
	s_mov_b32 m0, s42
	v_lshl_add_u64 v[186:187], s[38:39], 0, v[158:159]
	global_load_lds_dwordx4 v[184:185], off
	v_lshl_add_u64 v[184:185], s[62:63], 0, v[160:161]
	s_mov_b32 m0, s43
	s_nop 0
	global_load_lds_dwordx4 v[184:185], off
	v_lshl_add_u64 v[184:185], s[38:39], 0, v[154:155]
	s_mov_b32 m0, s23
	s_nop 0
	global_load_lds_dwordx4 v[184:185], off
	s_mov_b32 m0, s44
	s_nop 0
	global_load_lds_dwordx4 v[186:187], off
	s_waitcnt vmcnt(8)
	s_waitcnt lgkmcnt(0)
	s_setprio 1
	s_barrier
	v_mfma_f32_16x16x128_f8f6f4 v[70:73], v[2:9], v[216:223], v[70:73]
	v_mfma_f32_16x16x128_f8f6f4 v[66:69], v[192:199], v[216:223], v[66:69]
	v_mfma_f32_16x16x128_f8f6f4 v[34:37], v[208:215], v[216:223], v[34:37]
	v_mfma_f32_16x16x128_f8f6f4 v[38:41], v[200:207], v[216:223], v[38:41]
	s_setprio 0
	s_setprio 1
	v_mfma_f32_16x16x128_f8f6f4 v[30:33], v[200:207], v[224:231], v[30:33]
	v_mfma_f32_16x16x128_f8f6f4 v[26:29], v[208:215], v[224:231], v[26:29]
	v_mfma_f32_16x16x128_f8f6f4 v[58:61], v[192:199], v[224:231], v[58:61]
	v_mfma_f32_16x16x128_f8f6f4 v[62:65], v[2:9], v[224:231], v[62:65]
	s_setprio 0
	s_setprio 1
	v_mfma_f32_16x16x128_f8f6f4 v[54:57], v[2:9], v[232:239], v[54:57]
	v_mfma_f32_16x16x128_f8f6f4 v[50:53], v[192:199], v[232:239], v[50:53]
	v_mfma_f32_16x16x128_f8f6f4 v[18:21], v[208:215], v[232:239], v[18:21]
	v_mfma_f32_16x16x128_f8f6f4 v[22:25], v[200:207], v[232:239], v[22:25]
	s_setprio 0
	s_setprio 1
	v_mfma_f32_16x16x128_f8f6f4 v[14:17], v[200:207], v[240:247], v[14:17]
	v_mfma_f32_16x16x128_f8f6f4 v[10:13], v[208:215], v[240:247], v[10:13]
	v_mfma_f32_16x16x128_f8f6f4 v[42:45], v[192:199], v[240:247], v[42:45]
	v_mfma_f32_16x16x128_f8f6f4 v[46:49], v[2:9], v[240:247], v[46:49]
	s_barrier
	s_setprio 0
	ds_read_b128 v[192:195], v189 offset:32768
	ds_read_b128 v[196:199], v189 offset:33792
	ds_read_b128 v[200:203], v189 offset:34816
	ds_read_b128 v[204:207], v189 offset:35840
	ds_read_b128 v[2:5], v189 offset:49152
	ds_read_b128 v[6:9], v189 offset:50176
	ds_read_b128 v[208:211], v189 offset:51200
	ds_read_b128 v[212:215], v189 offset:52224
	s_add_u32 s38, s38, 0x158000
	s_addc_u32 s39, s39, 0
	s_mov_b32 m0, s45
	v_lshl_add_u64 v[248:249], s[38:39], 0, v[154:155]
	ds_read_b128 v[216:219], v190 offset:32768
	ds_read_b128 v[220:223], v190 offset:33792
	ds_read_b128 v[224:227], v190 offset:34816
	ds_read_b128 v[228:231], v190 offset:35840
	ds_read_b128 v[232:235], v190 offset:36864
	ds_read_b128 v[236:239], v190 offset:37888
	ds_read_b128 v[240:243], v190 offset:38912
	ds_read_b128 v[244:247], v190 offset:39936
	global_load_lds_dwordx4 v[248:249], off
	v_lshl_add_u64 v[248:249], s[38:39], 0, v[158:159]
	s_mov_b32 m0, s46
	s_nop 0
	global_load_lds_dwordx4 v[248:249], off
	s_waitcnt vmcnt(8)
	s_waitcnt lgkmcnt(0)
	s_setprio 1
	s_barrier
	v_mfma_f32_16x16x128_f8f6f4 v[134:137], v[192:199], v[216:223], v[134:137]
	v_mfma_f32_16x16x128_f8f6f4 v[130:133], v[200:207], v[216:223], v[130:133]
	v_mfma_f32_16x16x128_f8f6f4 v[98:101], v[208:215], v[216:223], v[98:101]
	v_mfma_f32_16x16x128_f8f6f4 v[102:105], v[2:9], v[216:223], v[102:105]
	s_setprio 0
	s_setprio 1
	v_mfma_f32_16x16x128_f8f6f4 v[94:97], v[2:9], v[224:231], v[94:97]
	v_mfma_f32_16x16x128_f8f6f4 v[90:93], v[208:215], v[224:231], v[90:93]
	v_mfma_f32_16x16x128_f8f6f4 v[122:125], v[200:207], v[224:231], v[122:125]
	v_mfma_f32_16x16x128_f8f6f4 v[126:129], v[192:199], v[224:231], v[126:129]
	s_setprio 0
	s_setprio 1
	v_mfma_f32_16x16x128_f8f6f4 v[118:121], v[192:199], v[232:239], v[118:121]
	v_mfma_f32_16x16x128_f8f6f4 v[114:117], v[200:207], v[232:239], v[114:117]
	v_mfma_f32_16x16x128_f8f6f4 v[82:85], v[208:215], v[232:239], v[82:85]
	v_mfma_f32_16x16x128_f8f6f4 v[86:89], v[2:9], v[232:239], v[86:89]
	s_setprio 0
	s_setprio 1
	v_mfma_f32_16x16x128_f8f6f4 v[78:81], v[2:9], v[240:247], v[78:81]
	v_mfma_f32_16x16x128_f8f6f4 v[74:77], v[208:215], v[240:247], v[74:77]
	v_mfma_f32_16x16x128_f8f6f4 v[106:109], v[200:207], v[240:247], v[106:109]
	v_mfma_f32_16x16x128_f8f6f4 v[110:113], v[192:199], v[240:247], v[110:113]
	s_barrier
	s_setprio 0
	s_mov_b32 m0, s52
	v_lshl_add_u64 v[176:177], v[176:177], 0, s[14:15]
	s_add_u32 s26, s26, 0x158080
	ds_read_b128 v[216:219], v190 offset:49152
	ds_read_b128 v[220:223], v190 offset:50176
	ds_read_b128 v[224:227], v190 offset:51200
	ds_read_b128 v[228:231], v190 offset:52224
	ds_read_b128 v[232:235], v190 offset:53248
	ds_read_b128 v[236:239], v190 offset:54272
	ds_read_b128 v[240:243], v190 offset:55296
	ds_read_b128 v[244:247], v190 offset:56320
	global_load_lds_dwordx4 v[176:177], off
	v_lshl_add_u64 v[176:177], v[182:183], 0, s[14:15]
	s_mov_b32 m0, s53
	s_addc_u32 s27, s27, 0
	global_load_lds_dwordx4 v[176:177], off
	v_lshl_add_u64 v[176:177], s[26:27], 0, v[156:157]
	s_mov_b32 m0, s56
	s_nop 0
	global_load_lds_dwordx4 v[176:177], off
	v_lshl_add_u64 v[176:177], s[26:27], 0, v[160:161]
	s_mov_b32 m0, s57
	s_nop 0
	global_load_lds_dwordx4 v[176:177], off
	v_lshl_add_u64 v[176:177], v[184:185], 0, s[14:15]
	s_mov_b32 m0, s54
	s_nop 0
	global_load_lds_dwordx4 v[176:177], off
	v_lshl_add_u64 v[176:177], v[186:187], 0, s[14:15]
	s_mov_b32 m0, s55
	s_nop 0
	global_load_lds_dwordx4 v[176:177], off
	s_waitcnt vmcnt(8)
	s_waitcnt lgkmcnt(0)
	s_setprio 1
	s_barrier
	v_mfma_f32_16x16x128_f8f6f4 v[70:73], v[192:199], v[216:223], v[70:73]
	v_mfma_f32_16x16x128_f8f6f4 v[66:69], v[200:207], v[216:223], v[66:69]
	v_mfma_f32_16x16x128_f8f6f4 v[34:37], v[208:215], v[216:223], v[34:37]
	v_mfma_f32_16x16x128_f8f6f4 v[38:41], v[2:9], v[216:223], v[38:41]
	s_setprio 0
	s_setprio 1
	v_mfma_f32_16x16x128_f8f6f4 v[30:33], v[2:9], v[224:231], v[30:33]
	v_mfma_f32_16x16x128_f8f6f4 v[26:29], v[208:215], v[224:231], v[26:29]
	v_mfma_f32_16x16x128_f8f6f4 v[58:61], v[200:207], v[224:231], v[58:61]
	v_mfma_f32_16x16x128_f8f6f4 v[62:65], v[192:199], v[224:231], v[62:65]
	s_setprio 0
	s_setprio 1
	v_mfma_f32_16x16x128_f8f6f4 v[54:57], v[192:199], v[232:239], v[54:57]
	v_mfma_f32_16x16x128_f8f6f4 v[50:53], v[200:207], v[232:239], v[50:53]
	v_mfma_f32_16x16x128_f8f6f4 v[18:21], v[208:215], v[232:239], v[18:21]
	v_mfma_f32_16x16x128_f8f6f4 v[22:25], v[2:9], v[232:239], v[22:25]
	s_setprio 0
	s_setprio 1
	v_mfma_f32_16x16x128_f8f6f4 v[14:17], v[2:9], v[240:247], v[14:17]
	v_mfma_f32_16x16x128_f8f6f4 v[10:13], v[208:215], v[240:247], v[10:13]
	v_mfma_f32_16x16x128_f8f6f4 v[42:45], v[200:207], v[240:247], v[42:45]
	v_mfma_f32_16x16x128_f8f6f4 v[46:49], v[192:199], v[240:247], v[46:49]
	s_barrier
	s_setprio 0
	s_add_i32 s26, s84, 2
	s_add_u32 s36, s36, 0x100
	s_addc_u32 s37, s37, 0
	s_add_u32 s40, s40, 0x100
	s_addc_u32 s41, s41, 0
	s_cmp_ge_i32 s84, s82
	s_cbranch_scc1 .LBB0_1036
	s_mov_b32 s84, s26
	s_cmp_eq_u32 s82, s84
	s_cselect_b64 s[26:27], -1, 0
	s_cmp_lg_u32 s82, s84
	s_cbranch_scc0 .LBB0_1033
	s_branch .LBB0_1034
